# v18
# speedup vs baseline: 1.0144x; 1.0144x over previous
; #define MFMA32(a, b, c) __builtin_amdgcn_mfma_f32_32x32x16_bf16((a), (b), (c), 0, 0, 0)
;   const int r = lane & 31, hh = lane >> 5;
;   const bf16x8* fq = (const bf16x8*)(smem + DS_FRAGQ);
;   bf16x8 a[4], an[4];
;   int kt = w;
;   if (kt < nt) for (int s = 0; s < 4; ++s) a[s] = ldg<bf16x8>(Ikb + (size_t)(kt * 32 + r) * 64 + 16 * s + 8 * hh);
;   for (; kt < nt; kt += stride) {
;     const bool more = kt + stride < nt;
;     if (more) for (int s = 0; s < 4; ++s) an[s] = ldg<bf16x8>(Ikb + (size_t)((kt + stride) * 32 + r) * 64 + 16 * s + 8 * hh);
;     f32x16 sc;
;     for (int i = 0; i < 16; ++i) sc[i] = 0.f;
;     {
;       const bf16x8* fb = (const bf16x8*)(smem + DS_QBAR);
;       #pragma unroll
;       for (int s = 0; s < 4; ++s) sc = MFMA32(a[s], fb[s * 64 + lane], sc);
;       for (int i = 0; i < 16; ++i) sc[i] *= 0.5f;
;     }
;     #pragma unroll
;     for (int hd = 0; hd < 8; ++hd) {
;       f32x16 acc;
;       for (int i = 0; i < 16; ++i) acc[i] = 0.f;
;       #pragma unroll
;       for (int s = 0; s < 4; ++s) acc = MFMA32(a[s], fq[(hd * 4 + s) * 64 + lane], acc);
;       for (int i = 0; i < 16; ++i) sc[i] = fmaf(wv[hd], __builtin_fabsf(acc[i]), sc[i]);
;     }
.Lhf_entry:
	s_nop 0
	v_readfirstlane_b32 s100, v207
	s_nop 3
	ds_read_b128 v[100:103], v200
	ds_read_b128 v[104:107], v200 offset:1024
	ds_read_b128 v[108:111], v200 offset:2048
	ds_read_b128 v[112:115], v200 offset:3072
	ds_read_b128 v[116:119], v199 offset:32768
	ds_read_b128 v[120:123], v199 offset:33792
	ds_read_b128 v[124:127], v199 offset:34816
	ds_read_b128 v[208:211], v199 offset:35840
	ds_read_b128 v[212:215], v199 offset:36864
	ds_read_b128 v[216:219], v199 offset:37888
	ds_read_b128 v[220:223], v199 offset:38912
	ds_read_b128 v[224:227], v199 offset:39936
	ds_read_b128 v[228:231], v199 offset:40960
	ds_read_b128 v[232:235], v199 offset:41984
	ds_read_b128 v[236:239], v199 offset:43008
	ds_read_b128 v[240:243], v199 offset:44032
	s_waitcnt lgkmcnt(0)

; #define MFMA32(a, b, c) __builtin_amdgcn_mfma_f32_32x32x16_bf16((a), (b), (c), 0, 0, 0)
;     ...
;     {
;       const bf16x8* fb = (const bf16x8*)(smem + DS_QBAR);
;       #pragma unroll
;       for (int s = 0; s < 4; ++s) sc = MFMA32(a[s], fb[s * 64 + lane], sc);
;       for (int i = 0; i < 16; ++i) sc[i] *= 0.5f;
;     }
;     #pragma unroll
;     for (int hd = 0; hd < 8; ++hd) {
;       f32x16 acc;
;       for (int i = 0; i < 16; ++i) acc[i] = 0.f;
;       #pragma unroll
;       for (int s = 0; s < 4; ++s) acc = MFMA32(a[s], fq[(hd * 4 + s) * 64 + lane], acc);
;       for (int i = 0; i < 16; ++i) sc[i] = fmaf(wv[hd], __builtin_fabsf(acc[i]), sc[i]);
;     }
.Lhf_nopf:
	ds_read_b128 v[66:69], v199 offset:45056
	ds_read_b128 v[70:73], v199 offset:46080
	ds_read_b128 v[74:77], v199 offset:47104
	ds_read_b128 v[78:81], v199 offset:48128
	v_mfma_f32_32x32x16_bf16 v[2:17], v[130:133], v[100:103], 0
	v_mfma_f32_32x32x16_bf16 v[2:17], v[162:165], v[104:107], v[2:17]
	v_mfma_f32_32x32x16_bf16 v[2:17], v[166:169], v[108:111], v[2:17]
	v_mfma_f32_32x32x16_bf16 v[2:17], v[170:173], v[112:115], v[2:17]
	v_mfma_f32_32x32x16_bf16 v[18:33], v[130:133], v[116:119], 0
	v_mfma_f32_32x32x16_bf16 v[18:33], v[162:165], v[120:123], v[18:33]
	v_mfma_f32_32x32x16_bf16 v[18:33], v[166:169], v[124:127], v[18:33]
	v_mfma_f32_32x32x16_bf16 v[18:33], v[170:173], v[208:211], v[18:33]
	v_mfma_f32_32x32x16_bf16 v[34:49], v[130:133], v[212:215], 0
	v_mul_f32_e32 v50, 0.5, v2
	v_mul_f32_e32 v51, 0.5, v3
	v_mul_f32_e32 v52, 0.5, v4
	v_mul_f32_e32 v53, 0.5, v5
	v_mfma_f32_32x32x16_bf16 v[34:49], v[162:165], v[216:219], v[34:49]
	v_mul_f32_e32 v54, 0.5, v6
	v_mul_f32_e32 v55, 0.5, v7
	v_mul_f32_e32 v56, 0.5, v8
	v_mul_f32_e32 v57, 0.5, v9
	v_mfma_f32_32x32x16_bf16 v[34:49], v[166:169], v[220:223], v[34:49]
	v_mul_f32_e32 v58, 0.5, v10
	v_mul_f32_e32 v59, 0.5, v11
	v_mul_f32_e32 v60, 0.5, v12
	v_mul_f32_e32 v61, 0.5, v13
	v_mfma_f32_32x32x16_bf16 v[34:49], v[170:173], v[224:227], v[34:49]
	v_mul_f32_e32 v62, 0.5, v14
	v_mul_f32_e32 v63, 0.5, v15
	v_mul_f32_e32 v64, 0.5, v16
	v_mul_f32_e32 v65, 0.5, v17
	v_mfma_f32_32x32x16_bf16 v[2:17], v[130:133], v[228:231], 0
	v_fma_f32 v50, v190, |v18|, v50
	v_fma_f32 v51, v190, |v19|, v51
	v_fma_f32 v52, v190, |v20|, v52
	v_fma_f32 v53, v190, |v21|, v53
	v_mfma_f32_32x32x16_bf16 v[2:17], v[162:165], v[232:235], v[2:17]
	v_fma_f32 v54, v190, |v22|, v54
	v_fma_f32 v55, v190, |v23|, v55
	v_fma_f32 v56, v190, |v24|, v56
	v_fma_f32 v57, v190, |v25|, v57
	v_mfma_f32_32x32x16_bf16 v[2:17], v[166:169], v[236:239], v[2:17]
	v_fma_f32 v58, v190, |v26|, v58
	v_fma_f32 v59, v190, |v27|, v59
	v_fma_f32 v60, v190, |v28|, v60
	v_fma_f32 v61, v190, |v29|, v61
	v_mfma_f32_32x32x16_bf16 v[2:17], v[170:173], v[240:243], v[2:17]
	v_fma_f32 v62, v190, |v30|, v62
	v_fma_f32 v63, v190, |v31|, v63
	v_fma_f32 v64, v190, |v32|, v64
	v_fma_f32 v65, v190, |v33|, v65
	s_waitcnt lgkmcnt(3)
	v_mfma_f32_32x32x16_bf16 v[18:33], v[130:133], v[66:69], 0
	ds_read_b128 v[66:69], v199 offset:49152
	v_fma_f32 v50, v191, |v34|, v50
	v_fma_f32 v51, v191, |v35|, v51
	v_fma_f32 v52, v191, |v36|, v52
	v_fma_f32 v53, v191, |v37|, v53
	s_waitcnt lgkmcnt(3)
	v_mfma_f32_32x32x16_bf16 v[18:33], v[162:165], v[70:73], v[18:33]
	ds_read_b128 v[70:73], v199 offset:50176
	v_fma_f32 v54, v191, |v38|, v54
	v_fma_f32 v55, v191, |v39|, v55
	v_fma_f32 v56, v191, |v40|, v56
	v_fma_f32 v57, v191, |v41|, v57
	s_waitcnt lgkmcnt(3)
	v_mfma_f32_32x32x16_bf16 v[18:33], v[166:169], v[74:77], v[18:33]
	ds_read_b128 v[74:77], v199 offset:51200
	v_fma_f32 v58, v191, |v42|, v58
	v_fma_f32 v59, v191, |v43|, v59
	v_fma_f32 v60, v191, |v44|, v60
	v_fma_f32 v61, v191, |v45|, v61
	s_waitcnt lgkmcnt(3)
	v_mfma_f32_32x32x16_bf16 v[18:33], v[170:173], v[78:81], v[18:33]
	ds_read_b128 v[78:81], v199 offset:52224
	v_fma_f32 v62, v191, |v46|, v62
	v_fma_f32 v63, v191, |v47|, v63
	v_fma_f32 v64, v191, |v48|, v64
	v_fma_f32 v65, v191, |v49|, v65
	s_waitcnt lgkmcnt(3)
	v_mfma_f32_32x32x16_bf16 v[34:49], v[130:133], v[66:69], 0
	ds_read_b128 v[66:69], v199 offset:53248
	v_fma_f32 v50, v192, |v2|, v50
	v_fma_f32 v51, v192, |v3|, v51
	v_fma_f32 v52, v192, |v4|, v52
	v_fma_f32 v53, v192, |v5|, v53
	s_waitcnt lgkmcnt(3)
	v_mfma_f32_32x32x16_bf16 v[34:49], v[162:165], v[70:73], v[34:49]
	ds_read_b128 v[70:73], v199 offset:54272
	v_fma_f32 v54, v192, |v6|, v54
	v_fma_f32 v55, v192, |v7|, v55
	v_fma_f32 v56, v192, |v8|, v56
	v_fma_f32 v57, v192, |v9|, v57
	s_waitcnt lgkmcnt(3)
	v_mfma_f32_32x32x16_bf16 v[34:49], v[166:169], v[74:77], v[34:49]
	ds_read_b128 v[74:77], v199 offset:55296
	v_fma_f32 v58, v192, |v10|, v58
	v_fma_f32 v59, v192, |v11|, v59
	v_fma_f32 v60, v192, |v12|, v60
	v_fma_f32 v61, v192, |v13|, v61
	s_waitcnt lgkmcnt(3)
	v_mfma_f32_32x32x16_bf16 v[34:49], v[170:173], v[78:81], v[34:49]
	ds_read_b128 v[78:81], v199 offset:56320
	v_fma_f32 v62, v192, |v14|, v62
	v_fma_f32 v63, v192, |v15|, v63
	v_fma_f32 v64, v192, |v16|, v64
	v_fma_f32 v65, v192, |v17|, v65
	s_waitcnt lgkmcnt(3)
	v_mfma_f32_32x32x16_bf16 v[2:17], v[130:133], v[66:69], 0
	ds_read_b128 v[66:69], v199 offset:57344
	v_fma_f32 v50, v193, |v18|, v50
	v_fma_f32 v51, v193, |v19|, v51
	v_fma_f32 v52, v193, |v20|, v52
	v_fma_f32 v53, v193, |v21|, v53
	s_waitcnt lgkmcnt(3)
	v_mfma_f32_32x32x16_bf16 v[2:17], v[162:165], v[70:73], v[2:17]
	ds_read_b128 v[70:73], v199 offset:58368
	v_fma_f32 v54, v193, |v22|, v54
	v_fma_f32 v55, v193, |v23|, v55
	v_fma_f32 v56, v193, |v24|, v56
	v_fma_f32 v57, v193, |v25|, v57
	s_waitcnt lgkmcnt(3)
	v_mfma_f32_32x32x16_bf16 v[2:17], v[166:169], v[74:77], v[2:17]
	ds_read_b128 v[74:77], v199 offset:59392
	v_fma_f32 v58, v193, |v26|, v58
	v_fma_f32 v59, v193, |v27|, v59
	v_fma_f32 v60, v193, |v28|, v60
	v_fma_f32 v61, v193, |v29|, v61
	s_waitcnt lgkmcnt(3)
	v_mfma_f32_32x32x16_bf16 v[2:17], v[170:173], v[78:81], v[2:17]
	ds_read_b128 v[78:81], v199 offset:60416
	v_fma_f32 v62, v193, |v30|, v62
	v_fma_f32 v63, v193, |v31|, v63
	v_fma_f32 v64, v193, |v32|, v64
	v_fma_f32 v65, v193, |v33|, v65
	s_waitcnt lgkmcnt(3)
	v_mfma_f32_32x32x16_bf16 v[18:33], v[130:133], v[66:69], 0
	ds_read_b128 v[66:69], v199 offset:61440
	v_fma_f32 v50, v194, |v34|, v50
	v_fma_f32 v51, v194, |v35|, v51
	v_fma_f32 v52, v194, |v36|, v52
	v_fma_f32 v53, v194, |v37|, v53
	s_waitcnt lgkmcnt(3)
; DI int crow(int reg, int h) { return (reg & 3) + 8 * (reg >> 2) + 4 * h; }
; #define MFMA32(a, b, c) __builtin_amdgcn_mfma_f32_32x32x16_bf16((a), (b), (c), 0, 0, 0)
;     ...
;     for (int hd = 0; hd < 8; ++hd) {
;       f32x16 acc;
;       for (int i = 0; i < 16; ++i) acc[i] = 0.f;
;       #pragma unroll
;       for (int s = 0; s < 4; ++s) acc = MFMA32(a[s], fq[(hd * 4 + s) * 64 + lane], acc);
;       for (int i = 0; i < 16; ++i) sc[i] = fmaf(wv[hd], __builtin_fabsf(acc[i]), sc[i]);
;     }
;     f(sc, kt);
;     if (more) for (int s = 0; s < 4; ++s) a[s] = an[s];
; DI void dsa_item(const Params& p, int b, int blk) {
;     ...
;     auto binof = [&](float s) -> unsigned { return (unsigned)(int)fminf(fmaxf(__fmul_rn(__fsub_rn(s, b_lo), b_sc), 0.f), 255.f); };
;     score_pass(Ikb, wv, nt, w, lane, [&](const f32x16& sc, int kt) {
;       for (int i = 0; i < 16; ++i) {
;         int key = kt * 32 + crow(i, hh);
;         if (key <= qpos) atomicAdd(&hist[binof(sc[i]) * 32 + r], 1u);
;       }
	v_mfma_f32_32x32x16_bf16 v[18:33], v[162:165], v[70:73], v[18:33]
	ds_read_b128 v[70:73], v199 offset:62464
	v_fma_f32 v54, v194, |v38|, v54
	v_fma_f32 v55, v194, |v39|, v55
	v_fma_f32 v56, v194, |v40|, v56
	v_fma_f32 v57, v194, |v41|, v57
	s_waitcnt lgkmcnt(3)
	v_mfma_f32_32x32x16_bf16 v[18:33], v[166:169], v[74:77], v[18:33]
	ds_read_b128 v[74:77], v199 offset:63488
	v_fma_f32 v58, v194, |v42|, v58
	v_fma_f32 v59, v194, |v43|, v59
	v_fma_f32 v60, v194, |v44|, v60
	v_fma_f32 v61, v194, |v45|, v61
	s_waitcnt lgkmcnt(3)
	v_mfma_f32_32x32x16_bf16 v[18:33], v[170:173], v[78:81], v[18:33]
	ds_read_b128 v[78:81], v199 offset:64512
	v_fma_f32 v62, v194, |v46|, v62
	v_fma_f32 v63, v194, |v47|, v63
	v_fma_f32 v64, v194, |v48|, v64
	v_fma_f32 v65, v194, |v49|, v65
	s_waitcnt lgkmcnt(3)
	v_mfma_f32_32x32x16_bf16 v[34:49], v[130:133], v[66:69], 0
	v_fma_f32 v50, v195, |v2|, v50
	v_fma_f32 v51, v195, |v3|, v51
	v_fma_f32 v52, v195, |v4|, v52
	v_fma_f32 v53, v195, |v5|, v53
	s_waitcnt lgkmcnt(2)
	v_mfma_f32_32x32x16_bf16 v[34:49], v[162:165], v[70:73], v[34:49]
	v_fma_f32 v54, v195, |v6|, v54
	v_fma_f32 v55, v195, |v7|, v55
	v_fma_f32 v56, v195, |v8|, v56
	v_fma_f32 v57, v195, |v9|, v57
	s_waitcnt lgkmcnt(1)
	v_mfma_f32_32x32x16_bf16 v[34:49], v[166:169], v[74:77], v[34:49]
	v_fma_f32 v58, v195, |v10|, v58
	v_fma_f32 v59, v195, |v11|, v59
	v_fma_f32 v60, v195, |v12|, v60
	v_fma_f32 v61, v195, |v13|, v61
	s_waitcnt lgkmcnt(0)
	v_mfma_f32_32x32x16_bf16 v[34:49], v[170:173], v[78:81], v[34:49]
	v_fma_f32 v62, v195, |v14|, v62
	v_fma_f32 v63, v195, |v15|, v63
	v_fma_f32 v64, v195, |v16|, v64
	v_fma_f32 v65, v195, |v17|, v65
	v_fma_f32 v50, v196, |v18|, v50
	v_fma_f32 v51, v196, |v19|, v51
	v_fma_f32 v52, v196, |v20|, v52
	v_fma_f32 v53, v196, |v21|, v53
	v_fma_f32 v54, v196, |v22|, v54
	v_fma_f32 v55, v196, |v23|, v55
	v_fma_f32 v56, v196, |v24|, v56
	v_fma_f32 v57, v196, |v25|, v57
	v_fma_f32 v58, v196, |v26|, v58
	v_fma_f32 v59, v196, |v27|, v59
	v_fma_f32 v60, v196, |v28|, v60
	v_fma_f32 v61, v196, |v29|, v61
	v_fma_f32 v62, v196, |v30|, v62
	v_fma_f32 v63, v196, |v31|, v63
	v_fma_f32 v64, v196, |v32|, v64
	v_fma_f32 v65, v196, |v33|, v65
	v_fma_f32 v50, v197, |v34|, v50
	v_fma_f32 v51, v197, |v35|, v51
	v_fma_f32 v52, v197, |v36|, v52
	v_fma_f32 v53, v197, |v37|, v53
	v_fma_f32 v54, v197, |v38|, v54
	v_fma_f32 v55, v197, |v39|, v55
	v_fma_f32 v56, v197, |v40|, v56
	v_fma_f32 v57, v197, |v41|, v57
	v_fma_f32 v58, v197, |v42|, v58
	v_fma_f32 v59, v197, |v43|, v59
	v_fma_f32 v60, v197, |v44|, v60
	v_fma_f32 v61, v197, |v45|, v61
	v_fma_f32 v62, v197, |v46|, v62
	v_fma_f32 v63, v197, |v47|, v63
	v_fma_f32 v64, v197, |v48|, v64
	v_fma_f32 v65, v197, |v49|, v65
	v_sub_f32_e32 v82, v50, v177
	v_sub_f32_e32 v83, v51, v177
	v_sub_f32_e32 v84, v52, v177
	v_sub_f32_e32 v85, v53, v177
	v_sub_f32_e32 v86, v54, v177
	v_sub_f32_e32 v87, v55, v177
	v_sub_f32_e32 v88, v56, v177
	v_sub_f32_e32 v89, v57, v177
	v_sub_f32_e32 v90, v58, v177
	v_sub_f32_e32 v91, v59, v177
	v_sub_f32_e32 v92, v60, v177
	v_sub_f32_e32 v93, v61, v177
	v_sub_f32_e32 v94, v62, v177
	v_sub_f32_e32 v95, v63, v177
	v_sub_f32_e32 v96, v64, v177
	v_sub_f32_e32 v97, v65, v177
	v_mul_f32_e32 v82, v206, v82
	v_mul_f32_e32 v83, v206, v83
	v_mul_f32_e32 v84, v206, v84
	v_mul_f32_e32 v85, v206, v85
	v_mul_f32_e32 v86, v206, v86
	v_mul_f32_e32 v87, v206, v87
	v_mul_f32_e32 v88, v206, v88
	v_mul_f32_e32 v89, v206, v89
	v_mul_f32_e32 v90, v206, v90
	v_mul_f32_e32 v91, v206, v91
	v_mul_f32_e32 v92, v206, v92
	v_mul_f32_e32 v93, v206, v93
	v_mul_f32_e32 v94, v206, v94
	v_mul_f32_e32 v95, v206, v95
	v_mul_f32_e32 v96, v206, v96
	v_mul_f32_e32 v97, v206, v97
	v_max_f32_e32 v82, 0, v82
	v_max_f32_e32 v83, 0, v83
	v_max_f32_e32 v84, 0, v84
	v_max_f32_e32 v85, 0, v85
	v_max_f32_e32 v86, 0, v86
	v_max_f32_e32 v87, 0, v87
	v_max_f32_e32 v88, 0, v88
	v_max_f32_e32 v89, 0, v89
	v_max_f32_e32 v90, 0, v90
	v_max_f32_e32 v91, 0, v91
	v_max_f32_e32 v92, 0, v92
	v_max_f32_e32 v93, 0, v93
	v_max_f32_e32 v94, 0, v94
	v_max_f32_e32 v95, 0, v95
	v_max_f32_e32 v96, 0, v96
	v_max_f32_e32 v97, 0, v97
	v_min_f32_e32 v82, 0x437f0000, v82
	v_min_f32_e32 v83, 0x437f0000, v83
	v_min_f32_e32 v84, 0x437f0000, v84
	v_min_f32_e32 v85, 0x437f0000, v85
	v_min_f32_e32 v86, 0x437f0000, v86
	v_min_f32_e32 v87, 0x437f0000, v87
	v_min_f32_e32 v88, 0x437f0000, v88
	v_min_f32_e32 v89, 0x437f0000, v89
	v_min_f32_e32 v90, 0x437f0000, v90
	v_min_f32_e32 v91, 0x437f0000, v91
	v_min_f32_e32 v92, 0x437f0000, v92
	v_min_f32_e32 v93, 0x437f0000, v93
	v_min_f32_e32 v94, 0x437f0000, v94
	v_min_f32_e32 v95, 0x437f0000, v95
	v_min_f32_e32 v96, 0x437f0000, v96
	v_min_f32_e32 v97, 0x437f0000, v97
	v_cvt_i32_f32_e32 v82, v82
	v_cvt_i32_f32_e32 v83, v83
	v_cvt_i32_f32_e32 v84, v84
	v_cvt_i32_f32_e32 v85, v85
	v_cvt_i32_f32_e32 v86, v86
	v_cvt_i32_f32_e32 v87, v87
	v_cvt_i32_f32_e32 v88, v88
	v_cvt_i32_f32_e32 v89, v89
	v_cvt_i32_f32_e32 v90, v90
	v_cvt_i32_f32_e32 v91, v91
	v_cvt_i32_f32_e32 v92, v92
	v_cvt_i32_f32_e32 v93, v93
	v_cvt_i32_f32_e32 v94, v94
	v_cvt_i32_f32_e32 v95, v95
	v_cvt_i32_f32_e32 v96, v96
	v_cvt_i32_f32_e32 v97, v97
	v_lshl_add_u32 v82, v82, 7, v205
	v_lshl_add_u32 v83, v83, 7, v205
	v_lshl_add_u32 v84, v84, 7, v205
	v_lshl_add_u32 v85, v85, 7, v205
	v_lshl_add_u32 v86, v86, 7, v205
	v_lshl_add_u32 v87, v87, 7, v205
	v_lshl_add_u32 v88, v88, 7, v205
	v_lshl_add_u32 v89, v89, 7, v205
	v_lshl_add_u32 v90, v90, 7, v205
	v_lshl_add_u32 v91, v91, 7, v205
	v_lshl_add_u32 v92, v92, 7, v205
	v_lshl_add_u32 v93, v93, 7, v205
	v_lshl_add_u32 v94, v94, 7, v205
	v_lshl_add_u32 v95, v95, 7, v205
	v_lshl_add_u32 v96, v96, 7, v205
	v_lshl_add_u32 v97, v97, 7, v205
	ds_add_u32 v82, v179
	ds_add_u32 v83, v179
	ds_add_u32 v84, v179
	ds_add_u32 v85, v179
	ds_add_u32 v86, v179
	ds_add_u32 v87, v179
	ds_add_u32 v88, v179
	ds_add_u32 v89, v179
	ds_add_u32 v90, v179
	ds_add_u32 v91, v179
	ds_add_u32 v92, v179
	ds_add_u32 v93, v179
	ds_add_u32 v94, v179
	ds_add_u32 v95, v179
	ds_add_u32 v96, v179
	ds_add_u32 v97, v179
	s_waitcnt vmcnt(0)
	v_mov_b32_e32 v130, v158
	v_mov_b32_e32 v131, v159
	v_mov_b32_e32 v132, v160
	v_mov_b32_e32 v133, v161
	v_mov_b32_e32 v162, v154
	v_mov_b32_e32 v163, v155
	v_mov_b32_e32 v164, v156
	v_mov_b32_e32 v165, v157
	v_mov_b32_e32 v166, v150
	v_mov_b32_e32 v167, v151
	v_mov_b32_e32 v168, v152
	v_mov_b32_e32 v169, v153
	v_mov_b32_e32 v170, v146
	v_mov_b32_e32 v171, v147
	v_mov_b32_e32 v172, v148
	v_mov_b32_e32 v173, v149
	v_add_u32_e32 v176, 0x100, v176
	v_add_u32_e32 v207, 8, v207
	s_mov_b32 s100, s101
	s_cmp_le_i32 s100, s37
	s_cbranch_scc1 .Lhf_top
	s_branch .LBB0_990

; #define MFMA32(a, b, c) __builtin_amdgcn_mfma_f32_32x32x16_bf16((a), (b), (c), 0, 0, 0)
;     ...
;   for (; kt < nt; kt += stride) {
;     const bool more = kt + stride < nt;
;     if (more) for (int s = 0; s < 4; ++s) an[s] = ldg<bf16x8>(Ikb + (size_t)((kt + stride) * 32 + r) * 64 + 16 * s + 8 * hh);
;     f32x16 sc;
;     for (int i = 0; i < 16; ++i) sc[i] = 0.f;
;     {
;       const bf16x8* fb = (const bf16x8*)(smem + DS_QBAR);
;       #pragma unroll
;       for (int s = 0; s < 4; ++s) sc = MFMA32(a[s], fb[s * 64 + lane], sc);
;       for (int i = 0; i < 16; ++i) sc[i] *= 0.5f;
;     }
;     #pragma unroll
;     for (int hd = 0; hd < 8; ++hd) {
;       f32x16 acc;
;       for (int i = 0; i < 16; ++i) acc[i] = 0.f;
;       #pragma unroll
;       for (int s = 0; s < 4; ++s) acc = MFMA32(a[s], fq[(hd * 4 + s) * 64 + lane], acc);
;       for (int i = 0; i < 16; ++i) sc[i] = fmaf(wv[hd], __builtin_fabsf(acc[i]), sc[i]);
;     }
.Lcf_entry:
	s_nop 0
	v_readfirstlane_b32 s100, v228
	s_nop 3
	s_waitcnt vmcnt(0) lgkmcnt(0)
	v_mov_b32_e32 v170, v146
	v_mov_b32_e32 v171, v147
	v_mov_b32_e32 v172, v148
	v_mov_b32_e32 v173, v149
	ds_read_b128 v[100:103], v200
	ds_read_b128 v[104:107], v200 offset:1024
	ds_read_b128 v[108:111], v200 offset:2048
	ds_read_b128 v[112:115], v200 offset:3072
	ds_read_b128 v[116:119], v199 offset:32768
	ds_read_b128 v[120:123], v199 offset:33792
	ds_read_b128 v[124:127], v199 offset:34816
	ds_read_b128 v[230:233], v199 offset:35840
	ds_read_b128 v[234:237], v199 offset:36864
	ds_read_b128 v[240:243], v199 offset:37888
	ds_read_b128 v[244:247], v199 offset:38912
	ds_read_b128 v[248:251], v199 offset:39936
	s_waitcnt lgkmcnt(0)
.Lcf_top:
	s_cmp_ge_i32 s100, s37
	s_cbranch_scc1 .LBB0_1062
	s_waitcnt vmcnt(0)
	s_add_i32 s101, s100, 8
	s_cmp_le_i32 s101, s37
	s_cbranch_scc0 .Lcf_nopf
	v_add_u32_e32 v98, v203, v207
	v_ashrrev_i32_e32 v99, 31, v98
	v_lshlrev_b64 v[98:99], 7, v[98:99]
	v_lshl_add_u64 v[98:99], v[174:175], 0, v[98:99]
	global_load_dwordx4 v[158:161], v[98:99], off
	global_load_dwordx4 v[154:157], v[98:99], off offset:32
	global_load_dwordx4 v[150:153], v[98:99], off offset:64
	global_load_dwordx4 v[146:149], v[98:99], off offset:96
.Lcf_nopf:
	ds_read_b128 v[66:69], v199 offset:40960
	ds_read_b128 v[70:73], v199 offset:41984
	ds_read_b128 v[74:77], v199 offset:43008
	ds_read_b128 v[78:81], v199 offset:44032
	v_mfma_f32_32x32x16_bf16 v[2:17], v[130:133], v[100:103], 0
	v_mfma_f32_32x32x16_bf16 v[2:17], v[162:165], v[104:107], v[2:17]
	v_mfma_f32_32x32x16_bf16 v[2:17], v[166:169], v[108:111], v[2:17]
	v_mfma_f32_32x32x16_bf16 v[2:17], v[170:173], v[112:115], v[2:17]
	v_mfma_f32_32x32x16_bf16 v[18:33], v[130:133], v[116:119], 0
	v_mfma_f32_32x32x16_bf16 v[18:33], v[162:165], v[120:123], v[18:33]
	v_mfma_f32_32x32x16_bf16 v[18:33], v[166:169], v[124:127], v[18:33]
	v_mfma_f32_32x32x16_bf16 v[18:33], v[170:173], v[230:233], v[18:33]
	v_mfma_f32_32x32x16_bf16 v[34:49], v[130:133], v[234:237], 0
	v_mul_f32_e32 v50, 0.5, v2
	v_mul_f32_e32 v51, 0.5, v3
	v_mul_f32_e32 v52, 0.5, v4
	v_mul_f32_e32 v53, 0.5, v5
	v_mfma_f32_32x32x16_bf16 v[34:49], v[162:165], v[240:243], v[34:49]
	v_mul_f32_e32 v54, 0.5, v6
	v_mul_f32_e32 v55, 0.5, v7
	v_mul_f32_e32 v56, 0.5, v8
	v_mul_f32_e32 v57, 0.5, v9
	v_mfma_f32_32x32x16_bf16 v[34:49], v[166:169], v[244:247], v[34:49]
	v_mul_f32_e32 v58, 0.5, v10
	v_mul_f32_e32 v59, 0.5, v11
	v_mul_f32_e32 v60, 0.5, v12
	v_mul_f32_e32 v61, 0.5, v13
	v_mfma_f32_32x32x16_bf16 v[34:49], v[170:173], v[248:251], v[34:49]
	v_mul_f32_e32 v62, 0.5, v14
	v_mul_f32_e32 v63, 0.5, v15
	v_mul_f32_e32 v64, 0.5, v16
	v_mul_f32_e32 v65, 0.5, v17
	s_waitcnt lgkmcnt(3)
	v_mfma_f32_32x32x16_bf16 v[2:17], v[130:133], v[66:69], 0
	ds_read_b128 v[66:69], v199 offset:45056
	v_fma_f32 v50, v190, |v18|, v50
	v_fma_f32 v51, v190, |v19|, v51
	v_fma_f32 v52, v190, |v20|, v52
	v_fma_f32 v53, v190, |v21|, v53
	s_waitcnt lgkmcnt(3)
	v_mfma_f32_32x32x16_bf16 v[2:17], v[162:165], v[70:73], v[2:17]
	ds_read_b128 v[70:73], v199 offset:46080
	v_fma_f32 v54, v190, |v22|, v54
	v_fma_f32 v55, v190, |v23|, v55
	v_fma_f32 v56, v190, |v24|, v56
	v_fma_f32 v57, v190, |v25|, v57
	s_waitcnt lgkmcnt(3)
	v_mfma_f32_32x32x16_bf16 v[2:17], v[166:169], v[74:77], v[2:17]
	ds_read_b128 v[74:77], v199 offset:47104
	v_fma_f32 v58, v190, |v26|, v58
	v_fma_f32 v59, v190, |v27|, v59
	v_fma_f32 v60, v190, |v28|, v60
	v_fma_f32 v61, v190, |v29|, v61
	s_waitcnt lgkmcnt(3)
	v_mfma_f32_32x32x16_bf16 v[2:17], v[170:173], v[78:81], v[2:17]
	ds_read_b128 v[78:81], v199 offset:48128
	v_fma_f32 v62, v190, |v30|, v62
	v_fma_f32 v63, v190, |v31|, v63
	v_fma_f32 v64, v190, |v32|, v64
	v_fma_f32 v65, v190, |v33|, v65
	s_waitcnt lgkmcnt(3)
	v_mfma_f32_32x32x16_bf16 v[18:33], v[130:133], v[66:69], 0
	ds_read_b128 v[66:69], v199 offset:49152
	v_fma_f32 v50, v191, |v34|, v50
	v_fma_f32 v51, v191, |v35|, v51
	v_fma_f32 v52, v191, |v36|, v52
	v_fma_f32 v53, v191, |v37|, v53
	s_waitcnt lgkmcnt(3)
	v_mfma_f32_32x32x16_bf16 v[18:33], v[162:165], v[70:73], v[18:33]
	ds_read_b128 v[70:73], v199 offset:50176
	v_fma_f32 v54, v191, |v38|, v54
	v_fma_f32 v55, v191, |v39|, v55
	v_fma_f32 v56, v191, |v40|, v56
	v_fma_f32 v57, v191, |v41|, v57
	s_waitcnt lgkmcnt(3)
	v_mfma_f32_32x32x16_bf16 v[18:33], v[166:169], v[74:77], v[18:33]
	ds_read_b128 v[74:77], v199 offset:51200
	v_fma_f32 v58, v191, |v42|, v58
	v_fma_f32 v59, v191, |v43|, v59
	v_fma_f32 v60, v191, |v44|, v60
	v_fma_f32 v61, v191, |v45|, v61
	s_waitcnt lgkmcnt(3)
	v_mfma_f32_32x32x16_bf16 v[18:33], v[170:173], v[78:81], v[18:33]
	ds_read_b128 v[78:81], v199 offset:52224
	v_fma_f32 v62, v191, |v46|, v62
	v_fma_f32 v63, v191, |v47|, v63
	v_fma_f32 v64, v191, |v48|, v64
	v_fma_f32 v65, v191, |v49|, v65
	s_waitcnt lgkmcnt(3)
	v_mfma_f32_32x32x16_bf16 v[34:49], v[130:133], v[66:69], 0
	ds_read_b128 v[66:69], v199 offset:53248
	v_fma_f32 v50, v192, |v2|, v50
	v_fma_f32 v51, v192, |v3|, v51
	v_fma_f32 v52, v192, |v4|, v52
	v_fma_f32 v53, v192, |v5|, v53
	s_waitcnt lgkmcnt(3)
	v_mfma_f32_32x32x16_bf16 v[34:49], v[162:165], v[70:73], v[34:49]
	ds_read_b128 v[70:73], v199 offset:54272
	v_fma_f32 v54, v192, |v6|, v54
	v_fma_f32 v55, v192, |v7|, v55
	v_fma_f32 v56, v192, |v8|, v56
	v_fma_f32 v57, v192, |v9|, v57
	s_waitcnt lgkmcnt(3)
	v_mfma_f32_32x32x16_bf16 v[34:49], v[166:169], v[74:77], v[34:49]
	ds_read_b128 v[74:77], v199 offset:55296
	v_fma_f32 v58, v192, |v10|, v58
	v_fma_f32 v59, v192, |v11|, v59
	v_fma_f32 v60, v192, |v12|, v60
	v_fma_f32 v61, v192, |v13|, v61
	s_waitcnt lgkmcnt(3)
; DI int crow(int reg, int h) { return (reg & 3) + 8 * (reg >> 2) + 4 * h; }
; #define MFMA32(a, b, c) __builtin_amdgcn_mfma_f32_32x32x16_bf16((a), (b), (c), 0, 0, 0)
; DI unsigned ordkey(float f) { unsigned u = __float_as_uint(f); return (u & 0x80000000u) ? ~u : (u | 0x80000000u); }
;     ...
;     for (int hd = 0; hd < 8; ++hd) {
;       f32x16 acc;
;       for (int i = 0; i < 16; ++i) acc[i] = 0.f;
;       #pragma unroll
;       for (int s = 0; s < 4; ++s) acc = MFMA32(a[s], fq[(hd * 4 + s) * 64 + lane], acc);
;       for (int i = 0; i < 16; ++i) sc[i] = fmaf(wv[hd], __builtin_fabsf(acc[i]), sc[i]);
;     }
; DI void dsa_item(const Params& p, int b, int blk) {
;     ...
;       score_pass(Ikb, wv, nt, w, lane, [&](const f32x16& sc, int kt) {
;         for (int i = 0; i < 16; ++i) {
;           int key = kt * 32 + crow(i, hh);
;           if (key <= qpos) {
;             const unsigned bn = binof(sc[i]);
;             if (bn > bstar) atomicOr(&mask[r * MASK_W + (key >> 5)], 1u << (key & 31));
;             else if (bn == bstar) { unsigned cp = atomicAdd(&candcnt[r], 1u); if (cp < CAND_CAP) cand[r * CAND_CAP + cp] = make_uint2(ordkey(sc[i]), (unsigned)key); }
;           }
;         }
	v_mfma_f32_32x32x16_bf16 v[34:49], v[170:173], v[78:81], v[34:49]
	ds_read_b128 v[78:81], v199 offset:56320
	v_fma_f32 v62, v192, |v14|, v62
	v_fma_f32 v63, v192, |v15|, v63
	v_fma_f32 v64, v192, |v16|, v64
	v_fma_f32 v65, v192, |v17|, v65
	s_waitcnt lgkmcnt(3)
	v_mfma_f32_32x32x16_bf16 v[2:17], v[130:133], v[66:69], 0
	ds_read_b128 v[66:69], v199 offset:57344
	v_fma_f32 v50, v193, |v18|, v50
	v_fma_f32 v51, v193, |v19|, v51
	v_fma_f32 v52, v193, |v20|, v52
	v_fma_f32 v53, v193, |v21|, v53
	s_waitcnt lgkmcnt(3)
	v_mfma_f32_32x32x16_bf16 v[2:17], v[162:165], v[70:73], v[2:17]
	ds_read_b128 v[70:73], v199 offset:58368
	v_fma_f32 v54, v193, |v22|, v54
	v_fma_f32 v55, v193, |v23|, v55
	v_fma_f32 v56, v193, |v24|, v56
	v_fma_f32 v57, v193, |v25|, v57
	s_waitcnt lgkmcnt(3)
	v_mfma_f32_32x32x16_bf16 v[2:17], v[166:169], v[74:77], v[2:17]
	ds_read_b128 v[74:77], v199 offset:59392
	v_fma_f32 v58, v193, |v26|, v58
	v_fma_f32 v59, v193, |v27|, v59
	v_fma_f32 v60, v193, |v28|, v60
	v_fma_f32 v61, v193, |v29|, v61
	s_waitcnt lgkmcnt(3)
	v_mfma_f32_32x32x16_bf16 v[2:17], v[170:173], v[78:81], v[2:17]
	ds_read_b128 v[78:81], v199 offset:60416
	v_fma_f32 v62, v193, |v30|, v62
	v_fma_f32 v63, v193, |v31|, v63
	v_fma_f32 v64, v193, |v32|, v64
	v_fma_f32 v65, v193, |v33|, v65
	s_waitcnt lgkmcnt(3)
	v_mfma_f32_32x32x16_bf16 v[18:33], v[130:133], v[66:69], 0
	ds_read_b128 v[66:69], v199 offset:61440
	v_fma_f32 v50, v194, |v34|, v50
	v_fma_f32 v51, v194, |v35|, v51
	v_fma_f32 v52, v194, |v36|, v52
	v_fma_f32 v53, v194, |v37|, v53
	s_waitcnt lgkmcnt(3)
	v_mfma_f32_32x32x16_bf16 v[18:33], v[162:165], v[70:73], v[18:33]
	ds_read_b128 v[70:73], v199 offset:62464
	v_fma_f32 v54, v194, |v38|, v54
	v_fma_f32 v55, v194, |v39|, v55
	v_fma_f32 v56, v194, |v40|, v56
	v_fma_f32 v57, v194, |v41|, v57
	s_waitcnt lgkmcnt(3)
	v_mfma_f32_32x32x16_bf16 v[18:33], v[166:169], v[74:77], v[18:33]
	ds_read_b128 v[74:77], v199 offset:63488
	v_fma_f32 v58, v194, |v42|, v58
	v_fma_f32 v59, v194, |v43|, v59
	v_fma_f32 v60, v194, |v44|, v60
	v_fma_f32 v61, v194, |v45|, v61
	s_waitcnt lgkmcnt(3)
	v_mfma_f32_32x32x16_bf16 v[18:33], v[170:173], v[78:81], v[18:33]
	ds_read_b128 v[78:81], v199 offset:64512
	v_fma_f32 v62, v194, |v46|, v62
	v_fma_f32 v63, v194, |v47|, v63
	v_fma_f32 v64, v194, |v48|, v64
	v_fma_f32 v65, v194, |v49|, v65
	s_waitcnt lgkmcnt(3)
	v_mfma_f32_32x32x16_bf16 v[34:49], v[130:133], v[66:69], 0
	v_fma_f32 v50, v195, |v2|, v50
	v_fma_f32 v51, v195, |v3|, v51
	v_fma_f32 v52, v195, |v4|, v52
	v_fma_f32 v53, v195, |v5|, v53
	s_waitcnt lgkmcnt(2)
	v_mfma_f32_32x32x16_bf16 v[34:49], v[162:165], v[70:73], v[34:49]
	v_fma_f32 v54, v195, |v6|, v54
	v_fma_f32 v55, v195, |v7|, v55
	v_fma_f32 v56, v195, |v8|, v56
	v_fma_f32 v57, v195, |v9|, v57
	s_waitcnt lgkmcnt(1)
	v_mfma_f32_32x32x16_bf16 v[34:49], v[166:169], v[74:77], v[34:49]
	v_fma_f32 v58, v195, |v10|, v58
	v_fma_f32 v59, v195, |v11|, v59
	v_fma_f32 v60, v195, |v12|, v60
	v_fma_f32 v61, v195, |v13|, v61
	s_waitcnt lgkmcnt(0)
	v_mfma_f32_32x32x16_bf16 v[34:49], v[170:173], v[78:81], v[34:49]
	v_fma_f32 v62, v195, |v14|, v62
	v_fma_f32 v63, v195, |v15|, v63
	v_fma_f32 v64, v195, |v16|, v64
	v_fma_f32 v65, v195, |v17|, v65
	v_fma_f32 v50, v196, |v18|, v50
	v_fma_f32 v51, v196, |v19|, v51
	v_fma_f32 v52, v196, |v20|, v52
	v_fma_f32 v53, v196, |v21|, v53
	v_fma_f32 v54, v196, |v22|, v54
	v_fma_f32 v55, v196, |v23|, v55
	v_fma_f32 v56, v196, |v24|, v56
	v_fma_f32 v57, v196, |v25|, v57
	v_fma_f32 v58, v196, |v26|, v58
	v_fma_f32 v59, v196, |v27|, v59
	v_fma_f32 v60, v196, |v28|, v60
	v_fma_f32 v61, v196, |v29|, v61
	v_fma_f32 v62, v196, |v30|, v62
	v_fma_f32 v63, v196, |v31|, v63
	v_fma_f32 v64, v196, |v32|, v64
	v_fma_f32 v65, v196, |v33|, v65
	v_fma_f32 v50, v197, |v34|, v50
	v_fma_f32 v51, v197, |v35|, v51
	v_fma_f32 v52, v197, |v36|, v52
	v_fma_f32 v53, v197, |v37|, v53
	v_fma_f32 v54, v197, |v38|, v54
	v_fma_f32 v55, v197, |v39|, v55
	v_fma_f32 v56, v197, |v40|, v56
	v_fma_f32 v57, v197, |v41|, v57
	v_fma_f32 v58, v197, |v42|, v58
	v_fma_f32 v59, v197, |v43|, v59
	v_fma_f32 v60, v197, |v44|, v60
	v_fma_f32 v61, v197, |v45|, v61
	v_fma_f32 v62, v197, |v46|, v62
	v_fma_f32 v63, v197, |v47|, v63
	v_fma_f32 v64, v197, |v48|, v64
	v_fma_f32 v65, v197, |v49|, v65
	v_sub_f32_e32 v82, v50, v177
	v_sub_f32_e32 v83, v51, v177
	v_sub_f32_e32 v84, v52, v177
	v_sub_f32_e32 v85, v53, v177
	v_sub_f32_e32 v86, v54, v177
	v_sub_f32_e32 v87, v55, v177
	v_sub_f32_e32 v88, v56, v177
	v_sub_f32_e32 v89, v57, v177
	v_sub_f32_e32 v90, v58, v177
	v_sub_f32_e32 v91, v59, v177
	v_sub_f32_e32 v92, v60, v177
	v_sub_f32_e32 v93, v61, v177
	v_sub_f32_e32 v94, v62, v177
	v_sub_f32_e32 v95, v63, v177
	v_sub_f32_e32 v96, v64, v177
	v_sub_f32_e32 v97, v65, v177
	v_mul_f32_e32 v82, v206, v82
	v_mul_f32_e32 v83, v206, v83
	v_mul_f32_e32 v84, v206, v84
	v_mul_f32_e32 v85, v206, v85
	v_mul_f32_e32 v86, v206, v86
	v_mul_f32_e32 v87, v206, v87
	v_mul_f32_e32 v88, v206, v88
	v_mul_f32_e32 v89, v206, v89
	v_mul_f32_e32 v90, v206, v90
	v_mul_f32_e32 v91, v206, v91
	v_mul_f32_e32 v92, v206, v92
	v_mul_f32_e32 v93, v206, v93
	v_mul_f32_e32 v94, v206, v94
	v_mul_f32_e32 v95, v206, v95
	v_mul_f32_e32 v96, v206, v96
	v_mul_f32_e32 v97, v206, v97
	v_max_f32_e32 v82, 0, v82
	v_max_f32_e32 v83, 0, v83
	v_max_f32_e32 v84, 0, v84
	v_max_f32_e32 v85, 0, v85
	v_max_f32_e32 v86, 0, v86
	v_max_f32_e32 v87, 0, v87
	v_max_f32_e32 v88, 0, v88
	v_max_f32_e32 v89, 0, v89
	v_max_f32_e32 v90, 0, v90
	v_max_f32_e32 v91, 0, v91
	v_max_f32_e32 v92, 0, v92
	v_max_f32_e32 v93, 0, v93
	v_max_f32_e32 v94, 0, v94
	v_max_f32_e32 v95, 0, v95
	v_max_f32_e32 v96, 0, v96
	v_max_f32_e32 v97, 0, v97
	v_min_f32_e32 v82, 0x437f0000, v82
	v_min_f32_e32 v83, 0x437f0000, v83
	v_min_f32_e32 v84, 0x437f0000, v84
	v_min_f32_e32 v85, 0x437f0000, v85
	v_min_f32_e32 v86, 0x437f0000, v86
	v_min_f32_e32 v87, 0x437f0000, v87
	v_min_f32_e32 v88, 0x437f0000, v88
	v_min_f32_e32 v89, 0x437f0000, v89
	v_min_f32_e32 v90, 0x437f0000, v90
	v_min_f32_e32 v91, 0x437f0000, v91
	v_min_f32_e32 v92, 0x437f0000, v92
	v_min_f32_e32 v93, 0x437f0000, v93
	v_min_f32_e32 v94, 0x437f0000, v94
	v_min_f32_e32 v95, 0x437f0000, v95
	v_min_f32_e32 v96, 0x437f0000, v96
	v_min_f32_e32 v97, 0x437f0000, v97
	v_cvt_i32_f32_e32 v82, v82
	v_cvt_i32_f32_e32 v83, v83
	v_cvt_i32_f32_e32 v84, v84
	v_cvt_i32_f32_e32 v85, v85
	v_cvt_i32_f32_e32 v86, v86
	v_cvt_i32_f32_e32 v87, v87
	v_cvt_i32_f32_e32 v88, v88
	v_cvt_i32_f32_e32 v89, v89
	v_cvt_i32_f32_e32 v90, v90
	v_cvt_i32_f32_e32 v91, v91
	v_cvt_i32_f32_e32 v92, v92
	v_cvt_i32_f32_e32 v93, v93
	v_cvt_i32_f32_e32 v94, v94
	v_cvt_i32_f32_e32 v95, v95
	v_cvt_i32_f32_e32 v96, v96
	v_cvt_i32_f32_e32 v97, v97
	v_mov_b32_e32 v252, 0
	v_add_u32_e32 v98, v201, v207
	v_cmp_lt_u32_e32 vcc, v208, v82
	s_nop 1
	v_cndmask_b32_e32 v229, v1, v210, vcc
	v_cmp_eq_u32_e32 vcc, v208, v82
	v_or_b32_e32 v252, v252, v229
	s_nop 0
	s_cbranch_vccz .Lcf_s0
; DI int crow(int reg, int h) { return (reg & 3) + 8 * (reg >> 2) + 4 * h; }
; DI unsigned ordkey(float f) { unsigned u = __float_as_uint(f); return (u & 0x80000000u) ? ~u : (u | 0x80000000u); }
; DI void dsa_item(const Params& p, int b, int blk) {
;     ...
;       score_pass(Ikb, wv, nt, w, lane, [&](const f32x16& sc, int kt) {
;         for (int i = 0; i < 16; ++i) {
;           int key = kt * 32 + crow(i, hh);
;           if (key <= qpos) {
;             const unsigned bn = binof(sc[i]);
;             if (bn > bstar) atomicOr(&mask[r * MASK_W + (key >> 5)], 1u << (key & 31));
;             else if (bn == bstar) { unsigned cp = atomicAdd(&candcnt[r], 1u); if (cp < CAND_CAP) cand[r * CAND_CAP + cp] = make_uint2(ordkey(sc[i]), (unsigned)key); }
;           }
;         }
;       });
	s_and_saveexec_b64 s[26:27], vcc
	ds_add_rtn_u32 v238, v209, v179
	s_waitcnt lgkmcnt(0)
	v_cmp_gt_u32_e64 s[0:1], s85, v238
	s_and_b64 exec, exec, s[0:1]
	v_not_b32_e32 v239, v50
	v_or_b32_e32 v253, 0x80000000, v50
	v_cmp_gt_i32_e64 s[0:1], 0, v50
	v_add_u32_e32 v129, 0, v98
	v_lshl_add_u32 v238, v238, 3, v226
	v_cndmask_b32_e64 v128, v253, v239, s[0:1]
	ds_write_b64 v238, v[128:129]
	s_mov_b64 exec, s[26:27]
.Lcf_s0:
	v_cmp_lt_u32_e32 vcc, v208, v83
	s_nop 1
	v_cndmask_b32_e32 v229, v1, v211, vcc
	v_cmp_eq_u32_e32 vcc, v208, v83
	v_or_b32_e32 v252, v252, v229
	s_nop 0
	s_cbranch_vccz .Lcf_s1
	s_and_saveexec_b64 s[26:27], vcc
	ds_add_rtn_u32 v238, v209, v179
	s_waitcnt lgkmcnt(0)
	v_cmp_gt_u32_e64 s[0:1], s85, v238
	s_and_b64 exec, exec, s[0:1]
	v_not_b32_e32 v239, v51
	v_or_b32_e32 v253, 0x80000000, v51
	v_cmp_gt_i32_e64 s[0:1], 0, v51
	v_add_u32_e32 v129, 1, v98
	v_lshl_add_u32 v238, v238, 3, v226
	v_cndmask_b32_e64 v128, v253, v239, s[0:1]
	ds_write_b64 v238, v[128:129]
	s_mov_b64 exec, s[26:27]
.Lcf_s1:
	v_cmp_lt_u32_e32 vcc, v208, v84
	s_nop 1
	v_cndmask_b32_e32 v229, v1, v212, vcc
	v_cmp_eq_u32_e32 vcc, v208, v84
	v_or_b32_e32 v252, v252, v229
	s_nop 0
	s_cbranch_vccz .Lcf_s2
	s_and_saveexec_b64 s[26:27], vcc
	ds_add_rtn_u32 v238, v209, v179
	s_waitcnt lgkmcnt(0)
	v_cmp_gt_u32_e64 s[0:1], s85, v238
	s_and_b64 exec, exec, s[0:1]
	v_not_b32_e32 v239, v52
	v_or_b32_e32 v253, 0x80000000, v52
	v_cmp_gt_i32_e64 s[0:1], 0, v52
	v_add_u32_e32 v129, 2, v98
	v_lshl_add_u32 v238, v238, 3, v226
	v_cndmask_b32_e64 v128, v253, v239, s[0:1]
	ds_write_b64 v238, v[128:129]
	s_mov_b64 exec, s[26:27]
.Lcf_s2:
	v_cmp_lt_u32_e32 vcc, v208, v85
	s_nop 1
	v_cndmask_b32_e32 v229, v1, v213, vcc
	v_cmp_eq_u32_e32 vcc, v208, v85
	v_or_b32_e32 v252, v252, v229
	s_nop 0
	s_cbranch_vccz .Lcf_s3
	s_and_saveexec_b64 s[26:27], vcc
	ds_add_rtn_u32 v238, v209, v179
	s_waitcnt lgkmcnt(0)
	v_cmp_gt_u32_e64 s[0:1], s85, v238
	s_and_b64 exec, exec, s[0:1]
	v_not_b32_e32 v239, v53
	v_or_b32_e32 v253, 0x80000000, v53
	v_cmp_gt_i32_e64 s[0:1], 0, v53
	v_add_u32_e32 v129, 3, v98
	v_lshl_add_u32 v238, v238, 3, v226
	v_cndmask_b32_e64 v128, v253, v239, s[0:1]
	ds_write_b64 v238, v[128:129]
	s_mov_b64 exec, s[26:27]
.Lcf_s3:
	v_cmp_lt_u32_e32 vcc, v208, v86
	s_nop 1
	v_cndmask_b32_e32 v229, v1, v214, vcc
	v_cmp_eq_u32_e32 vcc, v208, v86
	v_or_b32_e32 v252, v252, v229
	s_nop 0
	s_cbranch_vccz .Lcf_s4
	s_and_saveexec_b64 s[26:27], vcc
	ds_add_rtn_u32 v238, v209, v179
	s_waitcnt lgkmcnt(0)
	v_cmp_gt_u32_e64 s[0:1], s85, v238
	s_and_b64 exec, exec, s[0:1]
	v_not_b32_e32 v239, v54
	v_or_b32_e32 v253, 0x80000000, v54
	v_cmp_gt_i32_e64 s[0:1], 0, v54
	v_add_u32_e32 v129, 8, v98
	v_lshl_add_u32 v238, v238, 3, v226
	v_cndmask_b32_e64 v128, v253, v239, s[0:1]
	ds_write_b64 v238, v[128:129]
	s_mov_b64 exec, s[26:27]
.Lcf_s4:
	v_cmp_lt_u32_e32 vcc, v208, v87
	s_nop 1
	v_cndmask_b32_e32 v229, v1, v215, vcc
	v_cmp_eq_u32_e32 vcc, v208, v87
	v_or_b32_e32 v252, v252, v229
	s_nop 0
	s_cbranch_vccz .Lcf_s5
	s_and_saveexec_b64 s[26:27], vcc
	ds_add_rtn_u32 v238, v209, v179
	s_waitcnt lgkmcnt(0)
	v_cmp_gt_u32_e64 s[0:1], s85, v238
	s_and_b64 exec, exec, s[0:1]
	v_not_b32_e32 v239, v55
	v_or_b32_e32 v253, 0x80000000, v55
	v_cmp_gt_i32_e64 s[0:1], 0, v55
	v_add_u32_e32 v129, 9, v98
	v_lshl_add_u32 v238, v238, 3, v226
	v_cndmask_b32_e64 v128, v253, v239, s[0:1]
	ds_write_b64 v238, v[128:129]
	s_mov_b64 exec, s[26:27]
.Lcf_s5:
	v_cmp_lt_u32_e32 vcc, v208, v88
	s_nop 1
	v_cndmask_b32_e32 v229, v1, v216, vcc
	v_cmp_eq_u32_e32 vcc, v208, v88
	v_or_b32_e32 v252, v252, v229
	s_nop 0
	s_cbranch_vccz .Lcf_s6
	s_and_saveexec_b64 s[26:27], vcc
	ds_add_rtn_u32 v238, v209, v179
	s_waitcnt lgkmcnt(0)
	v_cmp_gt_u32_e64 s[0:1], s85, v238
	s_and_b64 exec, exec, s[0:1]
	v_not_b32_e32 v239, v56
	v_or_b32_e32 v253, 0x80000000, v56
	v_cmp_gt_i32_e64 s[0:1], 0, v56
	v_add_u32_e32 v129, 10, v98
	v_lshl_add_u32 v238, v238, 3, v226
	v_cndmask_b32_e64 v128, v253, v239, s[0:1]
	ds_write_b64 v238, v[128:129]
	s_mov_b64 exec, s[26:27]
.Lcf_s6:
	v_cmp_lt_u32_e32 vcc, v208, v89
	s_nop 1
	v_cndmask_b32_e32 v229, v1, v217, vcc
	v_cmp_eq_u32_e32 vcc, v208, v89
	v_or_b32_e32 v252, v252, v229
	s_nop 0
	s_cbranch_vccz .Lcf_s7
	s_and_saveexec_b64 s[26:27], vcc
	ds_add_rtn_u32 v238, v209, v179
	s_waitcnt lgkmcnt(0)
	v_cmp_gt_u32_e64 s[0:1], s85, v238
	s_and_b64 exec, exec, s[0:1]
	v_not_b32_e32 v239, v57
	v_or_b32_e32 v253, 0x80000000, v57
	v_cmp_gt_i32_e64 s[0:1], 0, v57
	v_add_u32_e32 v129, 11, v98
	v_lshl_add_u32 v238, v238, 3, v226
	v_cndmask_b32_e64 v128, v253, v239, s[0:1]
	ds_write_b64 v238, v[128:129]
	s_mov_b64 exec, s[26:27]
.Lcf_s7:
	v_cmp_lt_u32_e32 vcc, v208, v90
	s_nop 1
	v_cndmask_b32_e32 v229, v1, v218, vcc
	v_cmp_eq_u32_e32 vcc, v208, v90
	v_or_b32_e32 v252, v252, v229
	s_nop 0
	s_cbranch_vccz .Lcf_s8
	s_and_saveexec_b64 s[26:27], vcc
	ds_add_rtn_u32 v238, v209, v179
	s_waitcnt lgkmcnt(0)
	v_cmp_gt_u32_e64 s[0:1], s85, v238
	s_and_b64 exec, exec, s[0:1]
	v_not_b32_e32 v239, v58
	v_or_b32_e32 v253, 0x80000000, v58
	v_cmp_gt_i32_e64 s[0:1], 0, v58
	v_add_u32_e32 v129, 16, v98
	v_lshl_add_u32 v238, v238, 3, v226
	v_cndmask_b32_e64 v128, v253, v239, s[0:1]
	ds_write_b64 v238, v[128:129]
	s_mov_b64 exec, s[26:27]
; DI int crow(int reg, int h) { return (reg & 3) + 8 * (reg >> 2) + 4 * h; }
; DI unsigned ordkey(float f) { unsigned u = __float_as_uint(f); return (u & 0x80000000u) ? ~u : (u | 0x80000000u); }
;     ...
;     if (more) for (int s = 0; s < 4; ++s) a[s] = an[s];
;   }
; DI void dsa_item(const Params& p, int b, int blk) {
;     ...
;       score_pass(Ikb, wv, nt, w, lane, [&](const f32x16& sc, int kt) {
;         for (int i = 0; i < 16; ++i) {
;           int key = kt * 32 + crow(i, hh);
;           if (key <= qpos) {
;             const unsigned bn = binof(sc[i]);
;             if (bn > bstar) atomicOr(&mask[r * MASK_W + (key >> 5)], 1u << (key & 31));
;             else if (bn == bstar) { unsigned cp = atomicAdd(&candcnt[r], 1u); if (cp < CAND_CAP) cand[r * CAND_CAP + cp] = make_uint2(ordkey(sc[i]), (unsigned)key); }
;           }
;         }
;       });
.Lcf_s8:
	v_cmp_lt_u32_e32 vcc, v208, v91
	s_nop 1
	v_cndmask_b32_e32 v229, v1, v219, vcc
	v_cmp_eq_u32_e32 vcc, v208, v91
	v_or_b32_e32 v252, v252, v229
	s_nop 0
	s_cbranch_vccz .Lcf_s9
	s_and_saveexec_b64 s[26:27], vcc
	ds_add_rtn_u32 v238, v209, v179
	s_waitcnt lgkmcnt(0)
	v_cmp_gt_u32_e64 s[0:1], s85, v238
	s_and_b64 exec, exec, s[0:1]
	v_not_b32_e32 v239, v59
	v_or_b32_e32 v253, 0x80000000, v59
	v_cmp_gt_i32_e64 s[0:1], 0, v59
	v_add_u32_e32 v129, 17, v98
	v_lshl_add_u32 v238, v238, 3, v226
	v_cndmask_b32_e64 v128, v253, v239, s[0:1]
	ds_write_b64 v238, v[128:129]
	s_mov_b64 exec, s[26:27]
.Lcf_s9:
	v_cmp_lt_u32_e32 vcc, v208, v92
	s_nop 1
	v_cndmask_b32_e32 v229, v1, v220, vcc
	v_cmp_eq_u32_e32 vcc, v208, v92
	v_or_b32_e32 v252, v252, v229
	s_nop 0
	s_cbranch_vccz .Lcf_s10
	s_and_saveexec_b64 s[26:27], vcc
	ds_add_rtn_u32 v238, v209, v179
	s_waitcnt lgkmcnt(0)
	v_cmp_gt_u32_e64 s[0:1], s85, v238
	s_and_b64 exec, exec, s[0:1]
	v_not_b32_e32 v239, v60
	v_or_b32_e32 v253, 0x80000000, v60
	v_cmp_gt_i32_e64 s[0:1], 0, v60
	v_add_u32_e32 v129, 18, v98
	v_lshl_add_u32 v238, v238, 3, v226
	v_cndmask_b32_e64 v128, v253, v239, s[0:1]
	ds_write_b64 v238, v[128:129]
	s_mov_b64 exec, s[26:27]
.Lcf_s10:
	v_cmp_lt_u32_e32 vcc, v208, v93
	s_nop 1
	v_cndmask_b32_e32 v229, v1, v221, vcc
	v_cmp_eq_u32_e32 vcc, v208, v93
	v_or_b32_e32 v252, v252, v229
	s_nop 0
	s_cbranch_vccz .Lcf_s11
	s_and_saveexec_b64 s[26:27], vcc
	ds_add_rtn_u32 v238, v209, v179
	s_waitcnt lgkmcnt(0)
	v_cmp_gt_u32_e64 s[0:1], s85, v238
	s_and_b64 exec, exec, s[0:1]
	v_not_b32_e32 v239, v61
	v_or_b32_e32 v253, 0x80000000, v61
	v_cmp_gt_i32_e64 s[0:1], 0, v61
	v_add_u32_e32 v129, 19, v98
	v_lshl_add_u32 v238, v238, 3, v226
	v_cndmask_b32_e64 v128, v253, v239, s[0:1]
	ds_write_b64 v238, v[128:129]
	s_mov_b64 exec, s[26:27]
.Lcf_s11:
	v_cmp_lt_u32_e32 vcc, v208, v94
	s_nop 1
	v_cndmask_b32_e32 v229, v1, v222, vcc
	v_cmp_eq_u32_e32 vcc, v208, v94
	v_or_b32_e32 v252, v252, v229
	s_nop 0
	s_cbranch_vccz .Lcf_s12
	s_and_saveexec_b64 s[26:27], vcc
	ds_add_rtn_u32 v238, v209, v179
	s_waitcnt lgkmcnt(0)
	v_cmp_gt_u32_e64 s[0:1], s85, v238
	s_and_b64 exec, exec, s[0:1]
	v_not_b32_e32 v239, v62
	v_or_b32_e32 v253, 0x80000000, v62
	v_cmp_gt_i32_e64 s[0:1], 0, v62
	v_add_u32_e32 v129, 24, v98
	v_lshl_add_u32 v238, v238, 3, v226
	v_cndmask_b32_e64 v128, v253, v239, s[0:1]
	ds_write_b64 v238, v[128:129]
	s_mov_b64 exec, s[26:27]
.Lcf_s12:
	v_cmp_lt_u32_e32 vcc, v208, v95
	s_nop 1
	v_cndmask_b32_e32 v229, v1, v223, vcc
	v_cmp_eq_u32_e32 vcc, v208, v95
	v_or_b32_e32 v252, v252, v229
	s_nop 0
	s_cbranch_vccz .Lcf_s13
	s_and_saveexec_b64 s[26:27], vcc
	ds_add_rtn_u32 v238, v209, v179
	s_waitcnt lgkmcnt(0)
	v_cmp_gt_u32_e64 s[0:1], s85, v238
	s_and_b64 exec, exec, s[0:1]
	v_not_b32_e32 v239, v63
	v_or_b32_e32 v253, 0x80000000, v63
	v_cmp_gt_i32_e64 s[0:1], 0, v63
	v_add_u32_e32 v129, 25, v98
	v_lshl_add_u32 v238, v238, 3, v226
	v_cndmask_b32_e64 v128, v253, v239, s[0:1]
	ds_write_b64 v238, v[128:129]
	s_mov_b64 exec, s[26:27]
.Lcf_s13:
	v_cmp_lt_u32_e32 vcc, v208, v96
	s_nop 1
	v_cndmask_b32_e32 v229, v1, v224, vcc
	v_cmp_eq_u32_e32 vcc, v208, v96
	v_or_b32_e32 v252, v252, v229
	s_nop 0
	s_cbranch_vccz .Lcf_s14
	s_and_saveexec_b64 s[26:27], vcc
	ds_add_rtn_u32 v238, v209, v179
	s_waitcnt lgkmcnt(0)
	v_cmp_gt_u32_e64 s[0:1], s85, v238
	s_and_b64 exec, exec, s[0:1]
	v_not_b32_e32 v239, v64
	v_or_b32_e32 v253, 0x80000000, v64
	v_cmp_gt_i32_e64 s[0:1], 0, v64
	v_add_u32_e32 v129, 26, v98
	v_lshl_add_u32 v238, v238, 3, v226
	v_cndmask_b32_e64 v128, v253, v239, s[0:1]
	ds_write_b64 v238, v[128:129]
	s_mov_b64 exec, s[26:27]
.Lcf_s14:
	v_cmp_lt_u32_e32 vcc, v208, v97
	s_nop 1
	v_cndmask_b32_e32 v229, v1, v225, vcc
	v_cmp_eq_u32_e32 vcc, v208, v97
	v_or_b32_e32 v252, v252, v229
	s_nop 0
	s_cbranch_vccz .Lcf_s15
	s_and_saveexec_b64 s[26:27], vcc
	ds_add_rtn_u32 v238, v209, v179
	s_waitcnt lgkmcnt(0)
	v_cmp_gt_u32_e64 s[0:1], s85, v238
	s_and_b64 exec, exec, s[0:1]
	v_not_b32_e32 v239, v65
	v_or_b32_e32 v253, 0x80000000, v65
	v_cmp_gt_i32_e64 s[0:1], 0, v65
	v_add_u32_e32 v129, 27, v98
	v_lshl_add_u32 v238, v238, 3, v226
	v_cndmask_b32_e64 v128, v253, v239, s[0:1]
	ds_write_b64 v238, v[128:129]
	s_mov_b64 exec, s[26:27]
.Lcf_s15:
	ds_or_b32 v227, v252
	s_waitcnt vmcnt(0)
	v_mov_b32_e32 v130, v158
	v_mov_b32_e32 v131, v159
	v_mov_b32_e32 v132, v160
	v_mov_b32_e32 v133, v161
	v_mov_b32_e32 v162, v154
	v_mov_b32_e32 v163, v155
	v_mov_b32_e32 v164, v156
	v_mov_b32_e32 v165, v157
	v_mov_b32_e32 v166, v150
	v_mov_b32_e32 v167, v151
	v_mov_b32_e32 v168, v152
	v_mov_b32_e32 v169, v153
	v_mov_b32_e32 v170, v146
	v_mov_b32_e32 v171, v147
	v_mov_b32_e32 v172, v148
	v_mov_b32_e32 v173, v149
	v_add_u32_e32 v227, 32, v227
	v_add_u32_e32 v207, 0x100, v207
	v_add_u32_e32 v228, 8, v228
	s_mov_b32 s100, s101
	s_cmp_le_i32 s100, s37
	s_cbranch_scc1 .Lcf_top
	s_branch .LBB0_1206

; DI void dsa_item(const Params& p, int b, int blk) {
;     ...
;     const int qq = w * 4 + qq4;
;     const int t = q0 + qq;
;     if (t >= LVALID) continue;
;     const size_t row = rowbase + t;
;     const int cnt = min((int)selcnt[qq], TOPK);
;     const u16* qptr = Aq + row * 512 + (lane & 3) * 64;
;     bf16x8 qa[8], qb[8];
;     #pragma unroll
;     for (int c = 0; c < 8; ++c) { qa[c] = ldg<bf16x8>(qptr + c * 8); qb[c] = ldg<bf16x8>(qptr + 256 + c * 8); }
;     float sc[4][8];
;     bf16x8 ka[2][8], kb[2][8];
;     bool valid[4];
;     {
;       const int ks = lane;
;       valid[0] = ks < cnt;
;       const int idx = valid[0] ? (int)sel[qq * 256 + ks] : 0;
;       const u16* kptr = Ak + (rowbase + idx) * 128;
;       #pragma unroll
;       for (int c = 0; c < 8; ++c) { ka[0][c] = ldg<bf16x8>(kptr + c * 8); kb[0][c] = ldg<bf16x8>(kptr + 64 + c * 8); }
;     }
;     #pragma unroll
;     for (int rd = 0; rd < 4; ++rd) {
;       if (rd < 3) {
;         const int ks = (rd + 1) * 64 + lane;
;         valid[rd + 1] = ks < cnt;
;         const int idx = valid[rd + 1] ? (int)sel[qq * 256 + ks] : 0;
;         const u16* kptr = Ak + (rowbase + idx) * 128;
;         #pragma unroll
;         for (int c = 0; c < 8; ++c) { ka[(rd + 1) & 1][c] = ldg<bf16x8>(kptr + c * 8); kb[(rd + 1) & 1][c] = ldg<bf16x8>(kptr + 64 + c * 8); }
;       }
;     ...
;     {
;       const u32x4 si = *(const u32x4*)(sel + qq * 256 + 8 * g16);
;       #pragma unroll
;       for (int j = 0; j < 8; ++j) {
;         const int ks = 8 * g16 + j;
;         const int idx = ks < cnt ? (int)((si[j >> 1] >> (16 * (j & 1))) & 0xffffu) : 0;
;         vr[j] = ldg<u32x4>(Av + (rowbase + idx) * 128 + n16 * 8);
;       }
;     }
.LBB0_1667:
	v_add_u32_e32 v66, s24, v158
	s_waitcnt vmcnt(0)
	v_add_u32_e32 v2, s36, v66
	s_movk_i32 s4, 0x2010
	v_cmp_gt_i32_e32 vcc, s4, v2
	s_and_saveexec_b64 s[4:5], vcc
	s_cbranch_execz .LBB0_1666
	v_ashrrev_i32_e32 v3, 31, v2
	v_lshl_add_u32 v0, v66, 2, 0
	v_add_u32_e32 v0, 0x1ca80, v0
	ds_read_b32 v0, v0
	v_and_b32_e32 v130, 15, v187
	v_lshlrev_b32_e32 v133, 9, v66
	v_lshl_add_u32 v133, v130, 1, v133
	v_add_u32_e32 v133, 0x10000, v133
	ds_read_u16 v18, v133
	ds_read_u16 v22, v133 offset:32
	ds_read_u16 v26, v133 offset:64
	ds_read_u16 v30, v133 offset:96
	ds_read_u16 v34, v133 offset:128
	ds_read_u16 v38, v133 offset:160
	ds_read_u16 v42, v133 offset:192
	ds_read_u16 v46, v133 offset:224
	ds_read_u16 v50, v133 offset:256
	ds_read_u16 v54, v133 offset:288
	ds_read_u16 v58, v133 offset:320
	ds_read_u16 v62, v133 offset:352
	ds_read_u16 v66, v133 offset:384
	ds_read_u16 v70, v133 offset:416
	ds_read_u16 v74, v133 offset:448
	ds_read_u16 v78, v133 offset:480
	v_lshl_add_u64 v[152:153], s[16:17], 0, v[2:3]
	v_and_b32_e32 v142, 12, v187
	v_lshlrev_b32_e32 v142, 7, v142
	v_and_b32_e32 v144, 48, v187
	v_or_b32_e32 v142, v142, v144
	v_mov_b32_e32 v143, 0
	v_mov_b32_e32 v145, 0
	v_lshl_add_u64 v[134:135], s[0:1], 0, v[144:145]
	v_lshlrev_b64 v[4:5], 10, v[152:153]
	v_lshl_add_u64 v[4:5], v[146:147], 0, v[4:5]
	v_lshl_add_u64 v[142:143], v[4:5], 0, v[142:143]
	v_xor_b32_e32 v136, 16, v187
	v_lshlrev_b32_e32 v136, 2, v136
	v_xor_b32_e32 v137, 32, v187
	v_lshlrev_b32_e32 v137, 2, v137
	v_lshrrev_b32_e32 v138, 6, v178
	v_lshlrev_b32_e32 v138, 13, v138
	v_mul_u32_u24_e32 v252, 0x210, v130
	v_add3_u32 v138, v138, v252, v156
	v_mov_b32_e32 v139, 0xf149f2ca
	v_mov_b32_e32 v141, 0
	v_mov_b32_e32 v2, 0
	v_mov_b32_e32 v3, 0
	v_mov_b32_e32 v4, 0
	v_mov_b32_e32 v5, 0
	v_mov_b32_e32 v6, 0
	v_mov_b32_e32 v7, 0
	v_mov_b32_e32 v8, 0
	v_mov_b32_e32 v9, 0
	v_mov_b32_e32 v10, 0
	v_mov_b32_e32 v11, 0
	v_mov_b32_e32 v12, 0
	v_mov_b32_e32 v13, 0
	v_mov_b32_e32 v14, 0
	v_mov_b32_e32 v15, 0
	v_mov_b32_e32 v16, 0
	v_mov_b32_e32 v17, 0
	s_mov_b32 exec_lo, 0x000f000f
	s_mov_b32 exec_hi, 0x000f000f
	global_load_dwordx4 v[2:5], v[142:143], off
	global_load_dwordx4 v[6:9], v[142:143], off offset:64
	s_mov_b32 exec_lo, 0x00f000f0
	s_mov_b32 exec_hi, 0x00f000f0
	global_load_dwordx4 v[10:13], v[142:143], off
	global_load_dwordx4 v[14:17], v[142:143], off offset:64
	s_mov_b64 exec, -1
	s_waitcnt lgkmcnt(0)
	v_min_i32_e32 v206, 0x100, v0
	v_sub_u32_e32 v131, v206, v130
	v_lshrrev_b32_e32 v132, 1, v156
	v_sub_u32_e32 v132, v206, v132
	v_readfirstlane_b32 s100, v206
	v_add_u32_e32 v242, 0xffffffc0, v188
	v_mov_b32_e32 v241, 0
	ds_read_b128 v[248:251], v242
	s_waitcnt lgkmcnt(0)
	v_cmp_lt_i32_e32 vcc, v156, v206
	s_nop 1
	v_cndmask_b32_sdwa v240, v1, v248, vcc dst_sel:DWORD dst_unused:UNUSED_PAD src0_sel:DWORD src1_sel:WORD_0
	v_cmp_lt_i32_e32 vcc, v192, v206
	v_lshl_add_u64 v[244:245], s[16:17], 0, v[240:241]
	v_lshlrev_b64 v[244:245], 8, v[244:245]
	v_lshl_add_u64 v[244:245], v[148:149], 0, v[244:245]
	global_load_dwordx4 v[208:211], v[244:245], off
	v_cndmask_b32_sdwa v240, v1, v248, vcc dst_sel:DWORD dst_unused:UNUSED_PAD src0_sel:DWORD src1_sel:WORD_1
	v_cmp_lt_i32_e32 vcc, v193, v206
	v_lshl_add_u64 v[246:247], s[16:17], 0, v[240:241]
	v_lshlrev_b64 v[246:247], 8, v[246:247]
	v_lshl_add_u64 v[246:247], v[148:149], 0, v[246:247]
	global_load_dwordx4 v[212:215], v[246:247], off
	v_cndmask_b32_sdwa v240, v1, v249, vcc dst_sel:DWORD dst_unused:UNUSED_PAD src0_sel:DWORD src1_sel:WORD_0
	v_cmp_lt_i32_e32 vcc, v194, v206
	v_lshl_add_u64 v[244:245], s[16:17], 0, v[240:241]
	v_lshlrev_b64 v[244:245], 8, v[244:245]
	v_lshl_add_u64 v[244:245], v[148:149], 0, v[244:245]
	global_load_dwordx4 v[216:219], v[244:245], off
	v_cndmask_b32_sdwa v240, v1, v249, vcc dst_sel:DWORD dst_unused:UNUSED_PAD src0_sel:DWORD src1_sel:WORD_1
	v_cmp_lt_i32_e32 vcc, v157, v206
	v_lshl_add_u64 v[246:247], s[16:17], 0, v[240:241]
	v_lshlrev_b64 v[246:247], 8, v[246:247]
	v_lshl_add_u64 v[246:247], v[148:149], 0, v[246:247]
	global_load_dwordx4 v[220:223], v[246:247], off
	v_cndmask_b32_sdwa v240, v1, v250, vcc dst_sel:DWORD dst_unused:UNUSED_PAD src0_sel:DWORD src1_sel:WORD_0
	v_cmp_lt_i32_e32 vcc, v195, v206
	v_lshl_add_u64 v[244:245], s[16:17], 0, v[240:241]
	v_lshlrev_b64 v[244:245], 8, v[244:245]
	v_lshl_add_u64 v[244:245], v[148:149], 0, v[244:245]
	global_load_dwordx4 v[224:227], v[244:245], off
	v_cndmask_b32_sdwa v240, v1, v250, vcc dst_sel:DWORD dst_unused:UNUSED_PAD src0_sel:DWORD src1_sel:WORD_1
	v_cmp_lt_i32_e32 vcc, v196, v206
	v_lshl_add_u64 v[246:247], s[16:17], 0, v[240:241]
	v_lshlrev_b64 v[246:247], 8, v[246:247]
	v_lshl_add_u64 v[246:247], v[148:149], 0, v[246:247]
	global_load_dwordx4 v[228:231], v[246:247], off
	v_cndmask_b32_sdwa v240, v1, v251, vcc dst_sel:DWORD dst_unused:UNUSED_PAD src0_sel:DWORD src1_sel:WORD_0
	v_cmp_lt_i32_e32 vcc, v197, v206
	v_lshl_add_u64 v[244:245], s[16:17], 0, v[240:241]
	v_lshlrev_b64 v[244:245], 8, v[244:245]
	v_lshl_add_u64 v[244:245], v[148:149], 0, v[244:245]
	global_load_dwordx4 v[232:235], v[244:245], off
	v_cndmask_b32_sdwa v240, v1, v251, vcc dst_sel:DWORD dst_unused:UNUSED_PAD src0_sel:DWORD src1_sel:WORD_1
	v_lshl_add_u64 v[246:247], s[16:17], 0, v[240:241]
	v_lshlrev_b64 v[246:247], 8, v[246:247]
	v_lshl_add_u64 v[246:247], v[148:149], 0, v[246:247]
	global_load_dwordx4 v[236:239], v[246:247], off
	v_cmp_lt_i32_e32 vcc, 0, v131
	s_nop 1
	v_cndmask_b32_e32 v140, v1, v18, vcc
	v_lshl_add_u64 v[142:143], s[16:17], 0, v[140:141]
	v_lshlrev_b64 v[142:143], 8, v[142:143]
	v_lshl_add_u64 v[142:143], v[134:135], 0, v[142:143]
	global_load_dwordx4 v[82:85], v[142:143], off
	global_load_dwordx4 v[86:89], v[142:143], off offset:64
	global_load_dwordx4 v[90:93], v[142:143], off offset:128
	global_load_dwordx4 v[94:97], v[142:143], off offset:192
	v_cmp_lt_i32_e32 vcc, 16, v131
	s_nop 1
	v_cndmask_b32_e32 v140, v1, v22, vcc
	v_lshl_add_u64 v[144:145], s[16:17], 0, v[140:141]
	v_lshlrev_b64 v[144:145], 8, v[144:145]
	v_lshl_add_u64 v[144:145], v[134:135], 0, v[144:145]
	global_load_dwordx4 v[98:101], v[144:145], off
	global_load_dwordx4 v[102:105], v[144:145], off offset:64
	global_load_dwordx4 v[106:109], v[144:145], off offset:128
	global_load_dwordx4 v[110:113], v[144:145], off offset:192
	v_cmp_lt_i32_e32 vcc, 32, v131
	s_nop 1
	v_cndmask_b32_e32 v140, v1, v26, vcc
	v_lshl_add_u64 v[142:143], s[16:17], 0, v[140:141]
	v_lshlrev_b64 v[142:143], 8, v[142:143]
	v_lshl_add_u64 v[142:143], v[134:135], 0, v[142:143]
	global_load_dwordx4 v[114:117], v[142:143], off
	global_load_dwordx4 v[118:121], v[142:143], off offset:64
	global_load_dwordx4 v[122:125], v[142:143], off offset:128
	global_load_dwordx4 v[126:129], v[142:143], off offset:192
	s_waitcnt vmcnt(8)
; #define MFMA4(a, b, c)  __builtin_amdgcn_mfma_f32_4x4x4bf16_1k((a), (b), (c), 0, 0, 0)
; DI void dsa_item(const Params& p, int b, int blk) {
;     ...
;     #pragma unroll
;     for (int rd = 0; rd < 4; ++rd) {
;       if (rd < 3) {
;         const int ks = (rd + 1) * 64 + lane;
;         valid[rd + 1] = ks < cnt;
;         const int idx = valid[rd + 1] ? (int)sel[qq * 256 + ks] : 0;
;         const u16* kptr = Ak + (rowbase + idx) * 128;
;         #pragma unroll
;         for (int c = 0; c < 8; ++c) { ka[(rd + 1) & 1][c] = ldg<bf16x8>(kptr + c * 8); kb[(rd + 1) & 1][c] = ldg<bf16x8>(kptr + 64 + c * 8); }
;       }
;       f32x4 c0 = {0.f, 0.f, 0.f, 0.f}, c1 = {0.f, 0.f, 0.f, 0.f};
;       #pragma unroll
;       for (int c = 0; c < 8; ++c) {
;         const bf16x8 kav = ka[rd & 1][c], kbv = kb[rd & 1][c];
;         s16x4 qlo = {qa[c][0], qa[c][1], qa[c][2], qa[c][3]}, qhi = {qa[c][4], qa[c][5], qa[c][6], qa[c][7]};
;         s16x4 klo = {kav[0], kav[1], kav[2], kav[3]}, khi = {kav[4], kav[5], kav[6], kav[7]};
;         c0 = MFMA4(qlo, klo, c0); c0 = MFMA4(qhi, khi, c0);
;         s16x4 rlo = {qb[c][0], qb[c][1], qb[c][2], qb[c][3]}, rhi = {qb[c][4], qb[c][5], qb[c][6], qb[c][7]};
;         s16x4 llo = {kbv[0], kbv[1], kbv[2], kbv[3]}, lhi = {kbv[4], kbv[5], kbv[6], kbv[7]};
;         c1 = MFMA4(rlo, llo, c1); c1 = MFMA4(rhi, lhi, c1);
;       }
	v_mfma_f32_16x16x32_bf16 v[18:21], v[82:85], v[2:5], 0
	v_mfma_f32_16x16x32_bf16 v[18:21], v[86:89], v[6:9], v[18:21]
	v_mfma_f32_16x16x32_bf16 v[18:21], v[90:93], v[10:13], v[18:21]
	v_mfma_f32_16x16x32_bf16 v[18:21], v[94:97], v[14:17], v[18:21]
	v_cmp_lt_i32_e32 vcc, 48, v131
	s_nop 1
	v_cndmask_b32_e32 v140, v1, v30, vcc
	v_lshl_add_u64 v[144:145], s[16:17], 0, v[140:141]
	v_lshlrev_b64 v[144:145], 8, v[144:145]
	v_lshl_add_u64 v[144:145], v[134:135], 0, v[144:145]
	global_load_dwordx4 v[82:85], v[144:145], off
	global_load_dwordx4 v[86:89], v[144:145], off offset:64
	global_load_dwordx4 v[90:93], v[144:145], off offset:128
	global_load_dwordx4 v[94:97], v[144:145], off offset:192
	s_waitcnt vmcnt(8)
	v_mfma_f32_16x16x32_bf16 v[22:25], v[98:101], v[2:5], 0
	v_mfma_f32_16x16x32_bf16 v[22:25], v[102:105], v[6:9], v[22:25]
	v_mfma_f32_16x16x32_bf16 v[22:25], v[106:109], v[10:13], v[22:25]
	v_mfma_f32_16x16x32_bf16 v[22:25], v[110:113], v[14:17], v[22:25]
	v_cmp_lt_i32_e32 vcc, 64, v131
	s_nop 1
	v_cndmask_b32_e32 v140, v1, v34, vcc
	v_lshl_add_u64 v[142:143], s[16:17], 0, v[140:141]
	v_lshlrev_b64 v[142:143], 8, v[142:143]
	v_lshl_add_u64 v[142:143], v[134:135], 0, v[142:143]
	global_load_dwordx4 v[98:101], v[142:143], off
	global_load_dwordx4 v[102:105], v[142:143], off offset:64
	global_load_dwordx4 v[106:109], v[142:143], off offset:128
	global_load_dwordx4 v[110:113], v[142:143], off offset:192
	s_waitcnt vmcnt(8)
	v_mfma_f32_16x16x32_bf16 v[26:29], v[114:117], v[2:5], 0
	v_mfma_f32_16x16x32_bf16 v[26:29], v[118:121], v[6:9], v[26:29]
	v_mfma_f32_16x16x32_bf16 v[26:29], v[122:125], v[10:13], v[26:29]
	v_mfma_f32_16x16x32_bf16 v[26:29], v[126:129], v[14:17], v[26:29]
	v_cmp_lt_i32_e32 vcc, 0x50, v131
	s_nop 1
	v_cndmask_b32_e32 v140, v1, v38, vcc
	v_lshl_add_u64 v[144:145], s[16:17], 0, v[140:141]
	v_lshlrev_b64 v[144:145], 8, v[144:145]
	v_lshl_add_u64 v[144:145], v[134:135], 0, v[144:145]
	global_load_dwordx4 v[114:117], v[144:145], off
	global_load_dwordx4 v[118:121], v[144:145], off offset:64
	global_load_dwordx4 v[122:125], v[144:145], off offset:128
	global_load_dwordx4 v[126:129], v[144:145], off offset:192
	s_waitcnt vmcnt(8)
	v_mfma_f32_16x16x32_bf16 v[30:33], v[82:85], v[2:5], 0
	v_mfma_f32_16x16x32_bf16 v[30:33], v[86:89], v[6:9], v[30:33]
	v_mfma_f32_16x16x32_bf16 v[30:33], v[90:93], v[10:13], v[30:33]
	v_mfma_f32_16x16x32_bf16 v[30:33], v[94:97], v[14:17], v[30:33]
	v_cmp_lt_i32_e32 vcc, 0x60, v131
	s_nop 1
	v_cndmask_b32_e32 v140, v1, v42, vcc
	v_lshl_add_u64 v[142:143], s[16:17], 0, v[140:141]
	v_lshlrev_b64 v[142:143], 8, v[142:143]
	v_lshl_add_u64 v[142:143], v[134:135], 0, v[142:143]
	global_load_dwordx4 v[82:85], v[142:143], off
	global_load_dwordx4 v[86:89], v[142:143], off offset:64
	global_load_dwordx4 v[90:93], v[142:143], off offset:128
	global_load_dwordx4 v[94:97], v[142:143], off offset:192
	s_waitcnt vmcnt(8)
	v_mfma_f32_16x16x32_bf16 v[34:37], v[98:101], v[2:5], 0
	v_mfma_f32_16x16x32_bf16 v[34:37], v[102:105], v[6:9], v[34:37]
	v_mfma_f32_16x16x32_bf16 v[34:37], v[106:109], v[10:13], v[34:37]
	v_mfma_f32_16x16x32_bf16 v[34:37], v[110:113], v[14:17], v[34:37]
	v_cmp_lt_i32_e32 vcc, 0x70, v131
	s_nop 1
	v_cndmask_b32_e32 v140, v1, v46, vcc
	v_lshl_add_u64 v[144:145], s[16:17], 0, v[140:141]
	v_lshlrev_b64 v[144:145], 8, v[144:145]
	v_lshl_add_u64 v[144:145], v[134:135], 0, v[144:145]
	global_load_dwordx4 v[98:101], v[144:145], off
	global_load_dwordx4 v[102:105], v[144:145], off offset:64
	global_load_dwordx4 v[106:109], v[144:145], off offset:128
	global_load_dwordx4 v[110:113], v[144:145], off offset:192
	s_waitcnt vmcnt(8)
	v_mfma_f32_16x16x32_bf16 v[38:41], v[114:117], v[2:5], 0
	v_mfma_f32_16x16x32_bf16 v[38:41], v[118:121], v[6:9], v[38:41]
	v_mfma_f32_16x16x32_bf16 v[38:41], v[122:125], v[10:13], v[38:41]
	v_mfma_f32_16x16x32_bf16 v[38:41], v[126:129], v[14:17], v[38:41]
	v_cmp_lt_i32_e32 vcc, 0x80, v131
	s_nop 1
	v_cndmask_b32_e32 v140, v1, v50, vcc
	v_lshl_add_u64 v[142:143], s[16:17], 0, v[140:141]
	v_lshlrev_b64 v[142:143], 8, v[142:143]
	v_lshl_add_u64 v[142:143], v[134:135], 0, v[142:143]
	global_load_dwordx4 v[114:117], v[142:143], off
	global_load_dwordx4 v[118:121], v[142:143], off offset:64
	global_load_dwordx4 v[122:125], v[142:143], off offset:128
	global_load_dwordx4 v[126:129], v[142:143], off offset:192
	s_waitcnt vmcnt(8)
	v_mfma_f32_16x16x32_bf16 v[42:45], v[82:85], v[2:5], 0
	v_mfma_f32_16x16x32_bf16 v[42:45], v[86:89], v[6:9], v[42:45]
	v_mfma_f32_16x16x32_bf16 v[42:45], v[90:93], v[10:13], v[42:45]
	v_mfma_f32_16x16x32_bf16 v[42:45], v[94:97], v[14:17], v[42:45]
	v_cmp_lt_i32_e32 vcc, 0x90, v131
	s_nop 1
	v_cndmask_b32_e32 v140, v1, v54, vcc
	v_lshl_add_u64 v[144:145], s[16:17], 0, v[140:141]
	v_lshlrev_b64 v[144:145], 8, v[144:145]
	v_lshl_add_u64 v[144:145], v[134:135], 0, v[144:145]
	global_load_dwordx4 v[82:85], v[144:145], off
	global_load_dwordx4 v[86:89], v[144:145], off offset:64
	global_load_dwordx4 v[90:93], v[144:145], off offset:128
	global_load_dwordx4 v[94:97], v[144:145], off offset:192
	s_waitcnt vmcnt(8)
	v_mfma_f32_16x16x32_bf16 v[46:49], v[98:101], v[2:5], 0
	v_mfma_f32_16x16x32_bf16 v[46:49], v[102:105], v[6:9], v[46:49]
	v_mfma_f32_16x16x32_bf16 v[46:49], v[106:109], v[10:13], v[46:49]
	v_mfma_f32_16x16x32_bf16 v[46:49], v[110:113], v[14:17], v[46:49]
	v_cmp_lt_i32_e32 vcc, 0xa0, v131
	s_nop 1
	v_cndmask_b32_e32 v140, v1, v58, vcc
	v_lshl_add_u64 v[142:143], s[16:17], 0, v[140:141]
	v_lshlrev_b64 v[142:143], 8, v[142:143]
	v_lshl_add_u64 v[142:143], v[134:135], 0, v[142:143]
	global_load_dwordx4 v[98:101], v[142:143], off
	global_load_dwordx4 v[102:105], v[142:143], off offset:64
	global_load_dwordx4 v[106:109], v[142:143], off offset:128
	global_load_dwordx4 v[110:113], v[142:143], off offset:192
	s_waitcnt vmcnt(8)
; #define MFMA4(a, b, c)  __builtin_amdgcn_mfma_f32_4x4x4bf16_1k((a), (b), (c), 0, 0, 0)
; DI void dsa_item(const Params& p, int b, int blk) {
;     ...
;       f32x4 c0 = {0.f, 0.f, 0.f, 0.f}, c1 = {0.f, 0.f, 0.f, 0.f};
;       #pragma unroll
;       for (int c = 0; c < 8; ++c) {
;         const bf16x8 kav = ka[rd & 1][c], kbv = kb[rd & 1][c];
;         s16x4 qlo = {qa[c][0], qa[c][1], qa[c][2], qa[c][3]}, qhi = {qa[c][4], qa[c][5], qa[c][6], qa[c][7]};
;         s16x4 klo = {kav[0], kav[1], kav[2], kav[3]}, khi = {kav[4], kav[5], kav[6], kav[7]};
;         c0 = MFMA4(qlo, klo, c0); c0 = MFMA4(qhi, khi, c0);
;         s16x4 rlo = {qb[c][0], qb[c][1], qb[c][2], qb[c][3]}, rhi = {qb[c][4], qb[c][5], qb[c][6], qb[c][7]};
;         s16x4 llo = {kbv[0], kbv[1], kbv[2], kbv[3]}, lhi = {kbv[4], kbv[5], kbv[6], kbv[7]};
;         c1 = MFMA4(rlo, llo, c1); c1 = MFMA4(rhi, lhi, c1);
;       }
;     ...
;       if (kc < 7) {
;         const u32x4 si = *(const u32x4*)(sel + qq * 256 + (kc + 1) * 32 + 8 * g16);
;         #pragma unroll
;         for (int j = 0; j < 8; ++j) {
;           const int ks = (kc + 1) * 32 + 8 * g16 + j;
;           const int idx = ks < cnt ? (int)((si[j >> 1] >> (16 * (j & 1))) & 0xffffu) : 0;
;           vr[j] = ldg<u32x4>(Av + (rowbase + idx) * 128 + n16 * 8);
;         }
;       }
	v_mfma_f32_16x16x32_bf16 v[50:53], v[114:117], v[2:5], 0
	v_mfma_f32_16x16x32_bf16 v[50:53], v[118:121], v[6:9], v[50:53]
	v_mfma_f32_16x16x32_bf16 v[50:53], v[122:125], v[10:13], v[50:53]
	v_mfma_f32_16x16x32_bf16 v[50:53], v[126:129], v[14:17], v[50:53]
	v_cmp_lt_i32_e32 vcc, 0xb0, v131
	s_nop 1
	v_cndmask_b32_e32 v140, v1, v62, vcc
	v_lshl_add_u64 v[144:145], s[16:17], 0, v[140:141]
	v_lshlrev_b64 v[144:145], 8, v[144:145]
	v_lshl_add_u64 v[144:145], v[134:135], 0, v[144:145]
	global_load_dwordx4 v[114:117], v[144:145], off
	global_load_dwordx4 v[118:121], v[144:145], off offset:64
	global_load_dwordx4 v[122:125], v[144:145], off offset:128
	global_load_dwordx4 v[126:129], v[144:145], off offset:192
	s_waitcnt vmcnt(8)
	v_mfma_f32_16x16x32_bf16 v[54:57], v[82:85], v[2:5], 0
	v_mfma_f32_16x16x32_bf16 v[54:57], v[86:89], v[6:9], v[54:57]
	v_mfma_f32_16x16x32_bf16 v[54:57], v[90:93], v[10:13], v[54:57]
	v_mfma_f32_16x16x32_bf16 v[54:57], v[94:97], v[14:17], v[54:57]
	v_cmp_lt_i32_e32 vcc, 0xc0, v131
	s_nop 1
	v_cndmask_b32_e32 v140, v1, v66, vcc
	v_lshl_add_u64 v[142:143], s[16:17], 0, v[140:141]
	v_lshlrev_b64 v[142:143], 8, v[142:143]
	v_lshl_add_u64 v[142:143], v[134:135], 0, v[142:143]
	global_load_dwordx4 v[82:85], v[142:143], off
	global_load_dwordx4 v[86:89], v[142:143], off offset:64
	global_load_dwordx4 v[90:93], v[142:143], off offset:128
	global_load_dwordx4 v[94:97], v[142:143], off offset:192
	s_waitcnt vmcnt(8)
	v_mfma_f32_16x16x32_bf16 v[58:61], v[98:101], v[2:5], 0
	v_mfma_f32_16x16x32_bf16 v[58:61], v[102:105], v[6:9], v[58:61]
	v_mfma_f32_16x16x32_bf16 v[58:61], v[106:109], v[10:13], v[58:61]
	v_mfma_f32_16x16x32_bf16 v[58:61], v[110:113], v[14:17], v[58:61]
	v_cmp_lt_i32_e32 vcc, 0xd0, v131
	s_nop 1
	v_cndmask_b32_e32 v140, v1, v70, vcc
	v_lshl_add_u64 v[144:145], s[16:17], 0, v[140:141]
	v_lshlrev_b64 v[144:145], 8, v[144:145]
	v_lshl_add_u64 v[144:145], v[134:135], 0, v[144:145]
	global_load_dwordx4 v[98:101], v[144:145], off
	global_load_dwordx4 v[102:105], v[144:145], off offset:64
	global_load_dwordx4 v[106:109], v[144:145], off offset:128
	global_load_dwordx4 v[110:113], v[144:145], off offset:192
	s_waitcnt vmcnt(8)
	v_mfma_f32_16x16x32_bf16 v[62:65], v[114:117], v[2:5], 0
	v_mfma_f32_16x16x32_bf16 v[62:65], v[118:121], v[6:9], v[62:65]
	v_mfma_f32_16x16x32_bf16 v[62:65], v[122:125], v[10:13], v[62:65]
	v_mfma_f32_16x16x32_bf16 v[62:65], v[126:129], v[14:17], v[62:65]
	v_cmp_lt_i32_e32 vcc, 0xe0, v131
	s_nop 1
	v_cndmask_b32_e32 v140, v1, v74, vcc
	v_lshl_add_u64 v[142:143], s[16:17], 0, v[140:141]
	v_lshlrev_b64 v[142:143], 8, v[142:143]
	v_lshl_add_u64 v[142:143], v[134:135], 0, v[142:143]
	global_load_dwordx4 v[114:117], v[142:143], off
	global_load_dwordx4 v[118:121], v[142:143], off offset:64
	global_load_dwordx4 v[122:125], v[142:143], off offset:128
	global_load_dwordx4 v[126:129], v[142:143], off offset:192
	s_waitcnt vmcnt(8)
	v_mfma_f32_16x16x32_bf16 v[66:69], v[82:85], v[2:5], 0
	v_mfma_f32_16x16x32_bf16 v[66:69], v[86:89], v[6:9], v[66:69]
	v_mfma_f32_16x16x32_bf16 v[66:69], v[90:93], v[10:13], v[66:69]
	v_mfma_f32_16x16x32_bf16 v[66:69], v[94:97], v[14:17], v[66:69]
	v_cmp_lt_i32_e32 vcc, 0xf0, v131
	s_nop 1
	v_cndmask_b32_e32 v140, v1, v78, vcc
	v_lshl_add_u64 v[144:145], s[16:17], 0, v[140:141]
	v_lshlrev_b64 v[144:145], 8, v[144:145]
	v_lshl_add_u64 v[144:145], v[134:135], 0, v[144:145]
	global_load_dwordx4 v[82:85], v[144:145], off
	global_load_dwordx4 v[86:89], v[144:145], off offset:64
	global_load_dwordx4 v[90:93], v[144:145], off offset:128
	global_load_dwordx4 v[94:97], v[144:145], off offset:192
	s_waitcnt vmcnt(8)
	v_mfma_f32_16x16x32_bf16 v[70:73], v[98:101], v[2:5], 0
	v_mfma_f32_16x16x32_bf16 v[70:73], v[102:105], v[6:9], v[70:73]
	v_mfma_f32_16x16x32_bf16 v[70:73], v[106:109], v[10:13], v[70:73]
	v_mfma_f32_16x16x32_bf16 v[70:73], v[110:113], v[14:17], v[70:73]
	s_waitcnt vmcnt(4)
	v_mfma_f32_16x16x32_bf16 v[74:77], v[114:117], v[2:5], 0
	v_mfma_f32_16x16x32_bf16 v[74:77], v[118:121], v[6:9], v[74:77]
	v_mfma_f32_16x16x32_bf16 v[74:77], v[122:125], v[10:13], v[74:77]
	v_mfma_f32_16x16x32_bf16 v[74:77], v[126:129], v[14:17], v[74:77]
	s_waitcnt vmcnt(0)
	v_mfma_f32_16x16x32_bf16 v[78:81], v[82:85], v[2:5], 0
	v_mfma_f32_16x16x32_bf16 v[78:81], v[86:89], v[6:9], v[78:81]
	v_mfma_f32_16x16x32_bf16 v[78:81], v[90:93], v[10:13], v[78:81]
	v_mfma_f32_16x16x32_bf16 v[78:81], v[94:97], v[14:17], v[78:81]
	v_mov_b32_e32 v8, v132
	v_mov_b32_e32 v9, v136
	v_mov_b32_e32 v10, v137
	ds_read_b128 v[12:15], v242 offset:64
	s_waitcnt lgkmcnt(0)
; DI void dsa_item(const Params& p, int b, int blk) {
;     ...
;       for (int m = 0; m < 4; ++m) { sc[rd][m] = valid[rd] ? c0[m] * SSC : -1e30f; sc[rd][4 + m] = valid[rd] ? c1[m] * SSC : -1e30f; }
;     ...
;       if (kc < 7) {
;         const u32x4 si = *(const u32x4*)(sel + qq * 256 + (kc + 1) * 32 + 8 * g16);
;         #pragma unroll
;         for (int j = 0; j < 8; ++j) {
;           const int ks = (kc + 1) * 32 + 8 * g16 + j;
;           const int idx = ks < cnt ? (int)((si[j >> 1] >> (16 * (j & 1))) & 0xffffu) : 0;
;           vr[j] = ldg<u32x4>(Av + (rowbase + idx) * 128 + n16 * 8);
;         }
;       }
	v_add_u32_e32 v243, 0xffffffe0, v206
	v_cmp_lt_i32_e32 vcc, v156, v243
	s_nop 1
	v_cndmask_b32_sdwa v240, v1, v12, vcc dst_sel:DWORD dst_unused:UNUSED_PAD src0_sel:DWORD src1_sel:WORD_0
	v_cmp_lt_i32_e32 vcc, v192, v243
	v_lshl_add_u64 v[244:245], s[16:17], 0, v[240:241]
	v_lshlrev_b64 v[244:245], 8, v[244:245]
	v_lshl_add_u64 v[244:245], v[148:149], 0, v[244:245]
	global_load_dwordx4 v[106:109], v[244:245], off
	v_cndmask_b32_sdwa v240, v1, v12, vcc dst_sel:DWORD dst_unused:UNUSED_PAD src0_sel:DWORD src1_sel:WORD_1
	v_cmp_lt_i32_e32 vcc, v193, v243
	v_lshl_add_u64 v[246:247], s[16:17], 0, v[240:241]
	v_lshlrev_b64 v[246:247], 8, v[246:247]
	v_lshl_add_u64 v[246:247], v[148:149], 0, v[246:247]
	global_load_dwordx4 v[110:113], v[246:247], off
	v_cndmask_b32_sdwa v240, v1, v13, vcc dst_sel:DWORD dst_unused:UNUSED_PAD src0_sel:DWORD src1_sel:WORD_0
	v_cmp_lt_i32_e32 vcc, v194, v243
	v_lshl_add_u64 v[244:245], s[16:17], 0, v[240:241]
	v_lshlrev_b64 v[244:245], 8, v[244:245]
	v_lshl_add_u64 v[244:245], v[148:149], 0, v[244:245]
	global_load_dwordx4 v[114:117], v[244:245], off
	v_cndmask_b32_sdwa v240, v1, v13, vcc dst_sel:DWORD dst_unused:UNUSED_PAD src0_sel:DWORD src1_sel:WORD_1
	v_cmp_lt_i32_e32 vcc, v157, v243
	v_lshl_add_u64 v[246:247], s[16:17], 0, v[240:241]
	v_lshlrev_b64 v[246:247], 8, v[246:247]
	v_lshl_add_u64 v[246:247], v[148:149], 0, v[246:247]
	global_load_dwordx4 v[118:121], v[246:247], off
	v_cndmask_b32_sdwa v240, v1, v14, vcc dst_sel:DWORD dst_unused:UNUSED_PAD src0_sel:DWORD src1_sel:WORD_0
	v_cmp_lt_i32_e32 vcc, v195, v243
	v_lshl_add_u64 v[244:245], s[16:17], 0, v[240:241]
	v_lshlrev_b64 v[244:245], 8, v[244:245]
	v_lshl_add_u64 v[244:245], v[148:149], 0, v[244:245]
	global_load_dwordx4 v[122:125], v[244:245], off
	v_cndmask_b32_sdwa v240, v1, v14, vcc dst_sel:DWORD dst_unused:UNUSED_PAD src0_sel:DWORD src1_sel:WORD_1
	v_cmp_lt_i32_e32 vcc, v196, v243
	v_lshl_add_u64 v[246:247], s[16:17], 0, v[240:241]
	v_lshlrev_b64 v[246:247], 8, v[246:247]
	v_lshl_add_u64 v[246:247], v[148:149], 0, v[246:247]
	global_load_dwordx4 v[126:129], v[246:247], off
	v_cndmask_b32_sdwa v240, v1, v15, vcc dst_sel:DWORD dst_unused:UNUSED_PAD src0_sel:DWORD src1_sel:WORD_0
	v_cmp_lt_i32_e32 vcc, v197, v243
	v_lshl_add_u64 v[244:245], s[16:17], 0, v[240:241]
	v_lshlrev_b64 v[244:245], 8, v[244:245]
	v_lshl_add_u64 v[244:245], v[148:149], 0, v[244:245]
	global_load_dwordx4 v[130:133], v[244:245], off
	v_cndmask_b32_sdwa v240, v1, v15, vcc dst_sel:DWORD dst_unused:UNUSED_PAD src0_sel:DWORD src1_sel:WORD_1
	v_lshl_add_u64 v[246:247], s[16:17], 0, v[240:241]
	v_lshlrev_b64 v[246:247], 8, v[246:247]
	v_lshl_add_u64 v[246:247], v[148:149], 0, v[246:247]
	global_load_dwordx4 v[134:137], v[246:247], off
	v_mul_f32_e32 v18, 0x3e38aa3b, v18
	v_mul_f32_e32 v19, 0x3e38aa3b, v19
	v_mul_f32_e32 v20, 0x3e38aa3b, v20
	v_mul_f32_e32 v21, 0x3e38aa3b, v21
	v_mul_f32_e32 v22, 0x3e38aa3b, v22
	v_mul_f32_e32 v23, 0x3e38aa3b, v23
	v_mul_f32_e32 v24, 0x3e38aa3b, v24
	v_mul_f32_e32 v25, 0x3e38aa3b, v25
	v_mul_f32_e32 v26, 0x3e38aa3b, v26
	v_mul_f32_e32 v27, 0x3e38aa3b, v27
	v_mul_f32_e32 v28, 0x3e38aa3b, v28
	v_mul_f32_e32 v29, 0x3e38aa3b, v29
	v_mul_f32_e32 v30, 0x3e38aa3b, v30
	v_mul_f32_e32 v31, 0x3e38aa3b, v31
	v_mul_f32_e32 v32, 0x3e38aa3b, v32
	v_mul_f32_e32 v33, 0x3e38aa3b, v33
	v_mul_f32_e32 v34, 0x3e38aa3b, v34
	v_mul_f32_e32 v35, 0x3e38aa3b, v35
	v_mul_f32_e32 v36, 0x3e38aa3b, v36
	v_mul_f32_e32 v37, 0x3e38aa3b, v37
	v_mul_f32_e32 v38, 0x3e38aa3b, v38
	v_mul_f32_e32 v39, 0x3e38aa3b, v39
	v_mul_f32_e32 v40, 0x3e38aa3b, v40
	v_mul_f32_e32 v41, 0x3e38aa3b, v41
	v_mul_f32_e32 v42, 0x3e38aa3b, v42
	v_mul_f32_e32 v43, 0x3e38aa3b, v43
	v_mul_f32_e32 v44, 0x3e38aa3b, v44
	v_mul_f32_e32 v45, 0x3e38aa3b, v45
	v_mul_f32_e32 v46, 0x3e38aa3b, v46
	v_mul_f32_e32 v47, 0x3e38aa3b, v47
	v_mul_f32_e32 v48, 0x3e38aa3b, v48
	v_mul_f32_e32 v49, 0x3e38aa3b, v49
	v_mul_f32_e32 v50, 0x3e38aa3b, v50
	v_mul_f32_e32 v51, 0x3e38aa3b, v51
	v_mul_f32_e32 v52, 0x3e38aa3b, v52
	v_mul_f32_e32 v53, 0x3e38aa3b, v53
	v_mul_f32_e32 v54, 0x3e38aa3b, v54
	v_mul_f32_e32 v55, 0x3e38aa3b, v55
	v_mul_f32_e32 v56, 0x3e38aa3b, v56
	v_mul_f32_e32 v57, 0x3e38aa3b, v57
	v_mul_f32_e32 v58, 0x3e38aa3b, v58
	v_mul_f32_e32 v59, 0x3e38aa3b, v59
	v_mul_f32_e32 v60, 0x3e38aa3b, v60
	v_mul_f32_e32 v61, 0x3e38aa3b, v61
	v_mul_f32_e32 v62, 0x3e38aa3b, v62
	v_mul_f32_e32 v63, 0x3e38aa3b, v63
	v_mul_f32_e32 v64, 0x3e38aa3b, v64
	v_mul_f32_e32 v65, 0x3e38aa3b, v65
	v_mul_f32_e32 v66, 0x3e38aa3b, v66
	v_mul_f32_e32 v67, 0x3e38aa3b, v67
	v_mul_f32_e32 v68, 0x3e38aa3b, v68
	v_mul_f32_e32 v69, 0x3e38aa3b, v69
	v_mul_f32_e32 v70, 0x3e38aa3b, v70
	v_mul_f32_e32 v71, 0x3e38aa3b, v71
	v_mul_f32_e32 v72, 0x3e38aa3b, v72
	v_mul_f32_e32 v73, 0x3e38aa3b, v73
	v_mul_f32_e32 v74, 0x3e38aa3b, v74
	v_mul_f32_e32 v75, 0x3e38aa3b, v75
	v_mul_f32_e32 v76, 0x3e38aa3b, v76
	v_mul_f32_e32 v77, 0x3e38aa3b, v77
	v_mul_f32_e32 v78, 0x3e38aa3b, v78
	v_mul_f32_e32 v79, 0x3e38aa3b, v79
	v_mul_f32_e32 v80, 0x3e38aa3b, v80
	v_mul_f32_e32 v81, 0x3e38aa3b, v81
	s_cmpk_ge_i32 s100, 0x100
	s_cbranch_scc1 .Lqk_nomask
; DI void dsa_item(const Params& p, int b, int blk) {
;     ...
;       #pragma unroll
;       for (int m = 0; m < 4; ++m) { sc[rd][m] = valid[rd] ? c0[m] * SSC : -1e30f; sc[rd][4 + m] = valid[rd] ? c1[m] * SSC : -1e30f; }
	v_cmp_lt_i32_e32 vcc, 0, v8
	s_nop 1
	v_cndmask_b32_e32 v18, v139, v18, vcc
	v_cmp_lt_i32_e32 vcc, 1, v8
	s_nop 1
	v_cndmask_b32_e32 v19, v139, v19, vcc
	v_cmp_lt_i32_e32 vcc, 2, v8
	s_nop 1
	v_cndmask_b32_e32 v20, v139, v20, vcc
	v_cmp_lt_i32_e32 vcc, 3, v8
	s_nop 1
	v_cndmask_b32_e32 v21, v139, v21, vcc
	v_cmp_lt_i32_e32 vcc, 16, v8
	s_nop 1
	v_cndmask_b32_e32 v22, v139, v22, vcc
	v_cmp_lt_i32_e32 vcc, 17, v8
	s_nop 1
	v_cndmask_b32_e32 v23, v139, v23, vcc
	v_cmp_lt_i32_e32 vcc, 18, v8
	s_nop 1
	v_cndmask_b32_e32 v24, v139, v24, vcc
	v_cmp_lt_i32_e32 vcc, 19, v8
	s_nop 1
	v_cndmask_b32_e32 v25, v139, v25, vcc
	v_cmp_lt_i32_e32 vcc, 32, v8
	s_nop 1
	v_cndmask_b32_e32 v26, v139, v26, vcc
	v_cmp_lt_i32_e32 vcc, 33, v8
	s_nop 1
	v_cndmask_b32_e32 v27, v139, v27, vcc
	v_cmp_lt_i32_e32 vcc, 34, v8
	s_nop 1
	v_cndmask_b32_e32 v28, v139, v28, vcc
	v_cmp_lt_i32_e32 vcc, 35, v8
	s_nop 1
	v_cndmask_b32_e32 v29, v139, v29, vcc
	v_cmp_lt_i32_e32 vcc, 48, v8
	s_nop 1
	v_cndmask_b32_e32 v30, v139, v30, vcc
	v_cmp_lt_i32_e32 vcc, 49, v8
	s_nop 1
	v_cndmask_b32_e32 v31, v139, v31, vcc
	v_cmp_lt_i32_e32 vcc, 50, v8
	s_nop 1
	v_cndmask_b32_e32 v32, v139, v32, vcc
	v_cmp_lt_i32_e32 vcc, 51, v8
	s_nop 1
	v_cndmask_b32_e32 v33, v139, v33, vcc
	v_cmp_lt_i32_e32 vcc, 64, v8
	s_nop 1
	v_cndmask_b32_e32 v34, v139, v34, vcc
	v_cmp_lt_i32_e32 vcc, 0x41, v8
	s_nop 1
	v_cndmask_b32_e32 v35, v139, v35, vcc
	v_cmp_lt_i32_e32 vcc, 0x42, v8
	s_nop 1
	v_cndmask_b32_e32 v36, v139, v36, vcc
	v_cmp_lt_i32_e32 vcc, 0x43, v8
	s_nop 1
	v_cndmask_b32_e32 v37, v139, v37, vcc
	v_cmp_lt_i32_e32 vcc, 0x50, v8
	s_nop 1
	v_cndmask_b32_e32 v38, v139, v38, vcc
	v_cmp_lt_i32_e32 vcc, 0x51, v8
	s_nop 1
	v_cndmask_b32_e32 v39, v139, v39, vcc
	v_cmp_lt_i32_e32 vcc, 0x52, v8
	s_nop 1
	v_cndmask_b32_e32 v40, v139, v40, vcc
	v_cmp_lt_i32_e32 vcc, 0x53, v8
	s_nop 1
	v_cndmask_b32_e32 v41, v139, v41, vcc
	v_cmp_lt_i32_e32 vcc, 0x60, v8
	s_nop 1
	v_cndmask_b32_e32 v42, v139, v42, vcc
	v_cmp_lt_i32_e32 vcc, 0x61, v8
	s_nop 1
	v_cndmask_b32_e32 v43, v139, v43, vcc
	v_cmp_lt_i32_e32 vcc, 0x62, v8
	s_nop 1
	v_cndmask_b32_e32 v44, v139, v44, vcc
	v_cmp_lt_i32_e32 vcc, 0x63, v8
	s_nop 1
	v_cndmask_b32_e32 v45, v139, v45, vcc
	v_cmp_lt_i32_e32 vcc, 0x70, v8
	s_nop 1
	v_cndmask_b32_e32 v46, v139, v46, vcc
	v_cmp_lt_i32_e32 vcc, 0x71, v8
	s_nop 1
	v_cndmask_b32_e32 v47, v139, v47, vcc
	v_cmp_lt_i32_e32 vcc, 0x72, v8
	s_nop 1
	v_cndmask_b32_e32 v48, v139, v48, vcc
	v_cmp_lt_i32_e32 vcc, 0x73, v8
	s_nop 1
	v_cndmask_b32_e32 v49, v139, v49, vcc
	v_cmp_lt_i32_e32 vcc, 0x80, v8
	s_nop 1
	v_cndmask_b32_e32 v50, v139, v50, vcc
	v_cmp_lt_i32_e32 vcc, 0x81, v8
	s_nop 1
	v_cndmask_b32_e32 v51, v139, v51, vcc
	v_cmp_lt_i32_e32 vcc, 0x82, v8
	s_nop 1
	v_cndmask_b32_e32 v52, v139, v52, vcc
	v_cmp_lt_i32_e32 vcc, 0x83, v8
	s_nop 1
	v_cndmask_b32_e32 v53, v139, v53, vcc
	v_cmp_lt_i32_e32 vcc, 0x90, v8
	s_nop 1
	v_cndmask_b32_e32 v54, v139, v54, vcc
	v_cmp_lt_i32_e32 vcc, 0x91, v8
	s_nop 1
	v_cndmask_b32_e32 v55, v139, v55, vcc
	v_cmp_lt_i32_e32 vcc, 0x92, v8
	s_nop 1
	v_cndmask_b32_e32 v56, v139, v56, vcc
	v_cmp_lt_i32_e32 vcc, 0x93, v8
	s_nop 1
	v_cndmask_b32_e32 v57, v139, v57, vcc
	v_cmp_lt_i32_e32 vcc, 0xa0, v8
	s_nop 1
	v_cndmask_b32_e32 v58, v139, v58, vcc
	v_cmp_lt_i32_e32 vcc, 0xa1, v8
	s_nop 1
	v_cndmask_b32_e32 v59, v139, v59, vcc
	v_cmp_lt_i32_e32 vcc, 0xa2, v8
	s_nop 1
	v_cndmask_b32_e32 v60, v139, v60, vcc
	v_cmp_lt_i32_e32 vcc, 0xa3, v8
	s_nop 1
	v_cndmask_b32_e32 v61, v139, v61, vcc
	v_cmp_lt_i32_e32 vcc, 0xb0, v8
	s_nop 1
	v_cndmask_b32_e32 v62, v139, v62, vcc
	v_cmp_lt_i32_e32 vcc, 0xb1, v8
	s_nop 1
	v_cndmask_b32_e32 v63, v139, v63, vcc
	v_cmp_lt_i32_e32 vcc, 0xb2, v8
	s_nop 1
	v_cndmask_b32_e32 v64, v139, v64, vcc
	v_cmp_lt_i32_e32 vcc, 0xb3, v8
	s_nop 1
	v_cndmask_b32_e32 v65, v139, v65, vcc
	v_cmp_lt_i32_e32 vcc, 0xc0, v8
	s_nop 1
	v_cndmask_b32_e32 v66, v139, v66, vcc
	v_cmp_lt_i32_e32 vcc, 0xc1, v8
	s_nop 1
	v_cndmask_b32_e32 v67, v139, v67, vcc
	v_cmp_lt_i32_e32 vcc, 0xc2, v8
	s_nop 1
	v_cndmask_b32_e32 v68, v139, v68, vcc
	v_cmp_lt_i32_e32 vcc, 0xc3, v8
	s_nop 1
	v_cndmask_b32_e32 v69, v139, v69, vcc
	v_cmp_lt_i32_e32 vcc, 0xd0, v8
	s_nop 1
	v_cndmask_b32_e32 v70, v139, v70, vcc
	v_cmp_lt_i32_e32 vcc, 0xd1, v8
	s_nop 1
	v_cndmask_b32_e32 v71, v139, v71, vcc
	v_cmp_lt_i32_e32 vcc, 0xd2, v8
	s_nop 1
	v_cndmask_b32_e32 v72, v139, v72, vcc
	v_cmp_lt_i32_e32 vcc, 0xd3, v8
	s_nop 1
	v_cndmask_b32_e32 v73, v139, v73, vcc
	v_cmp_lt_i32_e32 vcc, 0xe0, v8
	s_nop 1
	v_cndmask_b32_e32 v74, v139, v74, vcc
	v_cmp_lt_i32_e32 vcc, 0xe1, v8
	s_nop 1
	v_cndmask_b32_e32 v75, v139, v75, vcc
	v_cmp_lt_i32_e32 vcc, 0xe2, v8
	s_nop 1
	v_cndmask_b32_e32 v76, v139, v76, vcc
	v_cmp_lt_i32_e32 vcc, 0xe3, v8
	s_nop 1
	v_cndmask_b32_e32 v77, v139, v77, vcc
	v_cmp_lt_i32_e32 vcc, 0xf0, v8
	s_nop 1
	v_cndmask_b32_e32 v78, v139, v78, vcc
	v_cmp_lt_i32_e32 vcc, 0xf1, v8
	s_nop 1
	v_cndmask_b32_e32 v79, v139, v79, vcc
	v_cmp_lt_i32_e32 vcc, 0xf2, v8
	s_nop 1
	v_cndmask_b32_e32 v80, v139, v80, vcc
	v_cmp_lt_i32_e32 vcc, 0xf3, v8
	s_nop 1
	v_cndmask_b32_e32 v81, v139, v81, vcc
; DI float fast_exp2(float x) { return __builtin_amdgcn_exp2f(x); }
; DI void dsa_item(const Params& p, int b, int blk) {
;     ...
;     for (int m = 0; m < 8; ++m) {
;       float mx = fmaxf(fmaxf(sc[0][m], sc[1][m]), fmaxf(sc[2][m], sc[3][m]));
;       mx = wave_max(mx);
;       float s = 0.f;
;       #pragma unroll
;       for (int rd = 0; rd < 4; ++rd) { sc[rd][m] = fast_exp2(sc[rd][m] - mx); s += sc[rd][m]; }
;       s = wave_sum(s);
.Lqk_nomask:
	v_max3_f32 v0, v18, v19, v20
	v_max3_f32 v0, v0, v21, v22
	v_max3_f32 v0, v0, v23, v24
	v_max3_f32 v0, v0, v25, v26
	v_max3_f32 v0, v0, v27, v28
	v_max3_f32 v0, v0, v29, v30
	v_max3_f32 v0, v0, v31, v32
	v_max3_f32 v0, v0, v33, v34
	v_max3_f32 v0, v0, v35, v36
	v_max3_f32 v0, v0, v37, v38
	v_max3_f32 v0, v0, v39, v40
	v_max3_f32 v0, v0, v41, v42
	v_max3_f32 v0, v0, v43, v44
	v_max3_f32 v0, v0, v45, v46
	v_max3_f32 v0, v0, v47, v48
	v_max3_f32 v0, v0, v49, v50
	v_max3_f32 v0, v0, v51, v52
	v_max3_f32 v0, v0, v53, v54
	v_max3_f32 v0, v0, v55, v56
	v_max3_f32 v0, v0, v57, v58
	v_max3_f32 v0, v0, v59, v60
	v_max3_f32 v0, v0, v61, v62
	v_max3_f32 v0, v0, v63, v64
	v_max3_f32 v0, v0, v65, v66
	v_max3_f32 v0, v0, v67, v68
	v_max3_f32 v0, v0, v69, v70
	v_max3_f32 v0, v0, v71, v72
	v_max3_f32 v0, v0, v73, v74
	v_max3_f32 v0, v0, v75, v76
	v_max3_f32 v0, v0, v77, v78
	v_max3_f32 v0, v0, v79, v80
	v_max_f32_e32 v0, v0, v81
	ds_bpermute_b32 v252, v9, v0
	s_waitcnt lgkmcnt(0)
	v_max_f32_e32 v0, v0, v252
	ds_bpermute_b32 v252, v10, v0
	s_waitcnt lgkmcnt(0)
	v_max_f32_e32 v0, v0, v252
	v_sub_f32_e32 v18, v18, v0
	v_sub_f32_e32 v19, v19, v0
	v_sub_f32_e32 v20, v20, v0
	v_sub_f32_e32 v21, v21, v0
	v_sub_f32_e32 v22, v22, v0
	v_sub_f32_e32 v23, v23, v0
	v_sub_f32_e32 v24, v24, v0
	v_sub_f32_e32 v25, v25, v0
	v_sub_f32_e32 v26, v26, v0
	v_sub_f32_e32 v27, v27, v0
	v_sub_f32_e32 v28, v28, v0
	v_sub_f32_e32 v29, v29, v0
	v_sub_f32_e32 v30, v30, v0
	v_sub_f32_e32 v31, v31, v0
	v_sub_f32_e32 v32, v32, v0
	v_sub_f32_e32 v33, v33, v0
	v_sub_f32_e32 v34, v34, v0
	v_sub_f32_e32 v35, v35, v0
	v_sub_f32_e32 v36, v36, v0
	v_sub_f32_e32 v37, v37, v0
	v_sub_f32_e32 v38, v38, v0
	v_sub_f32_e32 v39, v39, v0
	v_sub_f32_e32 v40, v40, v0
	v_sub_f32_e32 v41, v41, v0
	v_sub_f32_e32 v42, v42, v0
	v_sub_f32_e32 v43, v43, v0
	v_sub_f32_e32 v44, v44, v0
	v_sub_f32_e32 v45, v45, v0
	v_sub_f32_e32 v46, v46, v0
	v_sub_f32_e32 v47, v47, v0
	v_sub_f32_e32 v48, v48, v0
	v_sub_f32_e32 v49, v49, v0
	v_sub_f32_e32 v50, v50, v0
	v_sub_f32_e32 v51, v51, v0
	v_sub_f32_e32 v52, v52, v0
	v_sub_f32_e32 v53, v53, v0
	v_sub_f32_e32 v54, v54, v0
	v_sub_f32_e32 v55, v55, v0
	v_sub_f32_e32 v56, v56, v0
	v_sub_f32_e32 v57, v57, v0
	v_sub_f32_e32 v58, v58, v0
	v_sub_f32_e32 v59, v59, v0
	v_sub_f32_e32 v60, v60, v0
	v_sub_f32_e32 v61, v61, v0
	v_sub_f32_e32 v62, v62, v0
	v_sub_f32_e32 v63, v63, v0
	v_sub_f32_e32 v64, v64, v0
	v_sub_f32_e32 v65, v65, v0
	v_sub_f32_e32 v66, v66, v0
	v_sub_f32_e32 v67, v67, v0
	v_sub_f32_e32 v68, v68, v0
	v_sub_f32_e32 v69, v69, v0
	v_sub_f32_e32 v70, v70, v0
	v_sub_f32_e32 v71, v71, v0
	v_sub_f32_e32 v72, v72, v0
	v_sub_f32_e32 v73, v73, v0
	v_sub_f32_e32 v74, v74, v0
	v_sub_f32_e32 v75, v75, v0
	v_sub_f32_e32 v76, v76, v0
	v_sub_f32_e32 v77, v77, v0
	v_sub_f32_e32 v78, v78, v0
	v_sub_f32_e32 v79, v79, v0
	v_sub_f32_e32 v80, v80, v0
	v_sub_f32_e32 v81, v81, v0
	v_exp_f32_e32 v18, v18
	v_exp_f32_e32 v19, v19
	v_exp_f32_e32 v20, v20
	v_exp_f32_e32 v21, v21
	v_exp_f32_e32 v22, v22
	v_exp_f32_e32 v23, v23
	v_exp_f32_e32 v24, v24
	v_exp_f32_e32 v25, v25
	v_exp_f32_e32 v26, v26
	v_exp_f32_e32 v27, v27
	v_exp_f32_e32 v28, v28
	v_exp_f32_e32 v29, v29
	v_exp_f32_e32 v30, v30
	v_exp_f32_e32 v31, v31
	v_exp_f32_e32 v32, v32
	v_exp_f32_e32 v33, v33
	v_exp_f32_e32 v34, v34
	v_exp_f32_e32 v35, v35
	v_exp_f32_e32 v36, v36
	v_exp_f32_e32 v37, v37
	v_exp_f32_e32 v38, v38
	v_exp_f32_e32 v39, v39
	v_exp_f32_e32 v40, v40
	v_exp_f32_e32 v41, v41
	v_exp_f32_e32 v42, v42
	v_exp_f32_e32 v43, v43
	v_exp_f32_e32 v44, v44
	v_exp_f32_e32 v45, v45
	v_exp_f32_e32 v46, v46
	v_exp_f32_e32 v47, v47
	v_exp_f32_e32 v48, v48
	v_exp_f32_e32 v49, v49
	v_exp_f32_e32 v50, v50
	v_exp_f32_e32 v51, v51
	v_exp_f32_e32 v52, v52
	v_exp_f32_e32 v53, v53
	v_exp_f32_e32 v54, v54
	v_exp_f32_e32 v55, v55
	v_exp_f32_e32 v56, v56
	v_exp_f32_e32 v57, v57
	v_exp_f32_e32 v58, v58
	v_exp_f32_e32 v59, v59
	v_exp_f32_e32 v60, v60
	v_exp_f32_e32 v61, v61
	v_exp_f32_e32 v62, v62
	v_exp_f32_e32 v63, v63
	v_exp_f32_e32 v64, v64
	v_exp_f32_e32 v65, v65
	v_exp_f32_e32 v66, v66
	v_exp_f32_e32 v67, v67
	v_exp_f32_e32 v68, v68
	v_exp_f32_e32 v69, v69
	v_exp_f32_e32 v70, v70
	v_exp_f32_e32 v71, v71
	v_exp_f32_e32 v72, v72
	v_exp_f32_e32 v73, v73
	v_exp_f32_e32 v74, v74
	v_exp_f32_e32 v75, v75
	v_exp_f32_e32 v76, v76
	v_exp_f32_e32 v77, v77
	v_exp_f32_e32 v78, v78
	v_exp_f32_e32 v79, v79
	v_exp_f32_e32 v80, v80
	v_exp_f32_e32 v81, v81
	s_nop 0
	v_add_f32_e32 v253, v18, v19
	v_add_f32_e32 v253, v253, v20
	v_add_f32_e32 v253, v253, v21
	v_add_f32_e32 v253, v253, v22
	v_add_f32_e32 v253, v253, v23
	v_add_f32_e32 v253, v253, v24
	v_add_f32_e32 v253, v253, v25
	v_add_f32_e32 v253, v253, v26
	v_add_f32_e32 v253, v253, v27
	v_add_f32_e32 v253, v253, v28
	v_add_f32_e32 v253, v253, v29
	v_add_f32_e32 v253, v253, v30
	v_add_f32_e32 v253, v253, v31
	v_add_f32_e32 v253, v253, v32
	v_add_f32_e32 v253, v253, v33
	v_add_f32_e32 v253, v253, v34
	v_add_f32_e32 v253, v253, v35
	v_add_f32_e32 v253, v253, v36
	v_add_f32_e32 v253, v253, v37
	v_add_f32_e32 v253, v253, v38
	v_add_f32_e32 v253, v253, v39
	v_add_f32_e32 v253, v253, v40
	v_add_f32_e32 v253, v253, v41
	v_add_f32_e32 v253, v253, v42
	v_add_f32_e32 v253, v253, v43
	v_add_f32_e32 v253, v253, v44
	v_add_f32_e32 v253, v253, v45
	v_add_f32_e32 v253, v253, v46
	v_add_f32_e32 v253, v253, v47
	v_add_f32_e32 v253, v253, v48
	v_add_f32_e32 v253, v253, v49
	v_add_f32_e32 v253, v253, v50
	v_add_f32_e32 v253, v253, v51
	v_add_f32_e32 v253, v253, v52
	v_add_f32_e32 v253, v253, v53
	v_add_f32_e32 v253, v253, v54
	v_add_f32_e32 v253, v253, v55
	v_add_f32_e32 v253, v253, v56
	v_add_f32_e32 v253, v253, v57
	v_add_f32_e32 v253, v253, v58
	v_add_f32_e32 v253, v253, v59
	v_add_f32_e32 v253, v253, v60
	v_add_f32_e32 v253, v253, v61
	v_add_f32_e32 v253, v253, v62
	v_add_f32_e32 v253, v253, v63
	v_add_f32_e32 v253, v253, v64
	v_add_f32_e32 v253, v253, v65
	v_add_f32_e32 v253, v253, v66
	v_add_f32_e32 v253, v253, v67
	v_add_f32_e32 v253, v253, v68
	v_add_f32_e32 v253, v253, v69
	v_add_f32_e32 v253, v253, v70
	v_add_f32_e32 v253, v253, v71
	v_add_f32_e32 v253, v253, v72
	v_add_f32_e32 v253, v253, v73
	v_add_f32_e32 v253, v253, v74
	v_add_f32_e32 v253, v253, v75
	v_add_f32_e32 v253, v253, v76
	v_add_f32_e32 v253, v253, v77
	v_add_f32_e32 v253, v253, v78
	v_add_f32_e32 v253, v253, v79
	v_add_f32_e32 v253, v253, v80
	v_add_f32_e32 v253, v253, v81
	ds_bpermute_b32 v252, v9, v253
	s_waitcnt lgkmcnt(0)
; DI void dsa_item(const Params& p, int b, int blk) {
;     ...
;       s = wave_sum(s);
;       inv[m] = 1.f / s;
;     }
;     #pragma unroll
;     for (int rd = 0; rd < 4; ++rd)
;       #pragma unroll
;       for (int m = 0; m < 8; ++m) Pb[m * PSTR + rd * 64 + lane] = f2bf(sc[rd][m] * inv[m]);
;     f32x4 oacc[8];
;     #pragma unroll
;     for (int c = 0; c < 8; ++c) oacc[c] = (f32x4){0.f, 0.f, 0.f, 0.f};
	v_add_f32_e32 v253, v253, v252
	ds_bpermute_b32 v252, v10, v253
	s_waitcnt lgkmcnt(0)
	v_add_f32_e32 v253, v253, v252
	v_div_scale_f32 v2, s[10:11], v253, v253, 1.0
	v_rcp_f32_e32 v3, v2
	s_nop 0
	v_fma_f32 v4, -v2, v3, 1.0
	v_fmac_f32_e32 v3, v4, v3
	v_div_scale_f32 v4, vcc, 1.0, v253, 1.0
	v_mul_f32_e32 v5, v4, v3
	v_fma_f32 v6, -v2, v5, v4
	v_fmac_f32_e32 v5, v6, v3
	v_fma_f32 v4, -v2, v5, v4
	s_nop 0
	v_div_fmas_f32 v4, v4, v3, v5
	v_div_fixup_f32 v4, v4, v253, 1.0
	v_mul_f32_e32 v18, v18, v4
	v_mul_f32_e32 v19, v19, v4
	v_mul_f32_e32 v20, v20, v4
	v_mul_f32_e32 v21, v21, v4
	v_mul_f32_e32 v22, v22, v4
	v_mul_f32_e32 v23, v23, v4
	v_mul_f32_e32 v24, v24, v4
	v_mul_f32_e32 v25, v25, v4
	v_mul_f32_e32 v26, v26, v4
	v_mul_f32_e32 v27, v27, v4
	v_mul_f32_e32 v28, v28, v4
	v_mul_f32_e32 v29, v29, v4
	v_mul_f32_e32 v30, v30, v4
	v_mul_f32_e32 v31, v31, v4
	v_mul_f32_e32 v32, v32, v4
	v_mul_f32_e32 v33, v33, v4
	v_mul_f32_e32 v34, v34, v4
	v_mul_f32_e32 v35, v35, v4
	v_mul_f32_e32 v36, v36, v4
	v_mul_f32_e32 v37, v37, v4
	v_mul_f32_e32 v38, v38, v4
	v_mul_f32_e32 v39, v39, v4
	v_mul_f32_e32 v40, v40, v4
	v_mul_f32_e32 v41, v41, v4
	v_mul_f32_e32 v42, v42, v4
	v_mul_f32_e32 v43, v43, v4
	v_mul_f32_e32 v44, v44, v4
	v_mul_f32_e32 v45, v45, v4
	v_mul_f32_e32 v46, v46, v4
	v_mul_f32_e32 v47, v47, v4
	v_mul_f32_e32 v48, v48, v4
	v_mul_f32_e32 v49, v49, v4
	v_mul_f32_e32 v50, v50, v4
	v_mul_f32_e32 v51, v51, v4
	v_mul_f32_e32 v52, v52, v4
	v_mul_f32_e32 v53, v53, v4
	v_mul_f32_e32 v54, v54, v4
	v_mul_f32_e32 v55, v55, v4
	v_mul_f32_e32 v56, v56, v4
	v_mul_f32_e32 v57, v57, v4
	v_mul_f32_e32 v58, v58, v4
	v_mul_f32_e32 v59, v59, v4
	v_mul_f32_e32 v60, v60, v4
	v_mul_f32_e32 v61, v61, v4
	v_mul_f32_e32 v62, v62, v4
	v_mul_f32_e32 v63, v63, v4
	v_mul_f32_e32 v64, v64, v4
	v_mul_f32_e32 v65, v65, v4
	v_mul_f32_e32 v66, v66, v4
	v_mul_f32_e32 v67, v67, v4
	v_mul_f32_e32 v68, v68, v4
	v_mul_f32_e32 v69, v69, v4
	v_mul_f32_e32 v70, v70, v4
	v_mul_f32_e32 v71, v71, v4
	v_mul_f32_e32 v72, v72, v4
	v_mul_f32_e32 v73, v73, v4
	v_mul_f32_e32 v74, v74, v4
	v_mul_f32_e32 v75, v75, v4
	v_mul_f32_e32 v76, v76, v4
	v_mul_f32_e32 v77, v77, v4
	v_mul_f32_e32 v78, v78, v4
	v_mul_f32_e32 v79, v79, v4
	v_mul_f32_e32 v80, v80, v4
	v_mul_f32_e32 v81, v81, v4
	v_cvt_pk_bf16_f32 v18, v18, v19
	v_cvt_pk_bf16_f32 v19, v20, v21
	v_cvt_pk_bf16_f32 v22, v22, v23
	v_cvt_pk_bf16_f32 v23, v24, v25
	v_cvt_pk_bf16_f32 v26, v26, v27
	v_cvt_pk_bf16_f32 v27, v28, v29
	v_cvt_pk_bf16_f32 v30, v30, v31
	v_cvt_pk_bf16_f32 v31, v32, v33
	v_cvt_pk_bf16_f32 v34, v34, v35
	v_cvt_pk_bf16_f32 v35, v36, v37
	v_cvt_pk_bf16_f32 v38, v38, v39
	v_cvt_pk_bf16_f32 v39, v40, v41
	v_cvt_pk_bf16_f32 v42, v42, v43
	v_cvt_pk_bf16_f32 v43, v44, v45
	v_cvt_pk_bf16_f32 v46, v46, v47
	v_cvt_pk_bf16_f32 v47, v48, v49
	v_cvt_pk_bf16_f32 v50, v50, v51
	v_cvt_pk_bf16_f32 v51, v52, v53
	v_cvt_pk_bf16_f32 v54, v54, v55
	v_cvt_pk_bf16_f32 v55, v56, v57
	v_cvt_pk_bf16_f32 v58, v58, v59
	v_cvt_pk_bf16_f32 v59, v60, v61
	v_cvt_pk_bf16_f32 v62, v62, v63
	v_cvt_pk_bf16_f32 v63, v64, v65
	v_cvt_pk_bf16_f32 v66, v66, v67
	v_cvt_pk_bf16_f32 v67, v68, v69
	v_cvt_pk_bf16_f32 v70, v70, v71
	v_cvt_pk_bf16_f32 v71, v72, v73
	v_cvt_pk_bf16_f32 v74, v74, v75
	v_cvt_pk_bf16_f32 v75, v76, v77
	v_cvt_pk_bf16_f32 v78, v78, v79
	v_cvt_pk_bf16_f32 v79, v80, v81
	s_mov_b32 exec_lo, 0x00ff00ff
	s_mov_b32 exec_hi, 0x00ff00ff
	ds_write_b64 v138, v[18:19]
	ds_write_b64 v138, v[22:23] offset:32
	ds_write_b64 v138, v[26:27] offset:64
	ds_write_b64 v138, v[30:31] offset:96
	ds_write_b64 v138, v[34:35] offset:128
	ds_write_b64 v138, v[38:39] offset:160
	ds_write_b64 v138, v[42:43] offset:192
	ds_write_b64 v138, v[46:47] offset:224
	ds_write_b64 v138, v[50:51] offset:256
	ds_write_b64 v138, v[54:55] offset:288
	ds_write_b64 v138, v[58:59] offset:320
	ds_write_b64 v138, v[62:63] offset:352
	ds_write_b64 v138, v[66:67] offset:384
	ds_write_b64 v138, v[70:71] offset:416
	ds_write_b64 v138, v[74:75] offset:448
	ds_write_b64 v138, v[78:79] offset:480
	s_mov_b64 exec, -1
	v_lshlrev_b64 v[66:67], 9, v[152:153]
	v_mov_b32_e32 v68, v161
	v_mov_b32_e32 v50, 0
	v_mov_b32_e32 v51, 0
	v_mov_b32_e32 v52, 0
	v_mov_b32_e32 v53, 0
	v_mov_b32_e32 v38, 0
	v_mov_b32_e32 v39, 0
	v_mov_b32_e32 v40, 0
	v_mov_b32_e32 v41, 0
	v_mov_b32_e32 v30, 0
	v_mov_b32_e32 v31, 0
	v_mov_b32_e32 v32, 0
	v_mov_b32_e32 v33, 0
	v_mov_b32_e32 v18, 0
	v_mov_b32_e32 v19, 0
	v_mov_b32_e32 v20, 0
	v_mov_b32_e32 v21, 0
	v_mov_b32_e32 v42, 0
	v_mov_b32_e32 v43, 0
	v_mov_b32_e32 v44, 0
	v_mov_b32_e32 v45, 0
	v_mov_b32_e32 v26, 0
	v_mov_b32_e32 v27, 0
	v_mov_b32_e32 v28, 0
	v_mov_b32_e32 v29, 0
	v_mov_b32_e32 v14, 0
	v_mov_b32_e32 v15, 0
	v_mov_b32_e32 v16, 0
	v_mov_b32_e32 v17, 0
	v_mov_b32_e32 v6, 0
	v_mov_b32_e32 v7, 0
	v_mov_b32_e32 v8, 0
	v_mov_b32_e32 v9, 0
	ds_read_b128 v[248:251], v242 offset:128
	s_waitcnt lgkmcnt(0)
; DI void dsa_item(const Params& p, int b, int blk) {
;     ...
;     for (int kc = 0; kc < 8; ++kc) {
;       #pragma unroll
;       for (int j = 0; j < 8; ++j) {
;         const unsigned row = 8 * g16 + j;
;         *(u32x4*)(Vc + 256u * row + 16u * ((unsigned)n16 ^ (((row & 3) << 2) | ((row >> 2) & 3)))) = vr[j];
;       }
;       if (kc < 7) {
;         const u32x4 si = *(const u32x4*)(sel + qq * 256 + (kc + 1) * 32 + 8 * g16);
;         #pragma unroll
;         for (int j = 0; j < 8; ++j) {
;           const int ks = (kc + 1) * 32 + 8 * g16 + j;
;           const int idx = ks < cnt ? (int)((si[j >> 1] >> (16 * (j & 1))) & 0xffffu) : 0;
;           vr[j] = ldg<u32x4>(Av + (rowbase + idx) * 128 + n16 * 8);
;         }
;       }
	v_add_u32_e32 v243, 0xffffffc0, v206
	v_cmp_lt_i32_e32 vcc, v156, v243
	s_nop 1
	v_cndmask_b32_sdwa v240, v1, v248, vcc dst_sel:DWORD dst_unused:UNUSED_PAD src0_sel:DWORD src1_sel:WORD_0
	v_cmp_lt_i32_e32 vcc, v192, v243
	v_lshl_add_u64 v[244:245], s[16:17], 0, v[240:241]
	v_lshlrev_b64 v[244:245], 8, v[244:245]
	v_lshl_add_u64 v[244:245], v[148:149], 0, v[244:245]
	global_load_dwordx4 v[2:5], v[244:245], off
	v_cndmask_b32_sdwa v240, v1, v248, vcc dst_sel:DWORD dst_unused:UNUSED_PAD src0_sel:DWORD src1_sel:WORD_1
	v_cmp_lt_i32_e32 vcc, v193, v243
	v_lshl_add_u64 v[246:247], s[16:17], 0, v[240:241]
	v_lshlrev_b64 v[246:247], 8, v[246:247]
	v_lshl_add_u64 v[246:247], v[148:149], 0, v[246:247]
	global_load_dwordx4 v[10:13], v[246:247], off
	v_cndmask_b32_sdwa v240, v1, v249, vcc dst_sel:DWORD dst_unused:UNUSED_PAD src0_sel:DWORD src1_sel:WORD_0
	v_cmp_lt_i32_e32 vcc, v194, v243
	v_lshl_add_u64 v[244:245], s[16:17], 0, v[240:241]
	v_lshlrev_b64 v[244:245], 8, v[244:245]
	v_lshl_add_u64 v[244:245], v[148:149], 0, v[244:245]
	global_load_dwordx4 v[22:25], v[244:245], off
	v_cndmask_b32_sdwa v240, v1, v249, vcc dst_sel:DWORD dst_unused:UNUSED_PAD src0_sel:DWORD src1_sel:WORD_1
	v_cmp_lt_i32_e32 vcc, v157, v243
	v_lshl_add_u64 v[246:247], s[16:17], 0, v[240:241]
	v_lshlrev_b64 v[246:247], 8, v[246:247]
	v_lshl_add_u64 v[246:247], v[148:149], 0, v[246:247]
	global_load_dwordx4 v[34:37], v[246:247], off
	v_cndmask_b32_sdwa v240, v1, v250, vcc dst_sel:DWORD dst_unused:UNUSED_PAD src0_sel:DWORD src1_sel:WORD_0
	v_cmp_lt_i32_e32 vcc, v195, v243
	v_lshl_add_u64 v[244:245], s[16:17], 0, v[240:241]
	v_lshlrev_b64 v[244:245], 8, v[244:245]
	v_lshl_add_u64 v[244:245], v[148:149], 0, v[244:245]
	global_load_dwordx4 v[46:49], v[244:245], off
	v_cndmask_b32_sdwa v240, v1, v250, vcc dst_sel:DWORD dst_unused:UNUSED_PAD src0_sel:DWORD src1_sel:WORD_1
	v_cmp_lt_i32_e32 vcc, v196, v243
	v_lshl_add_u64 v[246:247], s[16:17], 0, v[240:241]
	v_lshlrev_b64 v[246:247], 8, v[246:247]
	v_lshl_add_u64 v[246:247], v[148:149], 0, v[246:247]
	global_load_dwordx4 v[54:57], v[246:247], off
	v_cndmask_b32_sdwa v240, v1, v251, vcc dst_sel:DWORD dst_unused:UNUSED_PAD src0_sel:DWORD src1_sel:WORD_0
	v_cmp_lt_i32_e32 vcc, v197, v243
	v_lshl_add_u64 v[244:245], s[16:17], 0, v[240:241]
	v_lshlrev_b64 v[244:245], 8, v[244:245]
	v_lshl_add_u64 v[244:245], v[148:149], 0, v[244:245]
	global_load_dwordx4 v[58:61], v[244:245], off
	v_cndmask_b32_sdwa v240, v1, v251, vcc dst_sel:DWORD dst_unused:UNUSED_PAD src0_sel:DWORD src1_sel:WORD_1
	v_lshl_add_u64 v[246:247], s[16:17], 0, v[240:241]
	v_lshlrev_b64 v[246:247], 8, v[246:247]
	v_lshl_add_u64 v[246:247], v[148:149], 0, v[246:247]
	global_load_dwordx4 v[62:65], v[246:247], off
	s_waitcnt vmcnt(16)
	ds_write_b128 v198, v[208:211]
	ds_write_b128 v199, v[212:215]
	ds_write_b128 v200, v[216:219]
	ds_write_b128 v201, v[220:223]
	ds_write_b128 v202, v[224:227]
	ds_write_b128 v203, v[228:231]
	ds_write_b128 v204, v[232:235]
	ds_write_b128 v205, v[236:239]
	ds_read_b128 v[248:251], v242 offset:192
	s_waitcnt lgkmcnt(0)
	v_add_u32_e32 v243, 0xffffffa0, v206
	v_cmp_lt_i32_e32 vcc, v156, v243
	s_nop 1
	v_cndmask_b32_sdwa v240, v1, v248, vcc dst_sel:DWORD dst_unused:UNUSED_PAD src0_sel:DWORD src1_sel:WORD_0
	v_cmp_lt_i32_e32 vcc, v192, v243
	v_lshl_add_u64 v[244:245], s[16:17], 0, v[240:241]
	v_lshlrev_b64 v[244:245], 8, v[244:245]
	v_lshl_add_u64 v[244:245], v[148:149], 0, v[244:245]
	global_load_dwordx4 v[208:211], v[244:245], off
	v_cndmask_b32_sdwa v240, v1, v248, vcc dst_sel:DWORD dst_unused:UNUSED_PAD src0_sel:DWORD src1_sel:WORD_1
	v_cmp_lt_i32_e32 vcc, v193, v243
	v_lshl_add_u64 v[246:247], s[16:17], 0, v[240:241]
	v_lshlrev_b64 v[246:247], 8, v[246:247]
	v_lshl_add_u64 v[246:247], v[148:149], 0, v[246:247]
	global_load_dwordx4 v[212:215], v[246:247], off
	v_cndmask_b32_sdwa v240, v1, v249, vcc dst_sel:DWORD dst_unused:UNUSED_PAD src0_sel:DWORD src1_sel:WORD_0
	v_cmp_lt_i32_e32 vcc, v194, v243
	v_lshl_add_u64 v[244:245], s[16:17], 0, v[240:241]
	v_lshlrev_b64 v[244:245], 8, v[244:245]
	v_lshl_add_u64 v[244:245], v[148:149], 0, v[244:245]
	global_load_dwordx4 v[216:219], v[244:245], off
	v_cndmask_b32_sdwa v240, v1, v249, vcc dst_sel:DWORD dst_unused:UNUSED_PAD src0_sel:DWORD src1_sel:WORD_1
	v_cmp_lt_i32_e32 vcc, v157, v243
	v_lshl_add_u64 v[246:247], s[16:17], 0, v[240:241]
	v_lshlrev_b64 v[246:247], 8, v[246:247]
	v_lshl_add_u64 v[246:247], v[148:149], 0, v[246:247]
	global_load_dwordx4 v[220:223], v[246:247], off
	v_cndmask_b32_sdwa v240, v1, v250, vcc dst_sel:DWORD dst_unused:UNUSED_PAD src0_sel:DWORD src1_sel:WORD_0
	v_cmp_lt_i32_e32 vcc, v195, v243
	v_lshl_add_u64 v[244:245], s[16:17], 0, v[240:241]
	v_lshlrev_b64 v[244:245], 8, v[244:245]
	v_lshl_add_u64 v[244:245], v[148:149], 0, v[244:245]
	global_load_dwordx4 v[224:227], v[244:245], off
	v_cndmask_b32_sdwa v240, v1, v250, vcc dst_sel:DWORD dst_unused:UNUSED_PAD src0_sel:DWORD src1_sel:WORD_1
	v_cmp_lt_i32_e32 vcc, v196, v243
	v_lshl_add_u64 v[246:247], s[16:17], 0, v[240:241]
	v_lshlrev_b64 v[246:247], 8, v[246:247]
	v_lshl_add_u64 v[246:247], v[148:149], 0, v[246:247]
	global_load_dwordx4 v[228:231], v[246:247], off
	v_cndmask_b32_sdwa v240, v1, v251, vcc dst_sel:DWORD dst_unused:UNUSED_PAD src0_sel:DWORD src1_sel:WORD_0
	v_cmp_lt_i32_e32 vcc, v197, v243
	v_lshl_add_u64 v[244:245], s[16:17], 0, v[240:241]
	v_lshlrev_b64 v[244:245], 8, v[244:245]
	v_lshl_add_u64 v[244:245], v[148:149], 0, v[244:245]
	global_load_dwordx4 v[232:235], v[244:245], off
	v_cndmask_b32_sdwa v240, v1, v251, vcc dst_sel:DWORD dst_unused:UNUSED_PAD src0_sel:DWORD src1_sel:WORD_1
	v_lshl_add_u64 v[246:247], s[16:17], 0, v[240:241]
	v_lshlrev_b64 v[246:247], 8, v[246:247]
	v_lshl_add_u64 v[246:247], v[148:149], 0, v[246:247]
	global_load_dwordx4 v[236:239], v[246:247], off
	ds_read_b128 v[70:73], v68
	s_waitcnt lgkmcnt(0)
; DI void dsa_item(const Params& p, int b, int blk) {
;     ...
;     for (int kc = 0; kc < 8; ++kc) {
;       #pragma unroll
;       for (int j = 0; j < 8; ++j) {
;         const unsigned row = 8 * g16 + j;
;         *(u32x4*)(Vc + 256u * row + 16u * ((unsigned)n16 ^ (((row & 3) << 2) | ((row >> 2) & 3)))) = vr[j];
;       }
;       if (kc < 7) {
;         const u32x4 si = *(const u32x4*)(sel + qq * 256 + (kc + 1) * 32 + 8 * g16);
;         #pragma unroll
;         for (int j = 0; j < 8; ++j) {
;           const int ks = (kc + 1) * 32 + 8 * g16 + j;
;           const int idx = ks < cnt ? (int)((si[j >> 1] >> (16 * (j & 1))) & 0xffffu) : 0;
;           vr[j] = ldg<u32x4>(Av + (rowbase + idx) * 128 + n16 * 8);
;         }
;       }
;       const bf16x8 pa = *(const bf16x8*)(Pb + arow * PSTR + kc * 32 + g16 * 8);
;       u32x2 t0[8], t1[8];
;       asm volatile(
;           "s_waitcnt lgkmcnt(0)\n\t"
;           "ds_read_b64_tr_b16 %0, %16\n\tds_read_b64_tr_b16 %1, %17\n\tds_read_b64_tr_b16 %2, %18\n\tds_read_b64_tr_b16 %3, %19\n\t"
;           "ds_read_b64_tr_b16 %4, %20\n\tds_read_b64_tr_b16 %5, %21\n\tds_read_b64_tr_b16 %6, %22\n\tds_read_b64_tr_b16 %7, %23\n\t"
;           "ds_read_b64_tr_b16 %8, %24\n\tds_read_b64_tr_b16 %9, %25\n\tds_read_b64_tr_b16 %10, %26\n\tds_read_b64_tr_b16 %11, %27\n\t"
;           "ds_read_b64_tr_b16 %12, %28\n\tds_read_b64_tr_b16 %13, %29\n\tds_read_b64_tr_b16 %14, %30\n\tds_read_b64_tr_b16 %15, %31\n\t"
;           "s_waitcnt lgkmcnt(0)"
;           : "=&v"(t0[0]), "=&v"(t1[0]), "=&v"(t0[1]), "=&v"(t1[1]), "=&v"(t0[2]), "=&v"(t1[2]), "=&v"(t0[3]), "=&v"(t1[3]),
;             "=&v"(t0[4]), "=&v"(t1[4]), "=&v"(t0[5]), "=&v"(t1[5]), "=&v"(t0[6]), "=&v"(t1[6]), "=&v"(t0[7]), "=&v"(t1[7])
;           : "v"(lds_base + taddr[0][0]), "v"(lds_base + taddr[0][1]), "v"(lds_base + taddr[1][0]), "v"(lds_base + taddr[1][1]),
;             "v"(lds_base + taddr[2][0]), "v"(lds_base + taddr[2][1]), "v"(lds_base + taddr[3][0]), "v"(lds_base + taddr[3][1]),
;             "v"(lds_base + taddr[4][0]), "v"(lds_base + taddr[4][1]), "v"(lds_base + taddr[5][0]), "v"(lds_base + taddr[5][1]),
;             "v"(lds_base + taddr[6][0]), "v"(lds_base + taddr[6][1]), "v"(lds_base + taddr[7][0]), "v"(lds_base + taddr[7][1])
;           : "memory");
;       #pragma unroll
;       for (int c = 0; c < 8; ++c) {
	ds_read_b64_tr_b16 v[102:103], v162
	ds_read_b64_tr_b16 v[104:105], v163
	ds_read_b64_tr_b16 v[98:99], v164
	ds_read_b64_tr_b16 v[100:101], v165
	ds_read_b64_tr_b16 v[94:95], v166
	ds_read_b64_tr_b16 v[96:97], v167
	ds_read_b64_tr_b16 v[90:91], v168
	ds_read_b64_tr_b16 v[92:93], v169
	ds_read_b64_tr_b16 v[86:87], v170
	ds_read_b64_tr_b16 v[88:89], v171
	ds_read_b64_tr_b16 v[82:83], v172
	ds_read_b64_tr_b16 v[84:85], v173
	ds_read_b64_tr_b16 v[78:79], v174
	ds_read_b64_tr_b16 v[80:81], v175
	ds_read_b64_tr_b16 v[74:75], v176
	ds_read_b64_tr_b16 v[76:77], v177
	s_waitcnt lgkmcnt(0)
	v_mfma_f32_16x16x32_bf16 v[50:53], v[70:73], v[102:105], v[50:53]
	v_mfma_f32_16x16x32_bf16 v[38:41], v[70:73], v[98:101], v[38:41]
	v_mfma_f32_16x16x32_bf16 v[30:33], v[70:73], v[94:97], v[30:33]
	v_mfma_f32_16x16x32_bf16 v[18:21], v[70:73], v[90:93], v[18:21]
	v_mfma_f32_16x16x32_bf16 v[42:45], v[70:73], v[86:89], v[42:45]
	v_mfma_f32_16x16x32_bf16 v[26:29], v[70:73], v[82:85], v[26:29]
	v_mfma_f32_16x16x32_bf16 v[14:17], v[70:73], v[78:81], v[14:17]
	v_mfma_f32_16x16x32_bf16 v[6:9], v[70:73], v[74:77], v[6:9]
	s_waitcnt vmcnt(16)
	ds_write_b128 v198, v[106:109]
	ds_write_b128 v199, v[110:113]
	ds_write_b128 v200, v[114:117]
	ds_write_b128 v201, v[118:121]
	ds_write_b128 v202, v[122:125]
	ds_write_b128 v203, v[126:129]
	ds_write_b128 v204, v[130:133]
	ds_write_b128 v205, v[134:137]
	ds_read_b128 v[248:251], v242 offset:256
	s_waitcnt lgkmcnt(0)
	v_add_u32_e32 v243, 0xffffff80, v206
	v_cmp_lt_i32_e32 vcc, v156, v243
	s_nop 1
	v_cndmask_b32_sdwa v240, v1, v248, vcc dst_sel:DWORD dst_unused:UNUSED_PAD src0_sel:DWORD src1_sel:WORD_0
	v_cmp_lt_i32_e32 vcc, v192, v243
	v_lshl_add_u64 v[244:245], s[16:17], 0, v[240:241]
	v_lshlrev_b64 v[244:245], 8, v[244:245]
	v_lshl_add_u64 v[244:245], v[148:149], 0, v[244:245]
	global_load_dwordx4 v[106:109], v[244:245], off
	v_cndmask_b32_sdwa v240, v1, v248, vcc dst_sel:DWORD dst_unused:UNUSED_PAD src0_sel:DWORD src1_sel:WORD_1
	v_cmp_lt_i32_e32 vcc, v193, v243
	v_lshl_add_u64 v[246:247], s[16:17], 0, v[240:241]
	v_lshlrev_b64 v[246:247], 8, v[246:247]
	v_lshl_add_u64 v[246:247], v[148:149], 0, v[246:247]
	global_load_dwordx4 v[110:113], v[246:247], off
	v_cndmask_b32_sdwa v240, v1, v249, vcc dst_sel:DWORD dst_unused:UNUSED_PAD src0_sel:DWORD src1_sel:WORD_0
	v_cmp_lt_i32_e32 vcc, v194, v243
	v_lshl_add_u64 v[244:245], s[16:17], 0, v[240:241]
	v_lshlrev_b64 v[244:245], 8, v[244:245]
	v_lshl_add_u64 v[244:245], v[148:149], 0, v[244:245]
	global_load_dwordx4 v[114:117], v[244:245], off
	v_cndmask_b32_sdwa v240, v1, v249, vcc dst_sel:DWORD dst_unused:UNUSED_PAD src0_sel:DWORD src1_sel:WORD_1
	v_cmp_lt_i32_e32 vcc, v157, v243
	v_lshl_add_u64 v[246:247], s[16:17], 0, v[240:241]
	v_lshlrev_b64 v[246:247], 8, v[246:247]
	v_lshl_add_u64 v[246:247], v[148:149], 0, v[246:247]
	global_load_dwordx4 v[118:121], v[246:247], off
	v_cndmask_b32_sdwa v240, v1, v250, vcc dst_sel:DWORD dst_unused:UNUSED_PAD src0_sel:DWORD src1_sel:WORD_0
	v_cmp_lt_i32_e32 vcc, v195, v243
	v_lshl_add_u64 v[244:245], s[16:17], 0, v[240:241]
	v_lshlrev_b64 v[244:245], 8, v[244:245]
	v_lshl_add_u64 v[244:245], v[148:149], 0, v[244:245]
	global_load_dwordx4 v[122:125], v[244:245], off
	v_cndmask_b32_sdwa v240, v1, v250, vcc dst_sel:DWORD dst_unused:UNUSED_PAD src0_sel:DWORD src1_sel:WORD_1
	v_cmp_lt_i32_e32 vcc, v196, v243
	v_lshl_add_u64 v[246:247], s[16:17], 0, v[240:241]
	v_lshlrev_b64 v[246:247], 8, v[246:247]
	v_lshl_add_u64 v[246:247], v[148:149], 0, v[246:247]
	global_load_dwordx4 v[126:129], v[246:247], off
	v_cndmask_b32_sdwa v240, v1, v251, vcc dst_sel:DWORD dst_unused:UNUSED_PAD src0_sel:DWORD src1_sel:WORD_0
	v_cmp_lt_i32_e32 vcc, v197, v243
	v_lshl_add_u64 v[244:245], s[16:17], 0, v[240:241]
	v_lshlrev_b64 v[244:245], 8, v[244:245]
	v_lshl_add_u64 v[244:245], v[148:149], 0, v[244:245]
	global_load_dwordx4 v[130:133], v[244:245], off
	v_cndmask_b32_sdwa v240, v1, v251, vcc dst_sel:DWORD dst_unused:UNUSED_PAD src0_sel:DWORD src1_sel:WORD_1
	v_lshl_add_u64 v[246:247], s[16:17], 0, v[240:241]
	v_lshlrev_b64 v[246:247], 8, v[246:247]
	v_lshl_add_u64 v[246:247], v[148:149], 0, v[246:247]
	global_load_dwordx4 v[134:137], v[246:247], off
	ds_read_b128 v[70:73], v68 offset:64
	s_waitcnt lgkmcnt(0)
	ds_read_b64_tr_b16 v[102:103], v162
	ds_read_b64_tr_b16 v[104:105], v163
	ds_read_b64_tr_b16 v[98:99], v164
	ds_read_b64_tr_b16 v[100:101], v165
	ds_read_b64_tr_b16 v[94:95], v166
	ds_read_b64_tr_b16 v[96:97], v167
	ds_read_b64_tr_b16 v[90:91], v168
	ds_read_b64_tr_b16 v[92:93], v169
	ds_read_b64_tr_b16 v[86:87], v170
	ds_read_b64_tr_b16 v[88:89], v171
	ds_read_b64_tr_b16 v[82:83], v172
	ds_read_b64_tr_b16 v[84:85], v173
	ds_read_b64_tr_b16 v[78:79], v174
	ds_read_b64_tr_b16 v[80:81], v175
	ds_read_b64_tr_b16 v[74:75], v176
	ds_read_b64_tr_b16 v[76:77], v177
	s_waitcnt lgkmcnt(0)
	v_mfma_f32_16x16x32_bf16 v[50:53], v[70:73], v[102:105], v[50:53]
	v_mfma_f32_16x16x32_bf16 v[38:41], v[70:73], v[98:101], v[38:41]
	v_mfma_f32_16x16x32_bf16 v[30:33], v[70:73], v[94:97], v[30:33]
	v_mfma_f32_16x16x32_bf16 v[18:21], v[70:73], v[90:93], v[18:21]
	v_mfma_f32_16x16x32_bf16 v[42:45], v[70:73], v[86:89], v[42:45]
	v_mfma_f32_16x16x32_bf16 v[26:29], v[70:73], v[82:85], v[26:29]
	v_mfma_f32_16x16x32_bf16 v[14:17], v[70:73], v[78:81], v[14:17]
	v_mfma_f32_16x16x32_bf16 v[6:9], v[70:73], v[74:77], v[6:9]
	s_waitcnt vmcnt(16)
	ds_write_b128 v198, v[2:5]
	ds_write_b128 v199, v[10:13]
	ds_write_b128 v200, v[22:25]
	ds_write_b128 v201, v[34:37]
	ds_write_b128 v202, v[46:49]
	ds_write_b128 v203, v[54:57]
	ds_write_b128 v204, v[58:61]
	ds_write_b128 v205, v[62:65]
	ds_read_b128 v[248:251], v242 offset:320
	s_waitcnt lgkmcnt(0)
; DI void dsa_item(const Params& p, int b, int blk) {
;     ...
;     for (int kc = 0; kc < 8; ++kc) {
;       #pragma unroll
;       for (int j = 0; j < 8; ++j) {
;         const unsigned row = 8 * g16 + j;
;         *(u32x4*)(Vc + 256u * row + 16u * ((unsigned)n16 ^ (((row & 3) << 2) | ((row >> 2) & 3)))) = vr[j];
;       }
;       if (kc < 7) {
;         const u32x4 si = *(const u32x4*)(sel + qq * 256 + (kc + 1) * 32 + 8 * g16);
;         #pragma unroll
;         for (int j = 0; j < 8; ++j) {
;           const int ks = (kc + 1) * 32 + 8 * g16 + j;
;           const int idx = ks < cnt ? (int)((si[j >> 1] >> (16 * (j & 1))) & 0xffffu) : 0;
;           vr[j] = ldg<u32x4>(Av + (rowbase + idx) * 128 + n16 * 8);
;         }
;       }
;       const bf16x8 pa = *(const bf16x8*)(Pb + arow * PSTR + kc * 32 + g16 * 8);
;       u32x2 t0[8], t1[8];
;       asm volatile(
;           "s_waitcnt lgkmcnt(0)\n\t"
;           "ds_read_b64_tr_b16 %0, %16\n\tds_read_b64_tr_b16 %1, %17\n\tds_read_b64_tr_b16 %2, %18\n\tds_read_b64_tr_b16 %3, %19\n\t"
;           "ds_read_b64_tr_b16 %4, %20\n\tds_read_b64_tr_b16 %5, %21\n\tds_read_b64_tr_b16 %6, %22\n\tds_read_b64_tr_b16 %7, %23\n\t"
;           "ds_read_b64_tr_b16 %8, %24\n\tds_read_b64_tr_b16 %9, %25\n\tds_read_b64_tr_b16 %10, %26\n\tds_read_b64_tr_b16 %11, %27\n\t"
;           "ds_read_b64_tr_b16 %12, %28\n\tds_read_b64_tr_b16 %13, %29\n\tds_read_b64_tr_b16 %14, %30\n\tds_read_b64_tr_b16 %15, %31\n\t"
;           "s_waitcnt lgkmcnt(0)"
;           : "=&v"(t0[0]), "=&v"(t1[0]), "=&v"(t0[1]), "=&v"(t1[1]), "=&v"(t0[2]), "=&v"(t1[2]), "=&v"(t0[3]), "=&v"(t1[3]),
;             "=&v"(t0[4]), "=&v"(t1[4]), "=&v"(t0[5]), "=&v"(t1[5]), "=&v"(t0[6]), "=&v"(t1[6]), "=&v"(t0[7]), "=&v"(t1[7])
;           : "v"(lds_base + taddr[0][0]), "v"(lds_base + taddr[0][1]), "v"(lds_base + taddr[1][0]), "v"(lds_base + taddr[1][1]),
;             "v"(lds_base + taddr[2][0]), "v"(lds_base + taddr[2][1]), "v"(lds_base + taddr[3][0]), "v"(lds_base + taddr[3][1]),
;             "v"(lds_base + taddr[4][0]), "v"(lds_base + taddr[4][1]), "v"(lds_base + taddr[5][0]), "v"(lds_base + taddr[5][1]),
;             "v"(lds_base + taddr[6][0]), "v"(lds_base + taddr[6][1]), "v"(lds_base + taddr[7][0]), "v"(lds_base + taddr[7][1])
;           : "memory");
;       #pragma unroll
;       for (int c = 0; c < 8; ++c) {
	v_add_u32_e32 v243, 0xffffff60, v206
	v_cmp_lt_i32_e32 vcc, v156, v243
	s_nop 1
	v_cndmask_b32_sdwa v240, v1, v248, vcc dst_sel:DWORD dst_unused:UNUSED_PAD src0_sel:DWORD src1_sel:WORD_0
	v_cmp_lt_i32_e32 vcc, v192, v243
	v_lshl_add_u64 v[244:245], s[16:17], 0, v[240:241]
	v_lshlrev_b64 v[244:245], 8, v[244:245]
	v_lshl_add_u64 v[244:245], v[148:149], 0, v[244:245]
	global_load_dwordx4 v[2:5], v[244:245], off
	v_cndmask_b32_sdwa v240, v1, v248, vcc dst_sel:DWORD dst_unused:UNUSED_PAD src0_sel:DWORD src1_sel:WORD_1
	v_cmp_lt_i32_e32 vcc, v193, v243
	v_lshl_add_u64 v[246:247], s[16:17], 0, v[240:241]
	v_lshlrev_b64 v[246:247], 8, v[246:247]
	v_lshl_add_u64 v[246:247], v[148:149], 0, v[246:247]
	global_load_dwordx4 v[10:13], v[246:247], off
	v_cndmask_b32_sdwa v240, v1, v249, vcc dst_sel:DWORD dst_unused:UNUSED_PAD src0_sel:DWORD src1_sel:WORD_0
	v_cmp_lt_i32_e32 vcc, v194, v243
	v_lshl_add_u64 v[244:245], s[16:17], 0, v[240:241]
	v_lshlrev_b64 v[244:245], 8, v[244:245]
	v_lshl_add_u64 v[244:245], v[148:149], 0, v[244:245]
	global_load_dwordx4 v[22:25], v[244:245], off
	v_cndmask_b32_sdwa v240, v1, v249, vcc dst_sel:DWORD dst_unused:UNUSED_PAD src0_sel:DWORD src1_sel:WORD_1
	v_cmp_lt_i32_e32 vcc, v157, v243
	v_lshl_add_u64 v[246:247], s[16:17], 0, v[240:241]
	v_lshlrev_b64 v[246:247], 8, v[246:247]
	v_lshl_add_u64 v[246:247], v[148:149], 0, v[246:247]
	global_load_dwordx4 v[34:37], v[246:247], off
	v_cndmask_b32_sdwa v240, v1, v250, vcc dst_sel:DWORD dst_unused:UNUSED_PAD src0_sel:DWORD src1_sel:WORD_0
	v_cmp_lt_i32_e32 vcc, v195, v243
	v_lshl_add_u64 v[244:245], s[16:17], 0, v[240:241]
	v_lshlrev_b64 v[244:245], 8, v[244:245]
	v_lshl_add_u64 v[244:245], v[148:149], 0, v[244:245]
	global_load_dwordx4 v[46:49], v[244:245], off
	v_cndmask_b32_sdwa v240, v1, v250, vcc dst_sel:DWORD dst_unused:UNUSED_PAD src0_sel:DWORD src1_sel:WORD_1
	v_cmp_lt_i32_e32 vcc, v196, v243
	v_lshl_add_u64 v[246:247], s[16:17], 0, v[240:241]
	v_lshlrev_b64 v[246:247], 8, v[246:247]
	v_lshl_add_u64 v[246:247], v[148:149], 0, v[246:247]
	global_load_dwordx4 v[54:57], v[246:247], off
	v_cndmask_b32_sdwa v240, v1, v251, vcc dst_sel:DWORD dst_unused:UNUSED_PAD src0_sel:DWORD src1_sel:WORD_0
	v_cmp_lt_i32_e32 vcc, v197, v243
	v_lshl_add_u64 v[244:245], s[16:17], 0, v[240:241]
	v_lshlrev_b64 v[244:245], 8, v[244:245]
	v_lshl_add_u64 v[244:245], v[148:149], 0, v[244:245]
	global_load_dwordx4 v[58:61], v[244:245], off
	v_cndmask_b32_sdwa v240, v1, v251, vcc dst_sel:DWORD dst_unused:UNUSED_PAD src0_sel:DWORD src1_sel:WORD_1
	v_lshl_add_u64 v[246:247], s[16:17], 0, v[240:241]
	v_lshlrev_b64 v[246:247], 8, v[246:247]
	v_lshl_add_u64 v[246:247], v[148:149], 0, v[246:247]
	global_load_dwordx4 v[62:65], v[246:247], off
	ds_read_b128 v[70:73], v68 offset:128
	s_waitcnt lgkmcnt(0)
	ds_read_b64_tr_b16 v[102:103], v162
	ds_read_b64_tr_b16 v[104:105], v163
	ds_read_b64_tr_b16 v[98:99], v164
	ds_read_b64_tr_b16 v[100:101], v165
	ds_read_b64_tr_b16 v[94:95], v166
	ds_read_b64_tr_b16 v[96:97], v167
	ds_read_b64_tr_b16 v[90:91], v168
	ds_read_b64_tr_b16 v[92:93], v169
	ds_read_b64_tr_b16 v[86:87], v170
	ds_read_b64_tr_b16 v[88:89], v171
	ds_read_b64_tr_b16 v[82:83], v172
	ds_read_b64_tr_b16 v[84:85], v173
	ds_read_b64_tr_b16 v[78:79], v174
	ds_read_b64_tr_b16 v[80:81], v175
	ds_read_b64_tr_b16 v[74:75], v176
	ds_read_b64_tr_b16 v[76:77], v177
	s_waitcnt lgkmcnt(0)
	v_mfma_f32_16x16x32_bf16 v[50:53], v[70:73], v[102:105], v[50:53]
	v_mfma_f32_16x16x32_bf16 v[38:41], v[70:73], v[98:101], v[38:41]
	v_mfma_f32_16x16x32_bf16 v[30:33], v[70:73], v[94:97], v[30:33]
	v_mfma_f32_16x16x32_bf16 v[18:21], v[70:73], v[90:93], v[18:21]
	v_mfma_f32_16x16x32_bf16 v[42:45], v[70:73], v[86:89], v[42:45]
	v_mfma_f32_16x16x32_bf16 v[26:29], v[70:73], v[82:85], v[26:29]
	v_mfma_f32_16x16x32_bf16 v[14:17], v[70:73], v[78:81], v[14:17]
	v_mfma_f32_16x16x32_bf16 v[6:9], v[70:73], v[74:77], v[6:9]
	s_waitcnt vmcnt(16)
	ds_write_b128 v198, v[208:211]
	ds_write_b128 v199, v[212:215]
	ds_write_b128 v200, v[216:219]
	ds_write_b128 v201, v[220:223]
	ds_write_b128 v202, v[224:227]
	ds_write_b128 v203, v[228:231]
	ds_write_b128 v204, v[232:235]
	ds_write_b128 v205, v[236:239]
	ds_read_b128 v[248:251], v242 offset:384
	s_waitcnt lgkmcnt(0)
	v_add_u32_e32 v243, 0xffffff40, v206
	v_cmp_lt_i32_e32 vcc, v156, v243
	s_nop 1
	v_cndmask_b32_sdwa v240, v1, v248, vcc dst_sel:DWORD dst_unused:UNUSED_PAD src0_sel:DWORD src1_sel:WORD_0
	v_cmp_lt_i32_e32 vcc, v192, v243
	v_lshl_add_u64 v[244:245], s[16:17], 0, v[240:241]
	v_lshlrev_b64 v[244:245], 8, v[244:245]
	v_lshl_add_u64 v[244:245], v[148:149], 0, v[244:245]
	global_load_dwordx4 v[208:211], v[244:245], off
	v_cndmask_b32_sdwa v240, v1, v248, vcc dst_sel:DWORD dst_unused:UNUSED_PAD src0_sel:DWORD src1_sel:WORD_1
	v_cmp_lt_i32_e32 vcc, v193, v243
	v_lshl_add_u64 v[246:247], s[16:17], 0, v[240:241]
	v_lshlrev_b64 v[246:247], 8, v[246:247]
	v_lshl_add_u64 v[246:247], v[148:149], 0, v[246:247]
	global_load_dwordx4 v[212:215], v[246:247], off
	v_cndmask_b32_sdwa v240, v1, v249, vcc dst_sel:DWORD dst_unused:UNUSED_PAD src0_sel:DWORD src1_sel:WORD_0
	v_cmp_lt_i32_e32 vcc, v194, v243
	v_lshl_add_u64 v[244:245], s[16:17], 0, v[240:241]
	v_lshlrev_b64 v[244:245], 8, v[244:245]
	v_lshl_add_u64 v[244:245], v[148:149], 0, v[244:245]
	global_load_dwordx4 v[216:219], v[244:245], off
	v_cndmask_b32_sdwa v240, v1, v249, vcc dst_sel:DWORD dst_unused:UNUSED_PAD src0_sel:DWORD src1_sel:WORD_1
	v_cmp_lt_i32_e32 vcc, v157, v243
	v_lshl_add_u64 v[246:247], s[16:17], 0, v[240:241]
	v_lshlrev_b64 v[246:247], 8, v[246:247]
	v_lshl_add_u64 v[246:247], v[148:149], 0, v[246:247]
	global_load_dwordx4 v[220:223], v[246:247], off
	v_cndmask_b32_sdwa v240, v1, v250, vcc dst_sel:DWORD dst_unused:UNUSED_PAD src0_sel:DWORD src1_sel:WORD_0
	v_cmp_lt_i32_e32 vcc, v195, v243
	v_lshl_add_u64 v[244:245], s[16:17], 0, v[240:241]
	v_lshlrev_b64 v[244:245], 8, v[244:245]
	v_lshl_add_u64 v[244:245], v[148:149], 0, v[244:245]
	global_load_dwordx4 v[224:227], v[244:245], off
	v_cndmask_b32_sdwa v240, v1, v250, vcc dst_sel:DWORD dst_unused:UNUSED_PAD src0_sel:DWORD src1_sel:WORD_1
	v_cmp_lt_i32_e32 vcc, v196, v243
	v_lshl_add_u64 v[246:247], s[16:17], 0, v[240:241]
	v_lshlrev_b64 v[246:247], 8, v[246:247]
	v_lshl_add_u64 v[246:247], v[148:149], 0, v[246:247]
	global_load_dwordx4 v[228:231], v[246:247], off
	v_cndmask_b32_sdwa v240, v1, v251, vcc dst_sel:DWORD dst_unused:UNUSED_PAD src0_sel:DWORD src1_sel:WORD_0
	v_cmp_lt_i32_e32 vcc, v197, v243
	v_lshl_add_u64 v[244:245], s[16:17], 0, v[240:241]
	v_lshlrev_b64 v[244:245], 8, v[244:245]
	v_lshl_add_u64 v[244:245], v[148:149], 0, v[244:245]
	global_load_dwordx4 v[232:235], v[244:245], off
	v_cndmask_b32_sdwa v240, v1, v251, vcc dst_sel:DWORD dst_unused:UNUSED_PAD src0_sel:DWORD src1_sel:WORD_1
	v_lshl_add_u64 v[246:247], s[16:17], 0, v[240:241]
	v_lshlrev_b64 v[246:247], 8, v[246:247]
	v_lshl_add_u64 v[246:247], v[148:149], 0, v[246:247]
	global_load_dwordx4 v[236:239], v[246:247], off
	ds_read_b128 v[70:73], v68 offset:192
	s_waitcnt lgkmcnt(0)
; DI void dsa_item(const Params& p, int b, int blk) {
;     ...
;     for (int kc = 0; kc < 8; ++kc) {
;       #pragma unroll
;       for (int j = 0; j < 8; ++j) {
;         const unsigned row = 8 * g16 + j;
;         *(u32x4*)(Vc + 256u * row + 16u * ((unsigned)n16 ^ (((row & 3) << 2) | ((row >> 2) & 3)))) = vr[j];
;       }
;       if (kc < 7) {
;         const u32x4 si = *(const u32x4*)(sel + qq * 256 + (kc + 1) * 32 + 8 * g16);
;         #pragma unroll
;         for (int j = 0; j < 8; ++j) {
;           const int ks = (kc + 1) * 32 + 8 * g16 + j;
;           const int idx = ks < cnt ? (int)((si[j >> 1] >> (16 * (j & 1))) & 0xffffu) : 0;
;           vr[j] = ldg<u32x4>(Av + (rowbase + idx) * 128 + n16 * 8);
;         }
;       }
;       const bf16x8 pa = *(const bf16x8*)(Pb + arow * PSTR + kc * 32 + g16 * 8);
;       u32x2 t0[8], t1[8];
;       asm volatile(
;           "s_waitcnt lgkmcnt(0)\n\t"
;           "ds_read_b64_tr_b16 %0, %16\n\tds_read_b64_tr_b16 %1, %17\n\tds_read_b64_tr_b16 %2, %18\n\tds_read_b64_tr_b16 %3, %19\n\t"
;           "ds_read_b64_tr_b16 %4, %20\n\tds_read_b64_tr_b16 %5, %21\n\tds_read_b64_tr_b16 %6, %22\n\tds_read_b64_tr_b16 %7, %23\n\t"
;           "ds_read_b64_tr_b16 %8, %24\n\tds_read_b64_tr_b16 %9, %25\n\tds_read_b64_tr_b16 %10, %26\n\tds_read_b64_tr_b16 %11, %27\n\t"
;           "ds_read_b64_tr_b16 %12, %28\n\tds_read_b64_tr_b16 %13, %29\n\tds_read_b64_tr_b16 %14, %30\n\tds_read_b64_tr_b16 %15, %31\n\t"
;           "s_waitcnt lgkmcnt(0)"
;           : "=&v"(t0[0]), "=&v"(t1[0]), "=&v"(t0[1]), "=&v"(t1[1]), "=&v"(t0[2]), "=&v"(t1[2]), "=&v"(t0[3]), "=&v"(t1[3]),
;             "=&v"(t0[4]), "=&v"(t1[4]), "=&v"(t0[5]), "=&v"(t1[5]), "=&v"(t0[6]), "=&v"(t1[6]), "=&v"(t0[7]), "=&v"(t1[7])
;           : "v"(lds_base + taddr[0][0]), "v"(lds_base + taddr[0][1]), "v"(lds_base + taddr[1][0]), "v"(lds_base + taddr[1][1]),
;             "v"(lds_base + taddr[2][0]), "v"(lds_base + taddr[2][1]), "v"(lds_base + taddr[3][0]), "v"(lds_base + taddr[3][1]),
;             "v"(lds_base + taddr[4][0]), "v"(lds_base + taddr[4][1]), "v"(lds_base + taddr[5][0]), "v"(lds_base + taddr[5][1]),
;             "v"(lds_base + taddr[6][0]), "v"(lds_base + taddr[6][1]), "v"(lds_base + taddr[7][0]), "v"(lds_base + taddr[7][1])
;           : "memory");
;       #pragma unroll
;       for (int c = 0; c < 8; ++c) {
	ds_read_b64_tr_b16 v[102:103], v162
	ds_read_b64_tr_b16 v[104:105], v163
	ds_read_b64_tr_b16 v[98:99], v164
	ds_read_b64_tr_b16 v[100:101], v165
	ds_read_b64_tr_b16 v[94:95], v166
	ds_read_b64_tr_b16 v[96:97], v167
	ds_read_b64_tr_b16 v[90:91], v168
	ds_read_b64_tr_b16 v[92:93], v169
	ds_read_b64_tr_b16 v[86:87], v170
	ds_read_b64_tr_b16 v[88:89], v171
	ds_read_b64_tr_b16 v[82:83], v172
	ds_read_b64_tr_b16 v[84:85], v173
	ds_read_b64_tr_b16 v[78:79], v174
	ds_read_b64_tr_b16 v[80:81], v175
	ds_read_b64_tr_b16 v[74:75], v176
	ds_read_b64_tr_b16 v[76:77], v177
	s_waitcnt lgkmcnt(0)
	v_mfma_f32_16x16x32_bf16 v[50:53], v[70:73], v[102:105], v[50:53]
	v_mfma_f32_16x16x32_bf16 v[38:41], v[70:73], v[98:101], v[38:41]
	v_mfma_f32_16x16x32_bf16 v[30:33], v[70:73], v[94:97], v[30:33]
	v_mfma_f32_16x16x32_bf16 v[18:21], v[70:73], v[90:93], v[18:21]
	v_mfma_f32_16x16x32_bf16 v[42:45], v[70:73], v[86:89], v[42:45]
	v_mfma_f32_16x16x32_bf16 v[26:29], v[70:73], v[82:85], v[26:29]
	v_mfma_f32_16x16x32_bf16 v[14:17], v[70:73], v[78:81], v[14:17]
	v_mfma_f32_16x16x32_bf16 v[6:9], v[70:73], v[74:77], v[6:9]
	s_waitcnt vmcnt(16)
	ds_write_b128 v198, v[106:109]
	ds_write_b128 v199, v[110:113]
	ds_write_b128 v200, v[114:117]
	ds_write_b128 v201, v[118:121]
	ds_write_b128 v202, v[122:125]
	ds_write_b128 v203, v[126:129]
	ds_write_b128 v204, v[130:133]
	ds_write_b128 v205, v[134:137]
	ds_read_b128 v[248:251], v242 offset:448
	s_waitcnt lgkmcnt(0)
	v_add_u32_e32 v243, 0xffffff20, v206
	v_cmp_lt_i32_e32 vcc, v156, v243
	s_nop 1
	v_cndmask_b32_sdwa v240, v1, v248, vcc dst_sel:DWORD dst_unused:UNUSED_PAD src0_sel:DWORD src1_sel:WORD_0
	v_cmp_lt_i32_e32 vcc, v192, v243
	v_lshl_add_u64 v[244:245], s[16:17], 0, v[240:241]
	v_lshlrev_b64 v[244:245], 8, v[244:245]
	v_lshl_add_u64 v[244:245], v[148:149], 0, v[244:245]
	global_load_dwordx4 v[106:109], v[244:245], off
	v_cndmask_b32_sdwa v240, v1, v248, vcc dst_sel:DWORD dst_unused:UNUSED_PAD src0_sel:DWORD src1_sel:WORD_1
	v_cmp_lt_i32_e32 vcc, v193, v243
	v_lshl_add_u64 v[246:247], s[16:17], 0, v[240:241]
	v_lshlrev_b64 v[246:247], 8, v[246:247]
	v_lshl_add_u64 v[246:247], v[148:149], 0, v[246:247]
	global_load_dwordx4 v[110:113], v[246:247], off
	v_cndmask_b32_sdwa v240, v1, v249, vcc dst_sel:DWORD dst_unused:UNUSED_PAD src0_sel:DWORD src1_sel:WORD_0
	v_cmp_lt_i32_e32 vcc, v194, v243
	v_lshl_add_u64 v[244:245], s[16:17], 0, v[240:241]
	v_lshlrev_b64 v[244:245], 8, v[244:245]
	v_lshl_add_u64 v[244:245], v[148:149], 0, v[244:245]
	global_load_dwordx4 v[114:117], v[244:245], off
	v_cndmask_b32_sdwa v240, v1, v249, vcc dst_sel:DWORD dst_unused:UNUSED_PAD src0_sel:DWORD src1_sel:WORD_1
	v_cmp_lt_i32_e32 vcc, v157, v243
	v_lshl_add_u64 v[246:247], s[16:17], 0, v[240:241]
	v_lshlrev_b64 v[246:247], 8, v[246:247]
	v_lshl_add_u64 v[246:247], v[148:149], 0, v[246:247]
	global_load_dwordx4 v[118:121], v[246:247], off
	v_cndmask_b32_sdwa v240, v1, v250, vcc dst_sel:DWORD dst_unused:UNUSED_PAD src0_sel:DWORD src1_sel:WORD_0
	v_cmp_lt_i32_e32 vcc, v195, v243
	v_lshl_add_u64 v[244:245], s[16:17], 0, v[240:241]
	v_lshlrev_b64 v[244:245], 8, v[244:245]
	v_lshl_add_u64 v[244:245], v[148:149], 0, v[244:245]
	global_load_dwordx4 v[122:125], v[244:245], off
	v_cndmask_b32_sdwa v240, v1, v250, vcc dst_sel:DWORD dst_unused:UNUSED_PAD src0_sel:DWORD src1_sel:WORD_1
	v_cmp_lt_i32_e32 vcc, v196, v243
	v_lshl_add_u64 v[246:247], s[16:17], 0, v[240:241]
	v_lshlrev_b64 v[246:247], 8, v[246:247]
	v_lshl_add_u64 v[246:247], v[148:149], 0, v[246:247]
	global_load_dwordx4 v[126:129], v[246:247], off
	v_cndmask_b32_sdwa v240, v1, v251, vcc dst_sel:DWORD dst_unused:UNUSED_PAD src0_sel:DWORD src1_sel:WORD_0
	v_cmp_lt_i32_e32 vcc, v197, v243
	v_lshl_add_u64 v[244:245], s[16:17], 0, v[240:241]
	v_lshlrev_b64 v[244:245], 8, v[244:245]
	v_lshl_add_u64 v[244:245], v[148:149], 0, v[244:245]
	global_load_dwordx4 v[130:133], v[244:245], off
	v_cndmask_b32_sdwa v240, v1, v251, vcc dst_sel:DWORD dst_unused:UNUSED_PAD src0_sel:DWORD src1_sel:WORD_1
	v_lshl_add_u64 v[246:247], s[16:17], 0, v[240:241]
	v_lshlrev_b64 v[246:247], 8, v[246:247]
	v_lshl_add_u64 v[246:247], v[148:149], 0, v[246:247]
	global_load_dwordx4 v[134:137], v[246:247], off
	ds_read_b128 v[70:73], v68 offset:256
	s_waitcnt lgkmcnt(0)
	ds_read_b64_tr_b16 v[102:103], v162
	ds_read_b64_tr_b16 v[104:105], v163
	ds_read_b64_tr_b16 v[98:99], v164
	ds_read_b64_tr_b16 v[100:101], v165
	ds_read_b64_tr_b16 v[94:95], v166
	ds_read_b64_tr_b16 v[96:97], v167
	ds_read_b64_tr_b16 v[90:91], v168
	ds_read_b64_tr_b16 v[92:93], v169
	ds_read_b64_tr_b16 v[86:87], v170
	ds_read_b64_tr_b16 v[88:89], v171
	ds_read_b64_tr_b16 v[82:83], v172
	ds_read_b64_tr_b16 v[84:85], v173
	ds_read_b64_tr_b16 v[78:79], v174
	ds_read_b64_tr_b16 v[80:81], v175
	ds_read_b64_tr_b16 v[74:75], v176
	ds_read_b64_tr_b16 v[76:77], v177
	s_waitcnt lgkmcnt(0)
; DI void dsa_item(const Params& p, int b, int blk) {
;     ...
;     for (int kc = 0; kc < 8; ++kc) {
;       #pragma unroll
;       for (int j = 0; j < 8; ++j) {
;         const unsigned row = 8 * g16 + j;
;         *(u32x4*)(Vc + 256u * row + 16u * ((unsigned)n16 ^ (((row & 3) << 2) | ((row >> 2) & 3)))) = vr[j];
;       }
;       if (kc < 7) {
;         const u32x4 si = *(const u32x4*)(sel + qq * 256 + (kc + 1) * 32 + 8 * g16);
;         #pragma unroll
;         for (int j = 0; j < 8; ++j) {
;           const int ks = (kc + 1) * 32 + 8 * g16 + j;
;           const int idx = ks < cnt ? (int)((si[j >> 1] >> (16 * (j & 1))) & 0xffffu) : 0;
;           vr[j] = ldg<u32x4>(Av + (rowbase + idx) * 128 + n16 * 8);
;         }
;       }
;       const bf16x8 pa = *(const bf16x8*)(Pb + arow * PSTR + kc * 32 + g16 * 8);
;       u32x2 t0[8], t1[8];
;       asm volatile(
;           "s_waitcnt lgkmcnt(0)\n\t"
;           "ds_read_b64_tr_b16 %0, %16\n\tds_read_b64_tr_b16 %1, %17\n\tds_read_b64_tr_b16 %2, %18\n\tds_read_b64_tr_b16 %3, %19\n\t"
;           "ds_read_b64_tr_b16 %4, %20\n\tds_read_b64_tr_b16 %5, %21\n\tds_read_b64_tr_b16 %6, %22\n\tds_read_b64_tr_b16 %7, %23\n\t"
;           "ds_read_b64_tr_b16 %8, %24\n\tds_read_b64_tr_b16 %9, %25\n\tds_read_b64_tr_b16 %10, %26\n\tds_read_b64_tr_b16 %11, %27\n\t"
;           "ds_read_b64_tr_b16 %12, %28\n\tds_read_b64_tr_b16 %13, %29\n\tds_read_b64_tr_b16 %14, %30\n\tds_read_b64_tr_b16 %15, %31\n\t"
;           "s_waitcnt lgkmcnt(0)"
;           : "=&v"(t0[0]), "=&v"(t1[0]), "=&v"(t0[1]), "=&v"(t1[1]), "=&v"(t0[2]), "=&v"(t1[2]), "=&v"(t0[3]), "=&v"(t1[3]),
;             "=&v"(t0[4]), "=&v"(t1[4]), "=&v"(t0[5]), "=&v"(t1[5]), "=&v"(t0[6]), "=&v"(t1[6]), "=&v"(t0[7]), "=&v"(t1[7])
;           : "v"(lds_base + taddr[0][0]), "v"(lds_base + taddr[0][1]), "v"(lds_base + taddr[1][0]), "v"(lds_base + taddr[1][1]),
;             "v"(lds_base + taddr[2][0]), "v"(lds_base + taddr[2][1]), "v"(lds_base + taddr[3][0]), "v"(lds_base + taddr[3][1]),
;             "v"(lds_base + taddr[4][0]), "v"(lds_base + taddr[4][1]), "v"(lds_base + taddr[5][0]), "v"(lds_base + taddr[5][1]),
;             "v"(lds_base + taddr[6][0]), "v"(lds_base + taddr[6][1]), "v"(lds_base + taddr[7][0]), "v"(lds_base + taddr[7][1])
;           : "memory");
;       #pragma unroll
;       for (int c = 0; c < 8; ++c) {
	v_mfma_f32_16x16x32_bf16 v[50:53], v[70:73], v[102:105], v[50:53]
	v_mfma_f32_16x16x32_bf16 v[38:41], v[70:73], v[98:101], v[38:41]
	v_mfma_f32_16x16x32_bf16 v[30:33], v[70:73], v[94:97], v[30:33]
	v_mfma_f32_16x16x32_bf16 v[18:21], v[70:73], v[90:93], v[18:21]
	v_mfma_f32_16x16x32_bf16 v[42:45], v[70:73], v[86:89], v[42:45]
	v_mfma_f32_16x16x32_bf16 v[26:29], v[70:73], v[82:85], v[26:29]
	v_mfma_f32_16x16x32_bf16 v[14:17], v[70:73], v[78:81], v[14:17]
	v_mfma_f32_16x16x32_bf16 v[6:9], v[70:73], v[74:77], v[6:9]
	s_waitcnt vmcnt(16)
	ds_write_b128 v198, v[2:5]
	ds_write_b128 v199, v[10:13]
	ds_write_b128 v200, v[22:25]
	ds_write_b128 v201, v[34:37]
	ds_write_b128 v202, v[46:49]
	ds_write_b128 v203, v[54:57]
	ds_write_b128 v204, v[58:61]
	ds_write_b128 v205, v[62:65]
	ds_read_b128 v[70:73], v68 offset:320
	s_waitcnt lgkmcnt(0)
	ds_read_b64_tr_b16 v[102:103], v162
	ds_read_b64_tr_b16 v[104:105], v163
	ds_read_b64_tr_b16 v[98:99], v164
	ds_read_b64_tr_b16 v[100:101], v165
	ds_read_b64_tr_b16 v[94:95], v166
	ds_read_b64_tr_b16 v[96:97], v167
	ds_read_b64_tr_b16 v[90:91], v168
	ds_read_b64_tr_b16 v[92:93], v169
	ds_read_b64_tr_b16 v[86:87], v170
	ds_read_b64_tr_b16 v[88:89], v171
	ds_read_b64_tr_b16 v[82:83], v172
	ds_read_b64_tr_b16 v[84:85], v173
	ds_read_b64_tr_b16 v[78:79], v174
	ds_read_b64_tr_b16 v[80:81], v175
	ds_read_b64_tr_b16 v[74:75], v176
	ds_read_b64_tr_b16 v[76:77], v177
	s_waitcnt lgkmcnt(0)
	v_mfma_f32_16x16x32_bf16 v[50:53], v[70:73], v[102:105], v[50:53]
	v_mfma_f32_16x16x32_bf16 v[38:41], v[70:73], v[98:101], v[38:41]
	v_mfma_f32_16x16x32_bf16 v[30:33], v[70:73], v[94:97], v[30:33]
	v_mfma_f32_16x16x32_bf16 v[18:21], v[70:73], v[90:93], v[18:21]
	v_mfma_f32_16x16x32_bf16 v[42:45], v[70:73], v[86:89], v[42:45]
	v_mfma_f32_16x16x32_bf16 v[26:29], v[70:73], v[82:85], v[26:29]
	v_mfma_f32_16x16x32_bf16 v[14:17], v[70:73], v[78:81], v[14:17]
	v_mfma_f32_16x16x32_bf16 v[6:9], v[70:73], v[74:77], v[6:9]
	s_waitcnt vmcnt(8)
	ds_write_b128 v198, v[208:211]
	ds_write_b128 v199, v[212:215]
	ds_write_b128 v200, v[216:219]
	ds_write_b128 v201, v[220:223]
	ds_write_b128 v202, v[224:227]
	ds_write_b128 v203, v[228:231]
	ds_write_b128 v204, v[232:235]
	ds_write_b128 v205, v[236:239]
	ds_read_b128 v[70:73], v68 offset:384
	s_waitcnt lgkmcnt(0)
	ds_read_b64_tr_b16 v[102:103], v162
	ds_read_b64_tr_b16 v[104:105], v163
	ds_read_b64_tr_b16 v[98:99], v164
	ds_read_b64_tr_b16 v[100:101], v165
	ds_read_b64_tr_b16 v[94:95], v166
	ds_read_b64_tr_b16 v[96:97], v167
	ds_read_b64_tr_b16 v[90:91], v168
	ds_read_b64_tr_b16 v[92:93], v169
	ds_read_b64_tr_b16 v[86:87], v170
	ds_read_b64_tr_b16 v[88:89], v171
	ds_read_b64_tr_b16 v[82:83], v172
	ds_read_b64_tr_b16 v[84:85], v173
	ds_read_b64_tr_b16 v[78:79], v174
	ds_read_b64_tr_b16 v[80:81], v175
	ds_read_b64_tr_b16 v[74:75], v176
	ds_read_b64_tr_b16 v[76:77], v177
	s_waitcnt lgkmcnt(0)
	v_mfma_f32_16x16x32_bf16 v[50:53], v[70:73], v[102:105], v[50:53]
	v_mfma_f32_16x16x32_bf16 v[38:41], v[70:73], v[98:101], v[38:41]
	v_mfma_f32_16x16x32_bf16 v[30:33], v[70:73], v[94:97], v[30:33]
	v_mfma_f32_16x16x32_bf16 v[18:21], v[70:73], v[90:93], v[18:21]
	v_mfma_f32_16x16x32_bf16 v[42:45], v[70:73], v[86:89], v[42:45]
	v_mfma_f32_16x16x32_bf16 v[26:29], v[70:73], v[82:85], v[26:29]
	v_mfma_f32_16x16x32_bf16 v[14:17], v[70:73], v[78:81], v[14:17]
	v_mfma_f32_16x16x32_bf16 v[6:9], v[70:73], v[74:77], v[6:9]
	s_waitcnt vmcnt(0)
	ds_write_b128 v198, v[106:109]
	ds_write_b128 v199, v[110:113]
	ds_write_b128 v200, v[114:117]
	ds_write_b128 v201, v[118:121]
	ds_write_b128 v202, v[122:125]
	ds_write_b128 v203, v[126:129]
	ds_write_b128 v204, v[130:133]
	ds_write_b128 v205, v[134:137]
	ds_read_b128 v[70:73], v68 offset:448
	s_waitcnt lgkmcnt(0)
	ds_read_b64_tr_b16 v[102:103], v162
	ds_read_b64_tr_b16 v[104:105], v163
	ds_read_b64_tr_b16 v[98:99], v164
	ds_read_b64_tr_b16 v[100:101], v165
	ds_read_b64_tr_b16 v[94:95], v166
	ds_read_b64_tr_b16 v[96:97], v167
	ds_read_b64_tr_b16 v[90:91], v168
	ds_read_b64_tr_b16 v[92:93], v169
	ds_read_b64_tr_b16 v[86:87], v170
	ds_read_b64_tr_b16 v[88:89], v171
	ds_read_b64_tr_b16 v[82:83], v172
	ds_read_b64_tr_b16 v[84:85], v173
	ds_read_b64_tr_b16 v[78:79], v174
	ds_read_b64_tr_b16 v[80:81], v175
	ds_read_b64_tr_b16 v[74:75], v176
	ds_read_b64_tr_b16 v[76:77], v177
	s_waitcnt lgkmcnt(0)
	v_mfma_f32_16x16x32_bf16 v[50:53], v[70:73], v[102:105], v[50:53]
	v_mfma_f32_16x16x32_bf16 v[38:41], v[70:73], v[98:101], v[38:41]
	v_mfma_f32_16x16x32_bf16 v[30:33], v[70:73], v[94:97], v[30:33]
	v_mfma_f32_16x16x32_bf16 v[18:21], v[70:73], v[90:93], v[18:21]
	v_mfma_f32_16x16x32_bf16 v[42:45], v[70:73], v[86:89], v[42:45]
	v_mfma_f32_16x16x32_bf16 v[26:29], v[70:73], v[82:85], v[26:29]
	v_mfma_f32_16x16x32_bf16 v[14:17], v[70:73], v[78:81], v[14:17]
	v_mfma_f32_16x16x32_bf16 v[6:9], v[70:73], v[74:77], v[6:9]
	s_nop 0
